# Epilogue de-serialisation, step 1: on v15, all 16 residual chunks of each lane touched (dummy loads into dead v228:231) before the EpiResid load ladder in the 12 residual-add GEMM epilogues
# baseline (speedup 1.0000x reference)
.LBB0_390:
	v_lshl_add_u32 v150, s79, 8, v1
	v_lshl_or_b32 v146, s80, 8, v153
	v_ashrrev_i32_e32 v151, 31, v150
	v_ashrrev_i32_e32 v147, 31, v146
	v_lshlrev_b64 v[148:149], 13, v[150:151]
	v_lshl_add_u64 v[158:159], s[12:13], 0, v[148:149]
	v_lshlrev_b64 v[148:149], 2, v[146:147]
	v_or_b32_e32 v190, 16, v150
	v_lshl_add_u64 v[170:171], v[158:159], 0, v[148:149]
	v_ashrrev_i32_e32 v191, 31, v190
	v_mov_b32_e32 v235, 0
	global_load_dwordx4 v[228:231], v[170:171], off
	global_load_dwordx4 v[228:231], v[170:171], off offset:512
	v_mov_b32_e32 v234, 1
	v_lshl_add_u64 v[232:233], v[234:235], 17, v[170:171]
	global_load_dwordx4 v[228:231], v[232:233], off
	global_load_dwordx4 v[228:231], v[232:233], off offset:512
	v_mov_b32_e32 v234, 2
	v_lshl_add_u64 v[232:233], v[234:235], 17, v[170:171]
	global_load_dwordx4 v[228:231], v[232:233], off
	global_load_dwordx4 v[228:231], v[232:233], off offset:512
	v_mov_b32_e32 v234, 3
	v_lshl_add_u64 v[232:233], v[234:235], 17, v[170:171]
	global_load_dwordx4 v[228:231], v[232:233], off
	global_load_dwordx4 v[228:231], v[232:233], off offset:512
	v_mov_b32_e32 v234, 8
	v_lshl_add_u64 v[232:233], v[234:235], 17, v[170:171]
	global_load_dwordx4 v[228:231], v[232:233], off
	global_load_dwordx4 v[228:231], v[232:233], off offset:512
	v_mov_b32_e32 v234, 9
	v_lshl_add_u64 v[232:233], v[234:235], 17, v[170:171]
	global_load_dwordx4 v[228:231], v[232:233], off
	global_load_dwordx4 v[228:231], v[232:233], off offset:512
	v_mov_b32_e32 v234, 10
	v_lshl_add_u64 v[232:233], v[234:235], 17, v[170:171]
	global_load_dwordx4 v[228:231], v[232:233], off
	global_load_dwordx4 v[228:231], v[232:233], off offset:512
	v_mov_b32_e32 v234, 11
	v_lshl_add_u64 v[232:233], v[234:235], 17, v[170:171]
	global_load_dwordx4 v[228:231], v[232:233], off
	global_load_dwordx4 v[228:231], v[232:233], off offset:512
	global_load_dwordx4 v[158:161], v[170:171], off
	global_load_dwordx4 v[162:165], v[170:171], off offset:16
	global_load_dwordx4 v[166:169], v[170:171], off offset:512
	s_nop 0
	global_load_dwordx4 v[170:173], v[170:171], off offset:528
	v_lshlrev_b64 v[174:175], 13, v[190:191]
	v_lshl_add_u64 v[174:175], s[12:13], 0, v[174:175]
	v_lshl_add_u64 v[186:187], v[174:175], 0, v[148:149]
	global_load_dwordx4 v[174:177], v[186:187], off
	global_load_dwordx4 v[178:181], v[186:187], off offset:16
	global_load_dwordx4 v[182:185], v[186:187], off offset:512
	s_nop 0
	global_load_dwordx4 v[186:189], v[186:187], off offset:528
	v_or_b32_e32 v192, 32, v150
	v_lshlrev_b64 v[196:197], 12, v[150:151]
	v_ashrrev_i32_e32 v193, 31, v192
	v_lshlrev_b64 v[146:147], 1, v[146:147]
	v_lshl_add_u64 v[196:197], s[64:65], 0, v[196:197]
	v_lshlrev_b64 v[198:199], 13, v[192:193]
	v_or_b32_e32 v194, 48, v150
	v_lshl_add_u64 v[196:197], v[196:197], 0, v[146:147]
	v_lshl_add_u64 v[198:199], s[12:13], 0, v[198:199]
	v_ashrrev_i32_e32 v195, 31, v194
	v_lshlrev_b64 v[190:191], 12, v[190:191]
	v_lshl_add_u64 v[198:199], v[198:199], 0, v[148:149]
	v_lshlrev_b64 v[200:201], 13, v[194:195]
	v_lshl_add_u64 v[190:191], s[64:65], 0, v[190:191]
	v_lshl_add_u64 v[200:201], s[12:13], 0, v[200:201]
	v_lshl_add_u64 v[190:191], v[190:191], 0, v[146:147]
	v_lshl_add_u64 v[200:201], v[200:201], 0, v[148:149]
	s_and_b64 vcc, exec, s[2:3]
	s_mov_b64 s[0:1], -1
	s_waitcnt vmcnt(0)
	v_pk_fma_f32 v[128:129], v[128:129], 0.5, v[160:161] op_sel_hi:[1,0,1]
	v_pk_fma_f32 v[126:127], v[126:127], 0.5, v[158:159] op_sel_hi:[1,0,1]
	v_pk_fma_f32 v[124:125], v[124:125], 0.5, v[164:165] op_sel_hi:[1,0,1]
	v_pk_fma_f32 v[122:123], v[122:123], 0.5, v[162:163] op_sel_hi:[1,0,1]
	v_pk_fma_f32 v[158:159], v[112:113], 0.5, v[168:169] op_sel_hi:[1,0,1]
	v_pk_fma_f32 v[160:161], v[110:111], 0.5, v[166:167] op_sel_hi:[1,0,1]
	v_pk_fma_f32 v[110:111], v[108:109], 0.5, v[172:173] op_sel_hi:[1,0,1]
	v_pk_fma_f32 v[162:163], v[106:107], 0.5, v[170:171] op_sel_hi:[1,0,1]
	v_cvt_pk_f16_f32 v109, v124, v125
	v_cvt_pk_f16_f32 v107, v128, v129
	v_cvt_pk_f16_f32 v108, v122, v123
	v_cvt_pk_f16_f32 v106, v126, v127
	v_cvt_pk_f16_f32 v113, v110, v111
	v_cvt_pk_f16_f32 v111, v158, v159
	v_cvt_pk_f16_f32 v112, v162, v163
	v_cvt_pk_f16_f32 v110, v160, v161
	global_store_dwordx4 v[196:197], v[106:109], off
	global_store_dwordx4 v[196:197], v[110:113], off offset:256
	v_pk_fma_f32 v[120:121], v[120:121], 0.5, v[176:177] op_sel_hi:[1,0,1]
	v_pk_fma_f32 v[122:123], v[118:119], 0.5, v[174:175] op_sel_hi:[1,0,1]
	v_pk_fma_f32 v[116:117], v[116:117], 0.5, v[180:181] op_sel_hi:[1,0,1]
	v_pk_fma_f32 v[124:125], v[114:115], 0.5, v[178:179] op_sel_hi:[1,0,1]
	v_pk_fma_f32 v[126:127], v[104:105], 0.5, v[184:185] op_sel_hi:[1,0,1]
	global_load_dwordx4 v[104:107], v[198:199], off offset:16
	global_load_dwordx4 v[108:111], v[198:199], off
	v_pk_fma_f32 v[128:129], v[102:103], 0.5, v[182:183] op_sel_hi:[1,0,1]
	v_pk_fma_f32 v[158:159], v[100:101], 0.5, v[188:189] op_sel_hi:[1,0,1]
	global_load_dwordx4 v[100:103], v[198:199], off offset:528
	global_load_dwordx4 v[112:115], v[198:199], off offset:512
	v_pk_fma_f32 v[98:99], v[98:99], 0.5, v[186:187] op_sel_hi:[1,0,1]
	v_cvt_pk_f16_f32 v119, v116, v117
	v_cvt_pk_f16_f32 v117, v120, v121
	v_cvt_pk_f16_f32 v118, v124, v125
	v_cvt_pk_f16_f32 v116, v122, v123
	v_cvt_pk_f16_f32 v123, v158, v159
	v_cvt_pk_f16_f32 v121, v126, v127
	v_cvt_pk_f16_f32 v122, v98, v99
	v_cvt_pk_f16_f32 v120, v128, v129
	global_store_dwordx4 v[190:191], v[116:119], off
	global_store_dwordx4 v[190:191], v[120:123], off offset:256
	global_load_dwordx4 v[116:119], v[200:201], off
	s_nop 0
	global_load_dwordx4 v[120:123], v[200:201], off offset:16
	global_load_dwordx4 v[124:127], v[200:201], off offset:512
	global_load_dwordx4 v[158:161], v[200:201], off offset:528
	v_add_u32_e32 v128, 0x80, v150
	v_ashrrev_i32_e32 v129, 31, v128
	v_lshlrev_b64 v[98:99], 12, v[192:193]
	v_add_u32_e32 v162, 0x90, v150
	v_lshlrev_b64 v[164:165], 13, v[128:129]
	v_lshl_add_u64 v[98:99], s[64:65], 0, v[98:99]
	v_ashrrev_i32_e32 v163, 31, v162
	v_lshlrev_b64 v[166:167], 12, v[194:195]
	v_lshl_add_u64 v[164:165], s[12:13], 0, v[164:165]
	v_lshl_add_u64 v[98:99], v[98:99], 0, v[146:147]
	v_lshlrev_b64 v[168:169], 13, v[162:163]
	v_lshl_add_u64 v[166:167], s[64:65], 0, v[166:167]
	v_lshl_add_u64 v[164:165], v[164:165], 0, v[148:149]
	v_lshl_add_u64 v[168:169], s[12:13], 0, v[168:169]
	v_lshl_add_u64 v[166:167], v[166:167], 0, v[146:147]
	v_lshl_add_u64 v[168:169], v[168:169], 0, v[148:149]
	s_waitcnt vmcnt(9)
	v_pk_fma_f32 v[92:93], v[92:93], 0.5, v[106:107] op_sel_hi:[1,0,1]
	s_waitcnt vmcnt(8)
	v_pk_fma_f32 v[96:97], v[96:97], 0.5, v[110:111] op_sel_hi:[1,0,1]
	v_pk_fma_f32 v[94:95], v[94:95], 0.5, v[108:109] op_sel_hi:[1,0,1]
	v_pk_fma_f32 v[90:91], v[90:91], 0.5, v[104:105] op_sel_hi:[1,0,1]
	s_waitcnt vmcnt(6)
	v_pk_fma_f32 v[104:105], v[80:81], 0.5, v[114:115] op_sel_hi:[1,0,1]
	v_pk_fma_f32 v[106:107], v[78:79], 0.5, v[112:113] op_sel_hi:[1,0,1]
	v_pk_fma_f32 v[78:79], v[76:77], 0.5, v[102:103] op_sel_hi:[1,0,1]
	v_pk_fma_f32 v[100:101], v[74:75], 0.5, v[100:101] op_sel_hi:[1,0,1]
	v_cvt_pk_f16_f32 v77, v92, v93
	v_cvt_pk_f16_f32 v75, v96, v97
	v_cvt_pk_f16_f32 v76, v90, v91
	v_cvt_pk_f16_f32 v74, v94, v95
	v_cvt_pk_f16_f32 v81, v78, v79
	v_cvt_pk_f16_f32 v79, v104, v105
	v_cvt_pk_f16_f32 v80, v100, v101
	v_cvt_pk_f16_f32 v78, v106, v107
	s_waitcnt vmcnt(3)
	v_pk_fma_f32 v[88:89], v[88:89], 0.5, v[118:119] op_sel_hi:[1,0,1]
	v_pk_fma_f32 v[90:91], v[86:87], 0.5, v[116:117] op_sel_hi:[1,0,1]
	s_waitcnt vmcnt(2)
	v_pk_fma_f32 v[84:85], v[84:85], 0.5, v[122:123] op_sel_hi:[1,0,1]
	v_pk_fma_f32 v[92:93], v[82:83], 0.5, v[120:121] op_sel_hi:[1,0,1]
	global_store_dwordx4 v[98:99], v[74:77], off
	global_store_dwordx4 v[98:99], v[78:81], off offset:256
	s_waitcnt vmcnt(3)
	v_pk_fma_f32 v[94:95], v[72:73], 0.5, v[126:127] op_sel_hi:[1,0,1]
	global_load_dwordx4 v[72:75], v[164:165], off offset:16
	global_load_dwordx4 v[76:79], v[164:165], off
	v_pk_fma_f32 v[96:97], v[70:71], 0.5, v[124:125] op_sel_hi:[1,0,1]
	s_waitcnt vmcnt(4)
	v_pk_fma_f32 v[98:99], v[68:69], 0.5, v[160:161] op_sel_hi:[1,0,1]
	v_pk_fma_f32 v[66:67], v[66:67], 0.5, v[158:159] op_sel_hi:[1,0,1]
	v_cvt_pk_f16_f32 v87, v84, v85
	v_cvt_pk_f16_f32 v85, v88, v89
	v_cvt_pk_f16_f32 v86, v92, v93
	v_cvt_pk_f16_f32 v84, v90, v91
	global_load_dwordx4 v[68:71], v[164:165], off offset:528
	global_load_dwordx4 v[80:83], v[164:165], off offset:512
	v_cvt_pk_f16_f32 v91, v98, v99
	v_cvt_pk_f16_f32 v89, v94, v95
	v_cvt_pk_f16_f32 v90, v66, v67
	v_cvt_pk_f16_f32 v88, v96, v97
	global_store_dwordx4 v[166:167], v[84:87], off
	global_store_dwordx4 v[166:167], v[88:91], off offset:256
	global_load_dwordx4 v[84:87], v[168:169], off
	s_nop 0
	global_load_dwordx4 v[88:91], v[168:169], off offset:16
	global_load_dwordx4 v[92:95], v[168:169], off offset:512
	global_load_dwordx4 v[96:99], v[168:169], off offset:528
	v_add_u32_e32 v100, 0xa0, v150
	v_add_u32_e32 v102, 0xb0, v150
	v_ashrrev_i32_e32 v101, 31, v100
	v_lshlrev_b64 v[66:67], 12, v[128:129]
	v_ashrrev_i32_e32 v103, 31, v102
	v_lshlrev_b64 v[104:105], 13, v[100:101]
	v_lshlrev_b64 v[106:107], 12, v[162:163]
	v_lshl_add_u64 v[66:67], s[64:65], 0, v[66:67]
	v_lshlrev_b64 v[108:109], 13, v[102:103]
	v_lshl_add_u64 v[104:105], s[12:13], 0, v[104:105]
	v_lshl_add_u64 v[106:107], s[64:65], 0, v[106:107]
	v_lshl_add_u64 v[66:67], v[66:67], 0, v[146:147]
	v_lshl_add_u64 v[108:109], s[12:13], 0, v[108:109]
	v_lshl_add_u64 v[104:105], v[104:105], 0, v[148:149]
	v_lshl_add_u64 v[106:107], v[106:107], 0, v[146:147]
	v_lshl_add_u64 v[108:109], v[108:109], 0, v[148:149]
	s_waitcnt vmcnt(9)
	v_pk_fma_f32 v[60:61], v[60:61], 0.5, v[74:75] op_sel_hi:[1,0,1]
	s_waitcnt vmcnt(8)
	v_pk_fma_f32 v[64:65], v[64:65], 0.5, v[78:79] op_sel_hi:[1,0,1]
	v_pk_fma_f32 v[62:63], v[62:63], 0.5, v[76:77] op_sel_hi:[1,0,1]
	v_pk_fma_f32 v[58:59], v[58:59], 0.5, v[72:73] op_sel_hi:[1,0,1]
	s_waitcnt vmcnt(7)
	v_pk_fma_f32 v[68:69], v[42:43], 0.5, v[68:69] op_sel_hi:[1,0,1]
	s_waitcnt vmcnt(6)
	v_pk_fma_f32 v[72:73], v[48:49], 0.5, v[82:83] op_sel_hi:[1,0,1]
	v_pk_fma_f32 v[74:75], v[46:47], 0.5, v[80:81] op_sel_hi:[1,0,1]
	v_pk_fma_f32 v[46:47], v[44:45], 0.5, v[70:71] op_sel_hi:[1,0,1]
	v_cvt_pk_f16_f32 v45, v60, v61
	v_cvt_pk_f16_f32 v43, v64, v65
	v_cvt_pk_f16_f32 v44, v58, v59
	v_cvt_pk_f16_f32 v42, v62, v63
	s_waitcnt vmcnt(3)
	v_pk_fma_f32 v[56:57], v[56:57], 0.5, v[86:87] op_sel_hi:[1,0,1]
	v_pk_fma_f32 v[58:59], v[54:55], 0.5, v[84:85] op_sel_hi:[1,0,1]
	s_waitcnt vmcnt(2)
	v_pk_fma_f32 v[52:53], v[52:53], 0.5, v[90:91] op_sel_hi:[1,0,1]
	v_pk_fma_f32 v[60:61], v[50:51], 0.5, v[88:89] op_sel_hi:[1,0,1]
	v_cvt_pk_f16_f32 v49, v46, v47
	v_cvt_pk_f16_f32 v47, v72, v73
	v_cvt_pk_f16_f32 v48, v68, v69
	v_cvt_pk_f16_f32 v46, v74, v75
	s_waitcnt vmcnt(1)
	v_pk_fma_f32 v[62:63], v[40:41], 0.5, v[94:95] op_sel_hi:[1,0,1]
	global_store_dwordx4 v[66:67], v[42:45], off
	global_store_dwordx4 v[66:67], v[46:49], off offset:256
	v_pk_fma_f32 v[64:65], v[38:39], 0.5, v[92:93] op_sel_hi:[1,0,1]
	s_waitcnt vmcnt(2)
	v_pk_fma_f32 v[66:67], v[36:37], 0.5, v[98:99] op_sel_hi:[1,0,1]
	v_pk_fma_f32 v[34:35], v[34:35], 0.5, v[96:97] op_sel_hi:[1,0,1]
	v_cvt_pk_f16_f32 v55, v52, v53
	v_cvt_pk_f16_f32 v53, v56, v57
	v_cvt_pk_f16_f32 v54, v60, v61
	v_cvt_pk_f16_f32 v52, v58, v59
	global_load_dwordx4 v[40:43], v[104:105], off offset:16
	global_load_dwordx4 v[44:47], v[104:105], off
	global_load_dwordx4 v[36:39], v[104:105], off offset:528
	global_load_dwordx4 v[48:51], v[104:105], off offset:512
	v_cvt_pk_f16_f32 v59, v66, v67
	v_cvt_pk_f16_f32 v57, v62, v63
	v_cvt_pk_f16_f32 v58, v34, v35
	v_cvt_pk_f16_f32 v56, v64, v65
	global_store_dwordx4 v[106:107], v[52:55], off
	global_store_dwordx4 v[106:107], v[56:59], off offset:256
	global_load_dwordx4 v[52:55], v[108:109], off
	s_nop 0
	global_load_dwordx4 v[56:59], v[108:109], off offset:16
	global_load_dwordx4 v[60:63], v[108:109], off offset:512
	global_load_dwordx4 v[64:67], v[108:109], off offset:528
	v_lshlrev_b64 v[34:35], 12, v[100:101]
	v_lshlrev_b64 v[68:69], 12, v[102:103]
	v_lshl_add_u64 v[34:35], s[64:65], 0, v[34:35]
	v_lshl_add_u64 v[68:69], s[64:65], 0, v[68:69]
	v_lshl_add_u64 v[34:35], v[34:35], 0, v[146:147]
	v_lshl_add_u64 v[68:69], v[68:69], 0, v[146:147]
	s_waitcnt vmcnt(9)
	v_pk_fma_f32 v[28:29], v[28:29], 0.5, v[42:43] op_sel_hi:[1,0,1]
	s_waitcnt vmcnt(8)
	v_pk_fma_f32 v[32:33], v[32:33], 0.5, v[46:47] op_sel_hi:[1,0,1]
	v_pk_fma_f32 v[30:31], v[30:31], 0.5, v[44:45] op_sel_hi:[1,0,1]
	v_pk_fma_f32 v[26:27], v[26:27], 0.5, v[40:41] op_sel_hi:[1,0,1]
	s_waitcnt vmcnt(6)
	v_pk_fma_f32 v[40:41], v[16:17], 0.5, v[50:51] op_sel_hi:[1,0,1]
	s_waitcnt vmcnt(3)
	v_pk_fma_f32 v[24:25], v[24:25], 0.5, v[54:55] op_sel_hi:[1,0,1]
	v_pk_fma_f32 v[22:23], v[22:23], 0.5, v[52:53] op_sel_hi:[1,0,1]
	s_waitcnt vmcnt(2)
	v_pk_fma_f32 v[20:21], v[20:21], 0.5, v[58:59] op_sel_hi:[1,0,1]
	v_pk_fma_f32 v[18:19], v[18:19], 0.5, v[56:57] op_sel_hi:[1,0,1]
	v_pk_fma_f32 v[42:43], v[14:15], 0.5, v[48:49] op_sel_hi:[1,0,1]
	v_pk_fma_f32 v[14:15], v[12:13], 0.5, v[38:39] op_sel_hi:[1,0,1]
	v_pk_fma_f32 v[36:37], v[10:11], 0.5, v[36:37] op_sel_hi:[1,0,1]
	v_cvt_pk_f16_f32 v13, v28, v29
	v_cvt_pk_f16_f32 v11, v32, v33
	v_cvt_pk_f16_f32 v12, v26, v27
	v_cvt_pk_f16_f32 v10, v30, v31
	s_waitcnt vmcnt(1)
	v_pk_fma_f32 v[26:27], v[8:9], 0.5, v[62:63] op_sel_hi:[1,0,1]
	v_pk_fma_f32 v[28:29], v[6:7], 0.5, v[60:61] op_sel_hi:[1,0,1]
	s_waitcnt vmcnt(0)
	v_pk_fma_f32 v[6:7], v[4:5], 0.5, v[66:67] op_sel_hi:[1,0,1]
	v_pk_fma_f32 v[30:31], v[2:3], 0.5, v[64:65] op_sel_hi:[1,0,1]
	v_cvt_pk_f16_f32 v5, v20, v21
	v_cvt_pk_f16_f32 v3, v24, v25
	v_cvt_pk_f16_f32 v4, v18, v19
	v_cvt_pk_f16_f32 v2, v22, v23
	v_cvt_pk_f16_f32 v17, v14, v15
	v_cvt_pk_f16_f32 v15, v40, v41
	v_cvt_pk_f16_f32 v16, v36, v37
	v_cvt_pk_f16_f32 v14, v42, v43
	global_store_dwordx4 v[34:35], v[10:13], off
	global_store_dwordx4 v[34:35], v[14:17], off offset:256
	v_cvt_pk_f16_f32 v9, v6, v7
	v_cvt_pk_f16_f32 v7, v26, v27
	v_cvt_pk_f16_f32 v8, v30, v31
	v_cvt_pk_f16_f32 v6, v28, v29
	global_store_dwordx4 v[68:69], v[2:5], off
	global_store_dwordx4 v[68:69], v[6:9], off offset:256
	s_cbranch_vccnz .LBB0_375
	s_andn2_b64 vcc, exec, s[8:9]
	s_cbranch_vccnz .LBB0_374
	s_barrier
	s_branch .LBB0_374

.LBB0_998:
	v_lshl_add_u32 v146, s76, 8, v1
	v_lshl_or_b32 v148, s73, 8, v163
	v_ashrrev_i32_e32 v147, 31, v146
	v_ashrrev_i32_e32 v149, 31, v148
	v_lshlrev_b64 v[150:151], 12, v[146:147]
	v_lshl_add_u64 v[150:151], s[64:65], 0, v[150:151]
	v_lshlrev_b64 v[148:149], 1, v[148:149]
	v_lshl_add_u64 v[150:151], v[150:151], 0, v[148:149]
	v_mov_b32_e32 v235, 0
	global_load_dwordx4 v[228:231], v[150:151], off
	global_load_dwordx4 v[228:231], v[150:151], off offset:256
	v_mov_b32_e32 v234, 1
	v_lshl_add_u64 v[232:233], v[234:235], 16, v[150:151]
	global_load_dwordx4 v[228:231], v[232:233], off
	global_load_dwordx4 v[228:231], v[232:233], off offset:256
	v_mov_b32_e32 v234, 2
	v_lshl_add_u64 v[232:233], v[234:235], 16, v[150:151]
	global_load_dwordx4 v[228:231], v[232:233], off
	global_load_dwordx4 v[228:231], v[232:233], off offset:256
	v_mov_b32_e32 v234, 3
	v_lshl_add_u64 v[232:233], v[234:235], 16, v[150:151]
	global_load_dwordx4 v[228:231], v[232:233], off
	global_load_dwordx4 v[228:231], v[232:233], off offset:256
	v_mov_b32_e32 v234, 8
	v_lshl_add_u64 v[232:233], v[234:235], 16, v[150:151]
	global_load_dwordx4 v[228:231], v[232:233], off
	global_load_dwordx4 v[228:231], v[232:233], off offset:256
	v_mov_b32_e32 v234, 9
	v_lshl_add_u64 v[232:233], v[234:235], 16, v[150:151]
	global_load_dwordx4 v[228:231], v[232:233], off
	global_load_dwordx4 v[228:231], v[232:233], off offset:256
	v_mov_b32_e32 v234, 10
	v_lshl_add_u64 v[232:233], v[234:235], 16, v[150:151]
	global_load_dwordx4 v[228:231], v[232:233], off
	global_load_dwordx4 v[228:231], v[232:233], off offset:256
	v_mov_b32_e32 v234, 11
	v_lshl_add_u64 v[232:233], v[234:235], 16, v[150:151]
	global_load_dwordx4 v[228:231], v[232:233], off
	global_load_dwordx4 v[228:231], v[232:233], off offset:256
	global_load_dwordx4 v[152:155], v[150:151], off
	s_mov_b64 s[0:1], 0x80000
	s_waitcnt vmcnt(0)
	v_cvt_f32_f16_e32 v172, v152
	v_cvt_f32_f16_sdwa v173, v152 dst_sel:DWORD dst_unused:UNUSED_PAD src0_sel:WORD_1
	v_cvt_f32_f16_e32 v174, v153
	v_cvt_f32_f16_sdwa v175, v153 dst_sel:DWORD dst_unused:UNUSED_PAD src0_sel:WORD_1
	v_cvt_f32_f16_e32 v176, v154
	v_cvt_f32_f16_sdwa v177, v154 dst_sel:DWORD dst_unused:UNUSED_PAD src0_sel:WORD_1
	v_cvt_f32_f16_e32 v178, v155
	v_cvt_f32_f16_sdwa v179, v155 dst_sel:DWORD dst_unused:UNUSED_PAD src0_sel:WORD_1
	global_load_dwordx4 v[152:155], v[150:151], off offset:256
	v_pk_add_f32 v[128:129], v[128:129], v[174:175]
	v_pk_add_f32 v[126:127], v[126:127], v[172:173]
	v_pk_add_f32 v[124:125], v[124:125], v[178:179]
	v_pk_add_f32 v[122:123], v[122:123], v[176:177]
	v_cvt_pk_f16_f32 v125, v124, v125
	v_cvt_pk_f16_f32 v124, v122, v123
	v_cvt_pk_f16_f32 v123, v128, v129
	v_cvt_pk_f16_f32 v122, v126, v127
	global_store_dwordx4 v[150:151], v[122:125], off
	s_waitcnt vmcnt(1)
	v_cvt_f32_f16_e32 v180, v152
	v_cvt_f32_f16_sdwa v181, v152 dst_sel:DWORD dst_unused:UNUSED_PAD src0_sel:WORD_1
	v_cvt_f32_f16_e32 v182, v153
	v_cvt_f32_f16_sdwa v183, v153 dst_sel:DWORD dst_unused:UNUSED_PAD src0_sel:WORD_1
	v_cvt_f32_f16_e32 v184, v154
	v_cvt_f32_f16_sdwa v185, v154 dst_sel:DWORD dst_unused:UNUSED_PAD src0_sel:WORD_1
	v_cvt_f32_f16_e32 v186, v155
	v_cvt_f32_f16_sdwa v187, v155 dst_sel:DWORD dst_unused:UNUSED_PAD src0_sel:WORD_1
	v_pk_add_f32 v[120:121], v[120:121], v[182:183]
	v_pk_add_f32 v[118:119], v[118:119], v[180:181]
	v_pk_add_f32 v[114:115], v[114:115], v[184:185]
	v_pk_add_f32 v[116:117], v[116:117], v[186:187]
	v_or_b32_e32 v152, 16, v146
	v_cvt_pk_f16_f32 v117, v116, v117
	v_cvt_pk_f16_f32 v116, v114, v115
	v_cvt_pk_f16_f32 v115, v120, v121
	v_cvt_pk_f16_f32 v114, v118, v119
	global_store_dwordx4 v[150:151], v[114:117], off offset:256
	v_ashrrev_i32_e32 v153, 31, v152
	v_lshlrev_b64 v[152:153], 12, v[152:153]
	v_or_b32_e32 v114, 32, v146
	v_ashrrev_i32_e32 v115, 31, v114
	v_lshlrev_b64 v[114:115], 12, v[114:115]
	v_lshl_add_u64 v[152:153], s[64:65], 0, v[152:153]
	v_lshl_add_u64 v[114:115], s[64:65], 0, v[114:115]
	v_lshl_add_u64 v[152:153], v[152:153], 0, v[148:149]
	v_lshl_add_u64 v[120:121], v[114:115], 0, v[148:149]
	global_load_dwordx4 v[158:161], v[152:153], off
	global_load_dwordx4 v[114:117], v[120:121], off
	global_load_dwordx4 v[168:171], v[152:153], off offset:256
	s_waitcnt vmcnt(2)
	v_cvt_f32_f16_e32 v154, v158
	s_waitcnt vmcnt(1)
	v_cvt_f32_f16_e32 v122, v114
	v_cvt_f32_f16_sdwa v123, v114 dst_sel:DWORD dst_unused:UNUSED_PAD src0_sel:WORD_1
	v_cvt_f32_f16_e32 v124, v115
	v_cvt_f32_f16_sdwa v125, v115 dst_sel:DWORD dst_unused:UNUSED_PAD src0_sel:WORD_1
	v_cvt_f32_f16_e32 v126, v116
	v_cvt_f32_f16_sdwa v127, v116 dst_sel:DWORD dst_unused:UNUSED_PAD src0_sel:WORD_1
	v_cvt_f32_f16_e32 v128, v117
	v_cvt_f32_f16_sdwa v129, v117 dst_sel:DWORD dst_unused:UNUSED_PAD src0_sel:WORD_1
	global_load_dwordx4 v[114:117], v[120:121], off offset:256
	s_waitcnt vmcnt(1)
	v_cvt_f32_f16_e32 v188, v168
	v_cvt_f32_f16_sdwa v189, v168 dst_sel:DWORD dst_unused:UNUSED_PAD src0_sel:WORD_1
	v_cvt_f32_f16_e32 v168, v169
	v_cvt_f32_f16_sdwa v169, v169 dst_sel:DWORD dst_unused:UNUSED_PAD src0_sel:WORD_1
	v_cvt_f32_f16_e32 v190, v170
	v_cvt_f32_f16_sdwa v191, v170 dst_sel:DWORD dst_unused:UNUSED_PAD src0_sel:WORD_1
	v_cvt_f32_f16_e32 v170, v171
	v_cvt_f32_f16_sdwa v171, v171 dst_sel:DWORD dst_unused:UNUSED_PAD src0_sel:WORD_1
	v_pk_add_f32 v[104:105], v[104:105], v[168:169]
	v_pk_add_f32 v[102:103], v[102:103], v[188:189]
	v_pk_add_f32 v[98:99], v[98:99], v[190:191]
	v_pk_add_f32 v[100:101], v[100:101], v[170:171]
	v_cvt_f32_f16_sdwa v155, v158 dst_sel:DWORD dst_unused:UNUSED_PAD src0_sel:WORD_1
	v_cvt_f32_f16_e32 v158, v159
	v_cvt_f32_f16_sdwa v159, v159 dst_sel:DWORD dst_unused:UNUSED_PAD src0_sel:WORD_1
	v_cvt_f32_f16_e32 v156, v160
	v_cvt_f32_f16_sdwa v157, v160 dst_sel:DWORD dst_unused:UNUSED_PAD src0_sel:WORD_1
	v_cvt_f32_f16_e32 v160, v161
	v_cvt_f32_f16_sdwa v161, v161 dst_sel:DWORD dst_unused:UNUSED_PAD src0_sel:WORD_1
	v_cvt_pk_f16_f32 v101, v100, v101
	v_cvt_pk_f16_f32 v100, v98, v99
	v_cvt_pk_f16_f32 v99, v104, v105
	v_cvt_pk_f16_f32 v98, v102, v103
	global_store_dwordx4 v[152:153], v[98:101], off offset:256
	v_pk_add_f32 v[112:113], v[112:113], v[158:159]
	v_pk_add_f32 v[110:111], v[110:111], v[154:155]
	v_or_b32_e32 v98, 48, v146
	v_ashrrev_i32_e32 v99, 31, v98
	v_lshlrev_b64 v[98:99], 12, v[98:99]
	v_pk_add_f32 v[108:109], v[108:109], v[160:161]
	v_pk_add_f32 v[106:107], v[106:107], v[156:157]
	v_lshl_add_u64 v[98:99], s[64:65], 0, v[98:99]
	v_cvt_pk_f16_f32 v109, v108, v109
	v_cvt_pk_f16_f32 v108, v106, v107
	v_cvt_pk_f16_f32 v107, v112, v113
	v_cvt_pk_f16_f32 v106, v110, v111
	v_lshl_add_u64 v[98:99], v[98:99], 0, v[148:149]
	global_store_dwordx4 v[152:153], v[106:109], off
	global_load_dwordx4 v[106:109], v[98:99], off
	v_pk_add_f32 v[96:97], v[96:97], v[124:125]
	v_pk_add_f32 v[94:95], v[94:95], v[122:123]
	v_pk_add_f32 v[92:93], v[92:93], v[128:129]
	v_pk_add_f32 v[90:91], v[90:91], v[126:127]
	v_cvt_pk_f16_f32 v93, v92, v93
	v_cvt_pk_f16_f32 v92, v90, v91
	v_cvt_pk_f16_f32 v91, v96, v97
	v_cvt_pk_f16_f32 v90, v94, v95
	global_store_dwordx4 v[120:121], v[90:93], off
	s_waitcnt vmcnt(4)
	v_cvt_f32_f16_e32 v176, v116
	v_cvt_f32_f16_sdwa v177, v116 dst_sel:DWORD dst_unused:UNUSED_PAD src0_sel:WORD_1
	v_cvt_f32_f16_e32 v178, v117
	v_cvt_f32_f16_sdwa v179, v117 dst_sel:DWORD dst_unused:UNUSED_PAD src0_sel:WORD_1
	global_load_dwordx4 v[116:119], v[98:99], off offset:256
	v_cvt_f32_f16_e32 v172, v114
	v_cvt_f32_f16_sdwa v173, v114 dst_sel:DWORD dst_unused:UNUSED_PAD src0_sel:WORD_1
	v_cvt_f32_f16_e32 v174, v115
	v_cvt_f32_f16_sdwa v175, v115 dst_sel:DWORD dst_unused:UNUSED_PAD src0_sel:WORD_1
	v_pk_add_f32 v[84:85], v[84:85], v[178:179]
	v_pk_add_f32 v[86:87], v[86:87], v[172:173]
	v_pk_add_f32 v[82:83], v[82:83], v[176:177]
	v_pk_add_f32 v[88:89], v[88:89], v[174:175]
	v_cvt_pk_f16_f32 v85, v84, v85
	v_cvt_pk_f16_f32 v84, v82, v83
	v_cvt_pk_f16_f32 v83, v88, v89
	v_cvt_pk_f16_f32 v82, v86, v87
	global_store_dwordx4 v[120:121], v[82:85], off offset:256
	s_waitcnt vmcnt(3)
	v_cvt_f32_f16_e32 v102, v106
	v_cvt_f32_f16_sdwa v103, v106 dst_sel:DWORD dst_unused:UNUSED_PAD src0_sel:WORD_1
	v_cvt_f32_f16_e32 v110, v107
	v_cvt_f32_f16_sdwa v111, v107 dst_sel:DWORD dst_unused:UNUSED_PAD src0_sel:WORD_1
	v_cvt_f32_f16_e32 v106, v108
	v_cvt_f32_f16_sdwa v107, v108 dst_sel:DWORD dst_unused:UNUSED_PAD src0_sel:WORD_1
	v_cvt_f32_f16_e32 v114, v109
	v_cvt_f32_f16_sdwa v115, v109 dst_sel:DWORD dst_unused:UNUSED_PAD src0_sel:WORD_1
	v_lshl_add_u64 v[82:83], v[150:151], 0, s[0:1]
	s_mov_b32 s0, 0x80000
	v_add_co_u32_e32 v84, vcc, s0, v150
	v_pk_add_f32 v[80:81], v[80:81], v[110:111]
	s_nop 0
	v_addc_co_u32_e32 v85, vcc, 0, v151, vcc
	global_load_dwordx4 v[90:93], v[84:85], off
	v_pk_add_f32 v[78:79], v[78:79], v[102:103]
	v_pk_add_f32 v[76:77], v[76:77], v[114:115]
	v_pk_add_f32 v[74:75], v[74:75], v[106:107]
	v_cvt_pk_f16_f32 v77, v76, v77
	v_cvt_pk_f16_f32 v76, v74, v75
	v_cvt_pk_f16_f32 v75, v80, v81
	v_cvt_pk_f16_f32 v74, v78, v79
	global_store_dwordx4 v[98:99], v[74:77], off
	s_mov_b64 s[0:1], -1
	s_andn2_b64 vcc, exec, s[2:3]
	s_waitcnt vmcnt(3)
	v_cvt_f32_f16_e32 v100, v116
	v_cvt_f32_f16_sdwa v101, v116 dst_sel:DWORD dst_unused:UNUSED_PAD src0_sel:WORD_1
	v_cvt_f32_f16_e32 v108, v117
	v_cvt_f32_f16_sdwa v109, v117 dst_sel:DWORD dst_unused:UNUSED_PAD src0_sel:WORD_1
	v_cvt_f32_f16_e32 v104, v118
	v_cvt_f32_f16_sdwa v105, v118 dst_sel:DWORD dst_unused:UNUSED_PAD src0_sel:WORD_1
	v_cvt_f32_f16_e32 v112, v119
	v_cvt_f32_f16_sdwa v113, v119 dst_sel:DWORD dst_unused:UNUSED_PAD src0_sel:WORD_1
	v_pk_add_f32 v[72:73], v[72:73], v[108:109]
	v_pk_add_f32 v[70:71], v[70:71], v[100:101]
	v_pk_add_f32 v[66:67], v[66:67], v[104:105]
	v_pk_add_f32 v[68:69], v[68:69], v[112:113]
	global_load_dwordx4 v[116:119], v[82:83], off offset:256
	v_cvt_pk_f16_f32 v69, v68, v69
	v_cvt_pk_f16_f32 v68, v66, v67
	v_cvt_pk_f16_f32 v67, v72, v73
	v_cvt_pk_f16_f32 v66, v70, v71
	global_store_dwordx4 v[98:99], v[66:69], off offset:256
	s_waitcnt vmcnt(3)
	v_cvt_f32_f16_e32 v86, v90
	v_add_u32_e32 v66, 0x90, v146
	v_ashrrev_i32_e32 v67, 31, v66
	v_lshlrev_b64 v[66:67], 12, v[66:67]
	v_lshl_add_u64 v[66:67], s[64:65], 0, v[66:67]
	v_lshl_add_u64 v[68:69], v[66:67], 0, v[148:149]
	global_load_dwordx4 v[74:77], v[68:69], off
	global_load_dwordx4 v[98:101], v[68:69], off offset:256
	v_cvt_f32_f16_sdwa v87, v90 dst_sel:DWORD dst_unused:UNUSED_PAD src0_sel:WORD_1
	v_cvt_f32_f16_e32 v90, v91
	v_cvt_f32_f16_sdwa v91, v91 dst_sel:DWORD dst_unused:UNUSED_PAD src0_sel:WORD_1
	v_cvt_f32_f16_e32 v88, v92
	v_cvt_f32_f16_sdwa v89, v92 dst_sel:DWORD dst_unused:UNUSED_PAD src0_sel:WORD_1
	v_cvt_f32_f16_e32 v92, v93
	v_cvt_f32_f16_sdwa v93, v93 dst_sel:DWORD dst_unused:UNUSED_PAD src0_sel:WORD_1
	v_pk_add_f32 v[64:65], v[64:65], v[90:91]
	v_pk_add_f32 v[62:63], v[62:63], v[86:87]
	v_pk_add_f32 v[58:59], v[58:59], v[88:89]
	v_pk_add_f32 v[60:61], v[60:61], v[92:93]
	s_waitcnt vmcnt(3)
	v_cvt_f32_f16_e32 v94, v116
	v_cvt_f32_f16_sdwa v95, v116 dst_sel:DWORD dst_unused:UNUSED_PAD src0_sel:WORD_1
	v_cvt_f32_f16_e32 v116, v117
	v_cvt_f32_f16_sdwa v117, v117 dst_sel:DWORD dst_unused:UNUSED_PAD src0_sel:WORD_1
	v_cvt_f32_f16_e32 v96, v118
	v_cvt_f32_f16_sdwa v97, v118 dst_sel:DWORD dst_unused:UNUSED_PAD src0_sel:WORD_1
	v_cvt_f32_f16_e32 v118, v119
	v_cvt_f32_f16_sdwa v119, v119 dst_sel:DWORD dst_unused:UNUSED_PAD src0_sel:WORD_1
	v_pk_add_f32 v[56:57], v[56:57], v[116:117]
	v_pk_add_f32 v[54:55], v[54:55], v[94:95]
	v_pk_add_f32 v[50:51], v[50:51], v[96:97]
	v_pk_add_f32 v[52:53], v[52:53], v[118:119]
	v_cvt_pk_f16_f32 v61, v60, v61
	v_cvt_pk_f16_f32 v53, v52, v53
	v_cvt_pk_f16_f32 v52, v50, v51
	v_cvt_pk_f16_f32 v51, v56, v57
	v_cvt_pk_f16_f32 v50, v54, v55
	global_store_dwordx4 v[82:83], v[50:53], off offset:256
	v_cvt_pk_f16_f32 v60, v58, v59
	v_cvt_pk_f16_f32 v59, v64, v65
	v_add_u32_e32 v50, 0xa0, v146
	v_ashrrev_i32_e32 v51, 31, v50
	v_lshlrev_b64 v[50:51], 12, v[50:51]
	v_lshl_add_u64 v[50:51], s[64:65], 0, v[50:51]
	v_cvt_pk_f16_f32 v58, v62, v63
	v_lshl_add_u64 v[50:51], v[50:51], 0, v[148:149]
	global_store_dwordx4 v[84:85], v[58:61], off
	global_load_dwordx4 v[58:61], v[50:51], off
	s_waitcnt vmcnt(4)
	v_cvt_f32_f16_e32 v70, v74
	s_waitcnt vmcnt(3)
	v_cvt_f32_f16_e32 v78, v98
	v_cvt_f32_f16_sdwa v79, v98 dst_sel:DWORD dst_unused:UNUSED_PAD src0_sel:WORD_1
	v_cvt_f32_f16_e32 v98, v99
	v_cvt_f32_f16_sdwa v99, v99 dst_sel:DWORD dst_unused:UNUSED_PAD src0_sel:WORD_1
	v_cvt_f32_f16_e32 v80, v100
	v_cvt_f32_f16_sdwa v81, v100 dst_sel:DWORD dst_unused:UNUSED_PAD src0_sel:WORD_1
	v_cvt_f32_f16_e32 v100, v101
	v_cvt_f32_f16_sdwa v101, v101 dst_sel:DWORD dst_unused:UNUSED_PAD src0_sel:WORD_1
	v_cvt_f32_f16_sdwa v71, v74 dst_sel:DWORD dst_unused:UNUSED_PAD src0_sel:WORD_1
	v_cvt_f32_f16_e32 v74, v75
	v_cvt_f32_f16_sdwa v75, v75 dst_sel:DWORD dst_unused:UNUSED_PAD src0_sel:WORD_1
	v_cvt_f32_f16_e32 v72, v76
	v_cvt_f32_f16_sdwa v73, v76 dst_sel:DWORD dst_unused:UNUSED_PAD src0_sel:WORD_1
	v_cvt_f32_f16_e32 v76, v77
	v_cvt_f32_f16_sdwa v77, v77 dst_sel:DWORD dst_unused:UNUSED_PAD src0_sel:WORD_1
	v_pk_add_f32 v[40:41], v[40:41], v[98:99]
	v_pk_add_f32 v[38:39], v[38:39], v[78:79]
	v_pk_add_f32 v[36:37], v[36:37], v[100:101]
	v_pk_add_f32 v[34:35], v[34:35], v[80:81]
	global_load_dwordx4 v[82:85], v[50:51], off offset:256
	v_cvt_pk_f16_f32 v37, v36, v37
	v_cvt_pk_f16_f32 v36, v34, v35
	v_cvt_pk_f16_f32 v35, v40, v41
	v_cvt_pk_f16_f32 v34, v38, v39
	global_store_dwordx4 v[68:69], v[34:37], off offset:256
	v_pk_add_f32 v[48:49], v[48:49], v[74:75]
	v_pk_add_f32 v[46:47], v[46:47], v[70:71]
	v_add_u32_e32 v34, 0xb0, v146
	v_ashrrev_i32_e32 v35, 31, v34
	v_pk_add_f32 v[44:45], v[44:45], v[76:77]
	v_pk_add_f32 v[42:43], v[42:43], v[72:73]
	v_lshlrev_b64 v[34:35], 12, v[34:35]
	v_cvt_pk_f16_f32 v45, v44, v45
	v_cvt_pk_f16_f32 v44, v42, v43
	v_cvt_pk_f16_f32 v43, v48, v49
	v_cvt_pk_f16_f32 v42, v46, v47
	v_lshl_add_u64 v[34:35], s[64:65], 0, v[34:35]
	global_store_dwordx4 v[68:69], v[42:45], off
	s_waitcnt vmcnt(3)
	v_cvt_f32_f16_e32 v54, v58
	v_lshl_add_u64 v[42:43], v[34:35], 0, v[148:149]
	global_load_dwordx4 v[34:37], v[42:43], off
	global_load_dwordx4 v[38:41], v[42:43], off offset:256
	v_cvt_f32_f16_sdwa v55, v58 dst_sel:DWORD dst_unused:UNUSED_PAD src0_sel:WORD_1
	v_cvt_f32_f16_e32 v58, v59
	v_cvt_f32_f16_sdwa v59, v59 dst_sel:DWORD dst_unused:UNUSED_PAD src0_sel:WORD_1
	v_cvt_f32_f16_e32 v52, v60
	v_cvt_f32_f16_sdwa v53, v60 dst_sel:DWORD dst_unused:UNUSED_PAD src0_sel:WORD_1
	v_cvt_f32_f16_e32 v56, v61
	v_cvt_f32_f16_sdwa v57, v61 dst_sel:DWORD dst_unused:UNUSED_PAD src0_sel:WORD_1
	v_pk_add_f32 v[32:33], v[32:33], v[58:59]
	v_pk_add_f32 v[30:31], v[30:31], v[54:55]
	v_pk_add_f32 v[26:27], v[26:27], v[52:53]
	v_pk_add_f32 v[28:29], v[28:29], v[56:57]
	s_waitcnt vmcnt(4)
	v_cvt_f32_f16_e32 v62, v82
	v_cvt_f32_f16_sdwa v63, v82 dst_sel:DWORD dst_unused:UNUSED_PAD src0_sel:WORD_1
	v_cvt_f32_f16_e32 v66, v83
	v_cvt_f32_f16_sdwa v67, v83 dst_sel:DWORD dst_unused:UNUSED_PAD src0_sel:WORD_1
	v_cvt_f32_f16_e32 v60, v84
	v_cvt_f32_f16_sdwa v61, v84 dst_sel:DWORD dst_unused:UNUSED_PAD src0_sel:WORD_1
	v_cvt_f32_f16_e32 v64, v85
	v_cvt_f32_f16_sdwa v65, v85 dst_sel:DWORD dst_unused:UNUSED_PAD src0_sel:WORD_1
	v_pk_add_f32 v[24:25], v[24:25], v[66:67]
	v_pk_add_f32 v[22:23], v[22:23], v[62:63]
	v_pk_add_f32 v[18:19], v[18:19], v[60:61]
	v_pk_add_f32 v[20:21], v[20:21], v[64:65]
	v_cvt_pk_f16_f32 v29, v28, v29
	v_cvt_pk_f16_f32 v28, v26, v27
	v_cvt_pk_f16_f32 v27, v32, v33
	v_cvt_pk_f16_f32 v26, v30, v31
	v_cvt_pk_f16_f32 v21, v20, v21
	v_cvt_pk_f16_f32 v20, v18, v19
	v_cvt_pk_f16_f32 v19, v24, v25
	v_cvt_pk_f16_f32 v18, v22, v23
	global_store_dwordx4 v[50:51], v[26:29], off
	global_store_dwordx4 v[50:51], v[18:21], off offset:256
	s_waitcnt vmcnt(3)
	v_cvt_f32_f16_e32 v30, v34
	s_waitcnt vmcnt(2)
	v_cvt_f32_f16_e32 v18, v40
	v_cvt_f32_f16_sdwa v19, v40 dst_sel:DWORD dst_unused:UNUSED_PAD src0_sel:WORD_1
	v_cvt_f32_f16_e32 v20, v41
	v_cvt_f32_f16_sdwa v21, v41 dst_sel:DWORD dst_unused:UNUSED_PAD src0_sel:WORD_1
	v_cvt_f32_f16_e32 v22, v38
	v_cvt_f32_f16_sdwa v23, v38 dst_sel:DWORD dst_unused:UNUSED_PAD src0_sel:WORD_1
	v_cvt_f32_f16_e32 v24, v39
	v_cvt_f32_f16_sdwa v25, v39 dst_sel:DWORD dst_unused:UNUSED_PAD src0_sel:WORD_1
	v_cvt_f32_f16_e32 v26, v36
	v_cvt_f32_f16_sdwa v27, v36 dst_sel:DWORD dst_unused:UNUSED_PAD src0_sel:WORD_1
	v_cvt_f32_f16_e32 v28, v37
	v_cvt_f32_f16_sdwa v29, v37 dst_sel:DWORD dst_unused:UNUSED_PAD src0_sel:WORD_1
	v_cvt_f32_f16_sdwa v31, v34 dst_sel:DWORD dst_unused:UNUSED_PAD src0_sel:WORD_1
	v_cvt_f32_f16_e32 v32, v35
	v_cvt_f32_f16_sdwa v33, v35 dst_sel:DWORD dst_unused:UNUSED_PAD src0_sel:WORD_1
	v_pk_add_f32 v[12:13], v[12:13], v[28:29]
	v_pk_add_f32 v[14:15], v[14:15], v[30:31]
	v_pk_add_f32 v[10:11], v[10:11], v[26:27]
	v_pk_add_f32 v[16:17], v[16:17], v[32:33]
	v_pk_add_f32 v[8:9], v[8:9], v[24:25]
	v_pk_add_f32 v[6:7], v[6:7], v[22:23]
	v_pk_add_f32 v[4:5], v[4:5], v[20:21]
	v_pk_add_f32 v[2:3], v[2:3], v[18:19]
	v_cvt_pk_f16_f32 v13, v12, v13
	v_cvt_pk_f16_f32 v12, v10, v11
	v_cvt_pk_f16_f32 v11, v16, v17
	v_cvt_pk_f16_f32 v10, v14, v15
	v_cvt_pk_f16_f32 v5, v4, v5
	v_cvt_pk_f16_f32 v4, v2, v3
	v_cvt_pk_f16_f32 v3, v8, v9
	v_cvt_pk_f16_f32 v2, v6, v7
	global_store_dwordx4 v[42:43], v[10:13], off
	global_store_dwordx4 v[42:43], v[2:5], off offset:256
	s_cbranch_vccnz .LBB0_987
	s_andn2_b64 vcc, exec, s[6:7]
	s_cbranch_vccnz .LBB0_986
	s_barrier
	s_branch .LBB0_986

.LBB0_1240:
	v_lshl_add_u32 v146, s75, 8, v1
	v_lshl_or_b32 v148, s86, 8, v163
	v_ashrrev_i32_e32 v147, 31, v146
	v_ashrrev_i32_e32 v149, 31, v148
	v_lshlrev_b64 v[150:151], 12, v[146:147]
	v_lshl_add_u64 v[150:151], s[64:65], 0, v[150:151]
	v_lshlrev_b64 v[148:149], 1, v[148:149]
	v_lshl_add_u64 v[150:151], v[150:151], 0, v[148:149]
	v_mov_b32_e32 v235, 0
	global_load_dwordx4 v[228:231], v[150:151], off
	global_load_dwordx4 v[228:231], v[150:151], off offset:256
	v_mov_b32_e32 v234, 1
	v_lshl_add_u64 v[232:233], v[234:235], 16, v[150:151]
	global_load_dwordx4 v[228:231], v[232:233], off
	global_load_dwordx4 v[228:231], v[232:233], off offset:256
	v_mov_b32_e32 v234, 2
	v_lshl_add_u64 v[232:233], v[234:235], 16, v[150:151]
	global_load_dwordx4 v[228:231], v[232:233], off
	global_load_dwordx4 v[228:231], v[232:233], off offset:256
	v_mov_b32_e32 v234, 3
	v_lshl_add_u64 v[232:233], v[234:235], 16, v[150:151]
	global_load_dwordx4 v[228:231], v[232:233], off
	global_load_dwordx4 v[228:231], v[232:233], off offset:256
	v_mov_b32_e32 v234, 8
	v_lshl_add_u64 v[232:233], v[234:235], 16, v[150:151]
	global_load_dwordx4 v[228:231], v[232:233], off
	global_load_dwordx4 v[228:231], v[232:233], off offset:256
	v_mov_b32_e32 v234, 9
	v_lshl_add_u64 v[232:233], v[234:235], 16, v[150:151]
	global_load_dwordx4 v[228:231], v[232:233], off
	global_load_dwordx4 v[228:231], v[232:233], off offset:256
	v_mov_b32_e32 v234, 10
	v_lshl_add_u64 v[232:233], v[234:235], 16, v[150:151]
	global_load_dwordx4 v[228:231], v[232:233], off
	global_load_dwordx4 v[228:231], v[232:233], off offset:256
	v_mov_b32_e32 v234, 11
	v_lshl_add_u64 v[232:233], v[234:235], 16, v[150:151]
	global_load_dwordx4 v[228:231], v[232:233], off
	global_load_dwordx4 v[228:231], v[232:233], off offset:256
	global_load_dwordx4 v[152:155], v[150:151], off
	s_mov_b64 s[0:1], 0x80000
	s_waitcnt vmcnt(0)
	v_cvt_f32_f16_e32 v172, v152
	v_cvt_f32_f16_sdwa v173, v152 dst_sel:DWORD dst_unused:UNUSED_PAD src0_sel:WORD_1
	v_cvt_f32_f16_e32 v174, v153
	v_cvt_f32_f16_sdwa v175, v153 dst_sel:DWORD dst_unused:UNUSED_PAD src0_sel:WORD_1
	v_cvt_f32_f16_e32 v176, v154
	v_cvt_f32_f16_sdwa v177, v154 dst_sel:DWORD dst_unused:UNUSED_PAD src0_sel:WORD_1
	v_cvt_f32_f16_e32 v178, v155
	v_cvt_f32_f16_sdwa v179, v155 dst_sel:DWORD dst_unused:UNUSED_PAD src0_sel:WORD_1
	global_load_dwordx4 v[152:155], v[150:151], off offset:256
	v_pk_fma_f32 v[128:129], v[128:129], 0.5, v[174:175] op_sel_hi:[1,0,1]
	v_pk_fma_f32 v[126:127], v[126:127], 0.5, v[172:173] op_sel_hi:[1,0,1]
	v_pk_fma_f32 v[124:125], v[124:125], 0.5, v[178:179] op_sel_hi:[1,0,1]
	v_pk_fma_f32 v[122:123], v[122:123], 0.5, v[176:177] op_sel_hi:[1,0,1]
	v_cvt_pk_f16_f32 v125, v124, v125
	v_cvt_pk_f16_f32 v124, v122, v123
	v_cvt_pk_f16_f32 v123, v128, v129
	v_cvt_pk_f16_f32 v122, v126, v127
	global_store_dwordx4 v[150:151], v[122:125], off
	s_waitcnt vmcnt(1)
	v_cvt_f32_f16_e32 v180, v152
	v_cvt_f32_f16_sdwa v181, v152 dst_sel:DWORD dst_unused:UNUSED_PAD src0_sel:WORD_1
	v_cvt_f32_f16_e32 v182, v153
	v_cvt_f32_f16_sdwa v183, v153 dst_sel:DWORD dst_unused:UNUSED_PAD src0_sel:WORD_1
	v_cvt_f32_f16_e32 v184, v154
	v_cvt_f32_f16_sdwa v185, v154 dst_sel:DWORD dst_unused:UNUSED_PAD src0_sel:WORD_1
	v_cvt_f32_f16_e32 v186, v155
	v_cvt_f32_f16_sdwa v187, v155 dst_sel:DWORD dst_unused:UNUSED_PAD src0_sel:WORD_1
	v_pk_fma_f32 v[120:121], v[120:121], 0.5, v[182:183] op_sel_hi:[1,0,1]
	v_pk_fma_f32 v[118:119], v[118:119], 0.5, v[180:181] op_sel_hi:[1,0,1]
	v_pk_fma_f32 v[114:115], v[114:115], 0.5, v[184:185] op_sel_hi:[1,0,1]
	v_pk_fma_f32 v[116:117], v[116:117], 0.5, v[186:187] op_sel_hi:[1,0,1]
	v_or_b32_e32 v152, 16, v146
	v_cvt_pk_f16_f32 v117, v116, v117
	v_cvt_pk_f16_f32 v116, v114, v115
	v_cvt_pk_f16_f32 v115, v120, v121
	v_cvt_pk_f16_f32 v114, v118, v119
	global_store_dwordx4 v[150:151], v[114:117], off offset:256
	v_ashrrev_i32_e32 v153, 31, v152
	v_lshlrev_b64 v[152:153], 12, v[152:153]
	v_or_b32_e32 v114, 32, v146
	v_ashrrev_i32_e32 v115, 31, v114
	v_lshlrev_b64 v[114:115], 12, v[114:115]
	v_lshl_add_u64 v[152:153], s[64:65], 0, v[152:153]
	v_lshl_add_u64 v[114:115], s[64:65], 0, v[114:115]
	v_lshl_add_u64 v[152:153], v[152:153], 0, v[148:149]
	v_lshl_add_u64 v[120:121], v[114:115], 0, v[148:149]
	global_load_dwordx4 v[158:161], v[152:153], off
	global_load_dwordx4 v[114:117], v[120:121], off
	global_load_dwordx4 v[168:171], v[152:153], off offset:256
	s_waitcnt vmcnt(2)
	v_cvt_f32_f16_e32 v154, v158
	s_waitcnt vmcnt(1)
	v_cvt_f32_f16_e32 v122, v114
	v_cvt_f32_f16_sdwa v123, v114 dst_sel:DWORD dst_unused:UNUSED_PAD src0_sel:WORD_1
	v_cvt_f32_f16_e32 v124, v115
	v_cvt_f32_f16_sdwa v125, v115 dst_sel:DWORD dst_unused:UNUSED_PAD src0_sel:WORD_1
	v_cvt_f32_f16_e32 v126, v116
	v_cvt_f32_f16_sdwa v127, v116 dst_sel:DWORD dst_unused:UNUSED_PAD src0_sel:WORD_1
	v_cvt_f32_f16_e32 v128, v117
	v_cvt_f32_f16_sdwa v129, v117 dst_sel:DWORD dst_unused:UNUSED_PAD src0_sel:WORD_1
	global_load_dwordx4 v[114:117], v[120:121], off offset:256
	s_waitcnt vmcnt(1)
	v_cvt_f32_f16_e32 v188, v168
	v_cvt_f32_f16_sdwa v189, v168 dst_sel:DWORD dst_unused:UNUSED_PAD src0_sel:WORD_1
	v_cvt_f32_f16_e32 v168, v169
	v_cvt_f32_f16_sdwa v169, v169 dst_sel:DWORD dst_unused:UNUSED_PAD src0_sel:WORD_1
	v_cvt_f32_f16_e32 v190, v170
	v_cvt_f32_f16_sdwa v191, v170 dst_sel:DWORD dst_unused:UNUSED_PAD src0_sel:WORD_1
	v_cvt_f32_f16_e32 v170, v171
	v_cvt_f32_f16_sdwa v171, v171 dst_sel:DWORD dst_unused:UNUSED_PAD src0_sel:WORD_1
	v_pk_fma_f32 v[104:105], v[104:105], 0.5, v[168:169] op_sel_hi:[1,0,1]
	v_pk_fma_f32 v[102:103], v[102:103], 0.5, v[188:189] op_sel_hi:[1,0,1]
	v_pk_fma_f32 v[98:99], v[98:99], 0.5, v[190:191] op_sel_hi:[1,0,1]
	v_pk_fma_f32 v[100:101], v[100:101], 0.5, v[170:171] op_sel_hi:[1,0,1]
	v_cvt_f32_f16_sdwa v155, v158 dst_sel:DWORD dst_unused:UNUSED_PAD src0_sel:WORD_1
	v_cvt_f32_f16_e32 v158, v159
	v_cvt_f32_f16_sdwa v159, v159 dst_sel:DWORD dst_unused:UNUSED_PAD src0_sel:WORD_1
	v_cvt_f32_f16_e32 v156, v160
	v_cvt_f32_f16_sdwa v157, v160 dst_sel:DWORD dst_unused:UNUSED_PAD src0_sel:WORD_1
	v_cvt_f32_f16_e32 v160, v161
	v_cvt_f32_f16_sdwa v161, v161 dst_sel:DWORD dst_unused:UNUSED_PAD src0_sel:WORD_1
	v_cvt_pk_f16_f32 v101, v100, v101
	v_cvt_pk_f16_f32 v100, v98, v99
	v_cvt_pk_f16_f32 v99, v104, v105
	v_cvt_pk_f16_f32 v98, v102, v103
	global_store_dwordx4 v[152:153], v[98:101], off offset:256
	v_pk_fma_f32 v[112:113], v[112:113], 0.5, v[158:159] op_sel_hi:[1,0,1]
	v_pk_fma_f32 v[110:111], v[110:111], 0.5, v[154:155] op_sel_hi:[1,0,1]
	v_or_b32_e32 v98, 48, v146
	v_ashrrev_i32_e32 v99, 31, v98
	v_lshlrev_b64 v[98:99], 12, v[98:99]
	v_pk_fma_f32 v[108:109], v[108:109], 0.5, v[160:161] op_sel_hi:[1,0,1]
	v_pk_fma_f32 v[106:107], v[106:107], 0.5, v[156:157] op_sel_hi:[1,0,1]
	v_lshl_add_u64 v[98:99], s[64:65], 0, v[98:99]
	v_cvt_pk_f16_f32 v109, v108, v109
	v_cvt_pk_f16_f32 v108, v106, v107
	v_cvt_pk_f16_f32 v107, v112, v113
	v_cvt_pk_f16_f32 v106, v110, v111
	v_lshl_add_u64 v[98:99], v[98:99], 0, v[148:149]
	global_store_dwordx4 v[152:153], v[106:109], off
	global_load_dwordx4 v[106:109], v[98:99], off
	v_pk_fma_f32 v[96:97], v[96:97], 0.5, v[124:125] op_sel_hi:[1,0,1]
	v_pk_fma_f32 v[94:95], v[94:95], 0.5, v[122:123] op_sel_hi:[1,0,1]
	v_pk_fma_f32 v[92:93], v[92:93], 0.5, v[128:129] op_sel_hi:[1,0,1]
	v_pk_fma_f32 v[90:91], v[90:91], 0.5, v[126:127] op_sel_hi:[1,0,1]
	v_cvt_pk_f16_f32 v93, v92, v93
	v_cvt_pk_f16_f32 v92, v90, v91
	v_cvt_pk_f16_f32 v91, v96, v97
	v_cvt_pk_f16_f32 v90, v94, v95
	global_store_dwordx4 v[120:121], v[90:93], off
	s_waitcnt vmcnt(4)
	v_cvt_f32_f16_e32 v176, v116
	v_cvt_f32_f16_sdwa v177, v116 dst_sel:DWORD dst_unused:UNUSED_PAD src0_sel:WORD_1
	v_cvt_f32_f16_e32 v178, v117
	v_cvt_f32_f16_sdwa v179, v117 dst_sel:DWORD dst_unused:UNUSED_PAD src0_sel:WORD_1
	global_load_dwordx4 v[116:119], v[98:99], off offset:256
	v_cvt_f32_f16_e32 v172, v114
	v_cvt_f32_f16_sdwa v173, v114 dst_sel:DWORD dst_unused:UNUSED_PAD src0_sel:WORD_1
	v_cvt_f32_f16_e32 v174, v115
	v_cvt_f32_f16_sdwa v175, v115 dst_sel:DWORD dst_unused:UNUSED_PAD src0_sel:WORD_1
	v_pk_fma_f32 v[84:85], v[84:85], 0.5, v[178:179] op_sel_hi:[1,0,1]
	v_pk_fma_f32 v[86:87], v[86:87], 0.5, v[172:173] op_sel_hi:[1,0,1]
	v_pk_fma_f32 v[82:83], v[82:83], 0.5, v[176:177] op_sel_hi:[1,0,1]
	v_pk_fma_f32 v[88:89], v[88:89], 0.5, v[174:175] op_sel_hi:[1,0,1]
	v_cvt_pk_f16_f32 v85, v84, v85
	v_cvt_pk_f16_f32 v84, v82, v83
	v_cvt_pk_f16_f32 v83, v88, v89
	v_cvt_pk_f16_f32 v82, v86, v87
	global_store_dwordx4 v[120:121], v[82:85], off offset:256
	s_waitcnt vmcnt(3)
	v_cvt_f32_f16_e32 v102, v106
	v_cvt_f32_f16_sdwa v103, v106 dst_sel:DWORD dst_unused:UNUSED_PAD src0_sel:WORD_1
	v_cvt_f32_f16_e32 v110, v107
	v_cvt_f32_f16_sdwa v111, v107 dst_sel:DWORD dst_unused:UNUSED_PAD src0_sel:WORD_1
	v_cvt_f32_f16_e32 v106, v108
	v_cvt_f32_f16_sdwa v107, v108 dst_sel:DWORD dst_unused:UNUSED_PAD src0_sel:WORD_1
	v_cvt_f32_f16_e32 v114, v109
	v_cvt_f32_f16_sdwa v115, v109 dst_sel:DWORD dst_unused:UNUSED_PAD src0_sel:WORD_1
	v_lshl_add_u64 v[82:83], v[150:151], 0, s[0:1]
	s_mov_b32 s0, 0x80000
	v_add_co_u32_e32 v84, vcc, s0, v150
	v_pk_fma_f32 v[80:81], v[80:81], 0.5, v[110:111] op_sel_hi:[1,0,1]
	s_nop 0
	v_addc_co_u32_e32 v85, vcc, 0, v151, vcc
	global_load_dwordx4 v[90:93], v[84:85], off
	v_pk_fma_f32 v[78:79], v[78:79], 0.5, v[102:103] op_sel_hi:[1,0,1]
	v_pk_fma_f32 v[76:77], v[76:77], 0.5, v[114:115] op_sel_hi:[1,0,1]
	v_pk_fma_f32 v[74:75], v[74:75], 0.5, v[106:107] op_sel_hi:[1,0,1]
	v_cvt_pk_f16_f32 v77, v76, v77
	v_cvt_pk_f16_f32 v76, v74, v75
	v_cvt_pk_f16_f32 v75, v80, v81
	v_cvt_pk_f16_f32 v74, v78, v79
	global_store_dwordx4 v[98:99], v[74:77], off
	s_mov_b64 s[0:1], -1
	s_and_b64 vcc, exec, s[2:3]
	s_waitcnt vmcnt(3)
	v_cvt_f32_f16_e32 v100, v116
	v_cvt_f32_f16_sdwa v101, v116 dst_sel:DWORD dst_unused:UNUSED_PAD src0_sel:WORD_1
	v_cvt_f32_f16_e32 v108, v117
	v_cvt_f32_f16_sdwa v109, v117 dst_sel:DWORD dst_unused:UNUSED_PAD src0_sel:WORD_1
	v_cvt_f32_f16_e32 v104, v118
	v_cvt_f32_f16_sdwa v105, v118 dst_sel:DWORD dst_unused:UNUSED_PAD src0_sel:WORD_1
	v_cvt_f32_f16_e32 v112, v119
	v_cvt_f32_f16_sdwa v113, v119 dst_sel:DWORD dst_unused:UNUSED_PAD src0_sel:WORD_1
	v_pk_fma_f32 v[72:73], v[72:73], 0.5, v[108:109] op_sel_hi:[1,0,1]
	v_pk_fma_f32 v[70:71], v[70:71], 0.5, v[100:101] op_sel_hi:[1,0,1]
	v_pk_fma_f32 v[66:67], v[66:67], 0.5, v[104:105] op_sel_hi:[1,0,1]
	v_pk_fma_f32 v[68:69], v[68:69], 0.5, v[112:113] op_sel_hi:[1,0,1]
	global_load_dwordx4 v[116:119], v[82:83], off offset:256
	v_cvt_pk_f16_f32 v69, v68, v69
	v_cvt_pk_f16_f32 v68, v66, v67
	v_cvt_pk_f16_f32 v67, v72, v73
	v_cvt_pk_f16_f32 v66, v70, v71
	global_store_dwordx4 v[98:99], v[66:69], off offset:256
	s_waitcnt vmcnt(3)
	v_cvt_f32_f16_e32 v86, v90
	v_add_u32_e32 v66, 0x90, v146
	v_ashrrev_i32_e32 v67, 31, v66
	v_lshlrev_b64 v[66:67], 12, v[66:67]
	v_lshl_add_u64 v[66:67], s[64:65], 0, v[66:67]
	v_lshl_add_u64 v[68:69], v[66:67], 0, v[148:149]
	global_load_dwordx4 v[74:77], v[68:69], off
	global_load_dwordx4 v[98:101], v[68:69], off offset:256
	v_cvt_f32_f16_sdwa v87, v90 dst_sel:DWORD dst_unused:UNUSED_PAD src0_sel:WORD_1
	v_cvt_f32_f16_e32 v90, v91
	v_cvt_f32_f16_sdwa v91, v91 dst_sel:DWORD dst_unused:UNUSED_PAD src0_sel:WORD_1
	v_cvt_f32_f16_e32 v88, v92
	v_cvt_f32_f16_sdwa v89, v92 dst_sel:DWORD dst_unused:UNUSED_PAD src0_sel:WORD_1
	v_cvt_f32_f16_e32 v92, v93
	v_cvt_f32_f16_sdwa v93, v93 dst_sel:DWORD dst_unused:UNUSED_PAD src0_sel:WORD_1
	v_pk_fma_f32 v[64:65], v[64:65], 0.5, v[90:91] op_sel_hi:[1,0,1]
	v_pk_fma_f32 v[62:63], v[62:63], 0.5, v[86:87] op_sel_hi:[1,0,1]
	v_pk_fma_f32 v[58:59], v[58:59], 0.5, v[88:89] op_sel_hi:[1,0,1]
	v_pk_fma_f32 v[60:61], v[60:61], 0.5, v[92:93] op_sel_hi:[1,0,1]
	s_waitcnt vmcnt(3)
	v_cvt_f32_f16_e32 v94, v116
	v_cvt_f32_f16_sdwa v95, v116 dst_sel:DWORD dst_unused:UNUSED_PAD src0_sel:WORD_1
	v_cvt_f32_f16_e32 v116, v117
	v_cvt_f32_f16_sdwa v117, v117 dst_sel:DWORD dst_unused:UNUSED_PAD src0_sel:WORD_1
	v_cvt_f32_f16_e32 v96, v118
	v_cvt_f32_f16_sdwa v97, v118 dst_sel:DWORD dst_unused:UNUSED_PAD src0_sel:WORD_1
	v_cvt_f32_f16_e32 v118, v119
	v_cvt_f32_f16_sdwa v119, v119 dst_sel:DWORD dst_unused:UNUSED_PAD src0_sel:WORD_1
	v_pk_fma_f32 v[56:57], v[56:57], 0.5, v[116:117] op_sel_hi:[1,0,1]
	v_pk_fma_f32 v[54:55], v[54:55], 0.5, v[94:95] op_sel_hi:[1,0,1]
	v_pk_fma_f32 v[50:51], v[50:51], 0.5, v[96:97] op_sel_hi:[1,0,1]
	v_pk_fma_f32 v[52:53], v[52:53], 0.5, v[118:119] op_sel_hi:[1,0,1]
	v_cvt_pk_f16_f32 v61, v60, v61
	v_cvt_pk_f16_f32 v53, v52, v53
	v_cvt_pk_f16_f32 v52, v50, v51
	v_cvt_pk_f16_f32 v51, v56, v57
	v_cvt_pk_f16_f32 v50, v54, v55
	global_store_dwordx4 v[82:83], v[50:53], off offset:256
	v_cvt_pk_f16_f32 v60, v58, v59
	v_cvt_pk_f16_f32 v59, v64, v65
	v_add_u32_e32 v50, 0xa0, v146
	v_ashrrev_i32_e32 v51, 31, v50
	v_lshlrev_b64 v[50:51], 12, v[50:51]
	v_lshl_add_u64 v[50:51], s[64:65], 0, v[50:51]
	v_cvt_pk_f16_f32 v58, v62, v63
	v_lshl_add_u64 v[50:51], v[50:51], 0, v[148:149]
	global_store_dwordx4 v[84:85], v[58:61], off
	global_load_dwordx4 v[58:61], v[50:51], off
	s_waitcnt vmcnt(4)
	v_cvt_f32_f16_e32 v70, v74
	s_waitcnt vmcnt(3)
	v_cvt_f32_f16_e32 v78, v98
	v_cvt_f32_f16_sdwa v79, v98 dst_sel:DWORD dst_unused:UNUSED_PAD src0_sel:WORD_1
	v_cvt_f32_f16_e32 v98, v99
	v_cvt_f32_f16_sdwa v99, v99 dst_sel:DWORD dst_unused:UNUSED_PAD src0_sel:WORD_1
	v_cvt_f32_f16_e32 v80, v100
	v_cvt_f32_f16_sdwa v81, v100 dst_sel:DWORD dst_unused:UNUSED_PAD src0_sel:WORD_1
	v_cvt_f32_f16_e32 v100, v101
	v_cvt_f32_f16_sdwa v101, v101 dst_sel:DWORD dst_unused:UNUSED_PAD src0_sel:WORD_1
	v_cvt_f32_f16_sdwa v71, v74 dst_sel:DWORD dst_unused:UNUSED_PAD src0_sel:WORD_1
	v_cvt_f32_f16_e32 v74, v75
	v_cvt_f32_f16_sdwa v75, v75 dst_sel:DWORD dst_unused:UNUSED_PAD src0_sel:WORD_1
	v_cvt_f32_f16_e32 v72, v76
	v_cvt_f32_f16_sdwa v73, v76 dst_sel:DWORD dst_unused:UNUSED_PAD src0_sel:WORD_1
	v_cvt_f32_f16_e32 v76, v77
	v_cvt_f32_f16_sdwa v77, v77 dst_sel:DWORD dst_unused:UNUSED_PAD src0_sel:WORD_1
	v_pk_fma_f32 v[40:41], v[40:41], 0.5, v[98:99] op_sel_hi:[1,0,1]
	v_pk_fma_f32 v[38:39], v[38:39], 0.5, v[78:79] op_sel_hi:[1,0,1]
	v_pk_fma_f32 v[36:37], v[36:37], 0.5, v[100:101] op_sel_hi:[1,0,1]
	v_pk_fma_f32 v[34:35], v[34:35], 0.5, v[80:81] op_sel_hi:[1,0,1]
	global_load_dwordx4 v[82:85], v[50:51], off offset:256
	v_cvt_pk_f16_f32 v37, v36, v37
	v_cvt_pk_f16_f32 v36, v34, v35
	v_cvt_pk_f16_f32 v35, v40, v41
	v_cvt_pk_f16_f32 v34, v38, v39
	global_store_dwordx4 v[68:69], v[34:37], off offset:256
	v_pk_fma_f32 v[48:49], v[48:49], 0.5, v[74:75] op_sel_hi:[1,0,1]
	v_pk_fma_f32 v[46:47], v[46:47], 0.5, v[70:71] op_sel_hi:[1,0,1]
	v_add_u32_e32 v34, 0xb0, v146
	v_ashrrev_i32_e32 v35, 31, v34
	v_pk_fma_f32 v[44:45], v[44:45], 0.5, v[76:77] op_sel_hi:[1,0,1]
	v_pk_fma_f32 v[42:43], v[42:43], 0.5, v[72:73] op_sel_hi:[1,0,1]
	v_lshlrev_b64 v[34:35], 12, v[34:35]
	v_cvt_pk_f16_f32 v45, v44, v45
	v_cvt_pk_f16_f32 v44, v42, v43
	v_cvt_pk_f16_f32 v43, v48, v49
	v_cvt_pk_f16_f32 v42, v46, v47
	v_lshl_add_u64 v[34:35], s[64:65], 0, v[34:35]
	global_store_dwordx4 v[68:69], v[42:45], off
	s_waitcnt vmcnt(3)
	v_cvt_f32_f16_e32 v54, v58
	v_lshl_add_u64 v[42:43], v[34:35], 0, v[148:149]
	global_load_dwordx4 v[34:37], v[42:43], off
	global_load_dwordx4 v[38:41], v[42:43], off offset:256
	v_cvt_f32_f16_sdwa v55, v58 dst_sel:DWORD dst_unused:UNUSED_PAD src0_sel:WORD_1
	v_cvt_f32_f16_e32 v58, v59
	v_cvt_f32_f16_sdwa v59, v59 dst_sel:DWORD dst_unused:UNUSED_PAD src0_sel:WORD_1
	v_cvt_f32_f16_e32 v52, v60
	v_cvt_f32_f16_sdwa v53, v60 dst_sel:DWORD dst_unused:UNUSED_PAD src0_sel:WORD_1
	v_cvt_f32_f16_e32 v56, v61
	v_cvt_f32_f16_sdwa v57, v61 dst_sel:DWORD dst_unused:UNUSED_PAD src0_sel:WORD_1
	v_pk_fma_f32 v[32:33], v[32:33], 0.5, v[58:59] op_sel_hi:[1,0,1]
	v_pk_fma_f32 v[30:31], v[30:31], 0.5, v[54:55] op_sel_hi:[1,0,1]
	v_pk_fma_f32 v[26:27], v[26:27], 0.5, v[52:53] op_sel_hi:[1,0,1]
	v_pk_fma_f32 v[28:29], v[28:29], 0.5, v[56:57] op_sel_hi:[1,0,1]
	s_waitcnt vmcnt(4)
	v_cvt_f32_f16_e32 v62, v82
	v_cvt_f32_f16_sdwa v63, v82 dst_sel:DWORD dst_unused:UNUSED_PAD src0_sel:WORD_1
	v_cvt_f32_f16_e32 v66, v83
	v_cvt_f32_f16_sdwa v67, v83 dst_sel:DWORD dst_unused:UNUSED_PAD src0_sel:WORD_1
	v_cvt_f32_f16_e32 v60, v84
	v_cvt_f32_f16_sdwa v61, v84 dst_sel:DWORD dst_unused:UNUSED_PAD src0_sel:WORD_1
	v_cvt_f32_f16_e32 v64, v85
	v_cvt_f32_f16_sdwa v65, v85 dst_sel:DWORD dst_unused:UNUSED_PAD src0_sel:WORD_1
	v_pk_fma_f32 v[24:25], v[24:25], 0.5, v[66:67] op_sel_hi:[1,0,1]
	v_pk_fma_f32 v[22:23], v[22:23], 0.5, v[62:63] op_sel_hi:[1,0,1]
	v_pk_fma_f32 v[18:19], v[18:19], 0.5, v[60:61] op_sel_hi:[1,0,1]
	v_pk_fma_f32 v[20:21], v[20:21], 0.5, v[64:65] op_sel_hi:[1,0,1]
	v_cvt_pk_f16_f32 v29, v28, v29
	v_cvt_pk_f16_f32 v28, v26, v27
	v_cvt_pk_f16_f32 v27, v32, v33
	v_cvt_pk_f16_f32 v26, v30, v31
	v_cvt_pk_f16_f32 v21, v20, v21
	v_cvt_pk_f16_f32 v20, v18, v19
	v_cvt_pk_f16_f32 v19, v24, v25
	v_cvt_pk_f16_f32 v18, v22, v23
	global_store_dwordx4 v[50:51], v[26:29], off
	global_store_dwordx4 v[50:51], v[18:21], off offset:256
	s_waitcnt vmcnt(3)
	v_cvt_f32_f16_e32 v30, v34
	s_waitcnt vmcnt(2)
	v_cvt_f32_f16_e32 v18, v40
	v_cvt_f32_f16_sdwa v19, v40 dst_sel:DWORD dst_unused:UNUSED_PAD src0_sel:WORD_1
	v_cvt_f32_f16_e32 v20, v41
	v_cvt_f32_f16_sdwa v21, v41 dst_sel:DWORD dst_unused:UNUSED_PAD src0_sel:WORD_1
	v_cvt_f32_f16_e32 v22, v38
	v_cvt_f32_f16_sdwa v23, v38 dst_sel:DWORD dst_unused:UNUSED_PAD src0_sel:WORD_1
	v_cvt_f32_f16_e32 v24, v39
	v_cvt_f32_f16_sdwa v25, v39 dst_sel:DWORD dst_unused:UNUSED_PAD src0_sel:WORD_1
	v_cvt_f32_f16_e32 v26, v36
	v_cvt_f32_f16_sdwa v27, v36 dst_sel:DWORD dst_unused:UNUSED_PAD src0_sel:WORD_1
	v_cvt_f32_f16_e32 v28, v37
	v_cvt_f32_f16_sdwa v29, v37 dst_sel:DWORD dst_unused:UNUSED_PAD src0_sel:WORD_1
	v_cvt_f32_f16_sdwa v31, v34 dst_sel:DWORD dst_unused:UNUSED_PAD src0_sel:WORD_1
	v_cvt_f32_f16_e32 v32, v35
	v_cvt_f32_f16_sdwa v33, v35 dst_sel:DWORD dst_unused:UNUSED_PAD src0_sel:WORD_1
	v_pk_fma_f32 v[12:13], v[12:13], 0.5, v[28:29] op_sel_hi:[1,0,1]
	v_pk_fma_f32 v[14:15], v[14:15], 0.5, v[30:31] op_sel_hi:[1,0,1]
	v_pk_fma_f32 v[10:11], v[10:11], 0.5, v[26:27] op_sel_hi:[1,0,1]
	v_pk_fma_f32 v[16:17], v[16:17], 0.5, v[32:33] op_sel_hi:[1,0,1]
	v_pk_fma_f32 v[8:9], v[8:9], 0.5, v[24:25] op_sel_hi:[1,0,1]
	v_pk_fma_f32 v[6:7], v[6:7], 0.5, v[22:23] op_sel_hi:[1,0,1]
	v_pk_fma_f32 v[4:5], v[4:5], 0.5, v[20:21] op_sel_hi:[1,0,1]
	v_pk_fma_f32 v[2:3], v[2:3], 0.5, v[18:19] op_sel_hi:[1,0,1]
	v_cvt_pk_f16_f32 v13, v12, v13
	v_cvt_pk_f16_f32 v12, v10, v11
	v_cvt_pk_f16_f32 v11, v16, v17
	v_cvt_pk_f16_f32 v10, v14, v15
	v_cvt_pk_f16_f32 v5, v4, v5
	v_cvt_pk_f16_f32 v4, v2, v3
	v_cvt_pk_f16_f32 v3, v8, v9
	v_cvt_pk_f16_f32 v2, v6, v7
	global_store_dwordx4 v[42:43], v[10:13], off
	global_store_dwordx4 v[42:43], v[2:5], off offset:256
	s_cbranch_vccnz .LBB0_1225
	s_andn2_b64 vcc, exec, s[8:9]
	s_cbranch_vccnz .LBB0_1224
	s_barrier
	s_branch .LBB0_1224

.LBB0_2092:
	v_lshl_or_b32 v130, s74, 8, v177
	v_lshl_add_u32 v162, s73, 8, v1
	v_ashrrev_i32_e32 v131, 31, v130
	v_lshlrev_b64 v[164:165], 1, v[130:131]
	v_or_b32_e32 v130, 16, v162
	v_ashrrev_i32_e32 v163, 31, v162
	v_ashrrev_i32_e32 v131, 31, v130
	v_lshlrev_b64 v[132:133], 12, v[162:163]
	v_lshlrev_b64 v[130:131], 12, v[130:131]
	v_lshl_add_u64 v[132:133], s[64:65], 0, v[132:133]
	v_lshl_add_u64 v[130:131], s[64:65], 0, v[130:131]
	v_lshl_add_u64 v[174:175], v[132:133], 0, v[164:165]
	v_lshl_add_u64 v[172:173], v[130:131], 0, v[164:165]
	v_mov_b32_e32 v235, 0
	global_load_dwordx4 v[228:231], v[174:175], off
	global_load_dwordx4 v[228:231], v[174:175], off offset:256
	v_mov_b32_e32 v234, 1
	v_lshl_add_u64 v[232:233], v[234:235], 16, v[174:175]
	global_load_dwordx4 v[228:231], v[232:233], off
	global_load_dwordx4 v[228:231], v[232:233], off offset:256
	v_mov_b32_e32 v234, 2
	v_lshl_add_u64 v[232:233], v[234:235], 16, v[174:175]
	global_load_dwordx4 v[228:231], v[232:233], off
	global_load_dwordx4 v[228:231], v[232:233], off offset:256
	v_mov_b32_e32 v234, 3
	v_lshl_add_u64 v[232:233], v[234:235], 16, v[174:175]
	global_load_dwordx4 v[228:231], v[232:233], off
	global_load_dwordx4 v[228:231], v[232:233], off offset:256
	v_mov_b32_e32 v234, 8
	v_lshl_add_u64 v[232:233], v[234:235], 16, v[174:175]
	global_load_dwordx4 v[228:231], v[232:233], off
	global_load_dwordx4 v[228:231], v[232:233], off offset:256
	v_mov_b32_e32 v234, 9
	v_lshl_add_u64 v[232:233], v[234:235], 16, v[174:175]
	global_load_dwordx4 v[228:231], v[232:233], off
	global_load_dwordx4 v[228:231], v[232:233], off offset:256
	v_mov_b32_e32 v234, 10
	v_lshl_add_u64 v[232:233], v[234:235], 16, v[174:175]
	global_load_dwordx4 v[228:231], v[232:233], off
	global_load_dwordx4 v[228:231], v[232:233], off offset:256
	v_mov_b32_e32 v234, 11
	v_lshl_add_u64 v[232:233], v[234:235], 16, v[174:175]
	global_load_dwordx4 v[228:231], v[232:233], off
	global_load_dwordx4 v[228:231], v[232:233], off offset:256
	global_load_dwordx4 v[134:137], v[174:175], off
	global_load_dwordx4 v[138:141], v[174:175], off offset:256
	global_load_dwordx4 v[142:145], v[172:173], off
	global_load_dwordx4 v[182:185], v[172:173], off offset:256
	v_or_b32_e32 v130, 32, v162
	v_ashrrev_i32_e32 v131, 31, v130
	v_lshlrev_b64 v[130:131], 12, v[130:131]
	v_lshl_add_u64 v[130:131], s[64:65], 0, v[130:131]
	v_lshl_add_u64 v[166:167], v[130:131], 0, v[164:165]
	global_load_dwordx4 v[186:189], v[166:167], off
	global_load_dwordx4 v[190:193], v[166:167], off offset:256
	v_or_b32_e32 v130, 48, v162
	v_ashrrev_i32_e32 v131, 31, v130
	v_lshlrev_b64 v[130:131], 12, v[130:131]
	s_mov_b32 s0, 0x80000
	v_lshl_add_u64 v[130:131], s[64:65], 0, v[130:131]
	v_lshl_add_u64 v[170:171], v[130:131], 0, v[164:165]
	v_add_co_u32_e32 v168, vcc, s0, v174
	s_mov_b64 s[0:1], 0x80000
	s_nop 0
	v_addc_co_u32_e32 v169, vcc, 0, v175, vcc
	global_load_dwordx4 v[194:197], v[170:171], off
	global_load_dwordx4 v[198:201], v[170:171], off offset:256
	global_load_dwordx4 v[130:133], v[168:169], off
	s_and_b64 vcc, exec, s[2:3]
	s_waitcnt vmcnt(0)
	v_cvt_f32_f16_e32 v202, v134
	v_cvt_f32_f16_e32 v210, v142
	v_cvt_f32_f16_sdwa v211, v142 dst_sel:DWORD dst_unused:UNUSED_PAD src0_sel:WORD_1
	v_cvt_f32_f16_e32 v212, v144
	v_cvt_f32_f16_sdwa v213, v144 dst_sel:DWORD dst_unused:UNUSED_PAD src0_sel:WORD_1
	v_cvt_f32_f16_e32 v144, v145
	v_cvt_f32_f16_sdwa v145, v145 dst_sel:DWORD dst_unused:UNUSED_PAD src0_sel:WORD_1
	v_cvt_f32_f16_e32 v218, v184
	v_cvt_f32_f16_sdwa v219, v184 dst_sel:DWORD dst_unused:UNUSED_PAD src0_sel:WORD_1
	v_cvt_f32_f16_e32 v214, v182
	v_cvt_f32_f16_sdwa v215, v182 dst_sel:DWORD dst_unused:UNUSED_PAD src0_sel:WORD_1
	v_cvt_f32_f16_sdwa v203, v134 dst_sel:DWORD dst_unused:UNUSED_PAD src0_sel:WORD_1
	v_cvt_f32_f16_e32 v134, v135
	v_cvt_f32_f16_sdwa v135, v135 dst_sel:DWORD dst_unused:UNUSED_PAD src0_sel:WORD_1
	v_cvt_f32_f16_e32 v204, v136
	v_cvt_f32_f16_sdwa v205, v136 dst_sel:DWORD dst_unused:UNUSED_PAD src0_sel:WORD_1
	v_cvt_f32_f16_e32 v136, v137
	v_cvt_f32_f16_sdwa v137, v137 dst_sel:DWORD dst_unused:UNUSED_PAD src0_sel:WORD_1
	v_cvt_f32_f16_e32 v206, v138
	v_cvt_f32_f16_sdwa v207, v138 dst_sel:DWORD dst_unused:UNUSED_PAD src0_sel:WORD_1
	v_cvt_f32_f16_e32 v138, v139
	v_cvt_f32_f16_sdwa v139, v139 dst_sel:DWORD dst_unused:UNUSED_PAD src0_sel:WORD_1
	v_cvt_f32_f16_e32 v208, v140
	v_cvt_f32_f16_sdwa v209, v140 dst_sel:DWORD dst_unused:UNUSED_PAD src0_sel:WORD_1
	v_cvt_f32_f16_e32 v140, v141
	v_cvt_f32_f16_sdwa v141, v141 dst_sel:DWORD dst_unused:UNUSED_PAD src0_sel:WORD_1
	v_cvt_f32_f16_e32 v142, v143
	v_cvt_f32_f16_sdwa v143, v143 dst_sel:DWORD dst_unused:UNUSED_PAD src0_sel:WORD_1
	v_pk_fma_f32 v[110:111], v[110:111], 0.5, v[210:211] op_sel_hi:[1,0,1]
	v_pk_fma_f32 v[108:109], v[108:109], 0.5, v[144:145] op_sel_hi:[1,0,1]
	v_pk_fma_f32 v[106:107], v[106:107], 0.5, v[212:213] op_sel_hi:[1,0,1]
	v_pk_fma_f32 v[98:99], v[98:99], 0.5, v[218:219] op_sel_hi:[1,0,1]
	v_cvt_pk_f16_f32 v109, v108, v109
	v_cvt_pk_f16_f32 v108, v106, v107
	v_cvt_pk_f16_f32 v106, v110, v111
	v_pk_fma_f32 v[110:111], v[102:103], 0.5, v[214:215] op_sel_hi:[1,0,1]
	v_cvt_pk_f16_f32 v102, v98, v99
	v_add_u32_e32 v98, 0x90, v162
	v_cvt_f32_f16_e32 v182, v183
	v_cvt_f32_f16_sdwa v183, v183 dst_sel:DWORD dst_unused:UNUSED_PAD src0_sel:WORD_1
	v_ashrrev_i32_e32 v99, 31, v98
	v_pk_fma_f32 v[128:129], v[128:129], 0.5, v[134:135] op_sel_hi:[1,0,1]
	v_pk_fma_f32 v[126:127], v[126:127], 0.5, v[202:203] op_sel_hi:[1,0,1]
	v_pk_fma_f32 v[124:125], v[124:125], 0.5, v[136:137] op_sel_hi:[1,0,1]
	v_pk_fma_f32 v[122:123], v[122:123], 0.5, v[204:205] op_sel_hi:[1,0,1]
	v_lshlrev_b64 v[98:99], 12, v[98:99]
	v_pk_fma_f32 v[134:135], v[120:121], 0.5, v[138:139] op_sel_hi:[1,0,1]
	v_pk_fma_f32 v[136:137], v[118:119], 0.5, v[206:207] op_sel_hi:[1,0,1]
	v_pk_fma_f32 v[118:119], v[116:117], 0.5, v[140:141] op_sel_hi:[1,0,1]
	v_pk_fma_f32 v[138:139], v[114:115], 0.5, v[208:209] op_sel_hi:[1,0,1]
	v_cvt_pk_f16_f32 v117, v124, v125
	v_cvt_pk_f16_f32 v116, v122, v123
	v_cvt_pk_f16_f32 v115, v128, v129
	v_cvt_pk_f16_f32 v114, v126, v127
	v_pk_fma_f32 v[112:113], v[112:113], 0.5, v[142:143] op_sel_hi:[1,0,1]
	v_lshl_add_u64 v[98:99], s[64:65], 0, v[98:99]
	v_cvt_pk_f16_f32 v121, v118, v119
	v_cvt_pk_f16_f32 v120, v138, v139
	v_cvt_pk_f16_f32 v119, v134, v135
	v_cvt_pk_f16_f32 v118, v136, v137
	global_store_dwordx4 v[174:175], v[114:117], off
	global_store_dwordx4 v[174:175], v[118:121], off offset:256
	v_cvt_pk_f16_f32 v107, v112, v113
	v_lshl_add_u64 v[98:99], v[98:99], 0, v[164:165]
	global_store_dwordx4 v[172:173], v[106:109], off
	v_cvt_f32_f16_e32 v126, v192
	v_cvt_f32_f16_sdwa v127, v192 dst_sel:DWORD dst_unused:UNUSED_PAD src0_sel:WORD_1
	v_pk_fma_f32 v[108:109], v[104:105], 0.5, v[182:183] op_sel_hi:[1,0,1]
	global_load_dwordx4 v[104:107], v[98:99], off
	v_cvt_f32_f16_e32 v128, v193
	v_cvt_f32_f16_sdwa v129, v193 dst_sel:DWORD dst_unused:UNUSED_PAD src0_sel:WORD_1
	v_cvt_f32_f16_e32 v184, v185
	v_cvt_f32_f16_sdwa v185, v185 dst_sel:DWORD dst_unused:UNUSED_PAD src0_sel:WORD_1
	v_cvt_f32_f16_e32 v220, v186
	v_cvt_f32_f16_sdwa v221, v186 dst_sel:DWORD dst_unused:UNUSED_PAD src0_sel:WORD_1
	v_cvt_f32_f16_e32 v186, v187
	v_cvt_f32_f16_sdwa v187, v187 dst_sel:DWORD dst_unused:UNUSED_PAD src0_sel:WORD_1
	v_cvt_f32_f16_e32 v222, v188
	v_cvt_f32_f16_sdwa v223, v188 dst_sel:DWORD dst_unused:UNUSED_PAD src0_sel:WORD_1
	v_cvt_f32_f16_e32 v120, v189
	v_cvt_f32_f16_sdwa v121, v189 dst_sel:DWORD dst_unused:UNUSED_PAD src0_sel:WORD_1
	v_lshl_add_u64 v[114:115], v[174:175], 0, s[0:1]
	v_cvt_f32_f16_e32 v122, v190
	v_cvt_f32_f16_sdwa v123, v190 dst_sel:DWORD dst_unused:UNUSED_PAD src0_sel:WORD_1
	v_cvt_f32_f16_e32 v124, v191
	global_load_dwordx4 v[116:119], v[114:115], off offset:256
	v_cvt_f32_f16_sdwa v125, v191 dst_sel:DWORD dst_unused:UNUSED_PAD src0_sel:WORD_1
	v_pk_fma_f32 v[84:85], v[84:85], 0.5, v[128:129] op_sel_hi:[1,0,1]
	v_pk_fma_f32 v[82:83], v[82:83], 0.5, v[126:127] op_sel_hi:[1,0,1]
	v_cvt_f32_f16_e32 v136, v198
	v_cvt_f32_f16_sdwa v137, v198 dst_sel:DWORD dst_unused:UNUSED_PAD src0_sel:WORD_1
	v_cvt_f32_f16_e32 v138, v199
	v_cvt_f32_f16_sdwa v139, v199 dst_sel:DWORD dst_unused:UNUSED_PAD src0_sel:WORD_1
	v_cvt_f32_f16_e32 v140, v200
	v_cvt_f32_f16_sdwa v141, v200 dst_sel:DWORD dst_unused:UNUSED_PAD src0_sel:WORD_1
	v_cvt_f32_f16_e32 v142, v201
	v_cvt_f32_f16_sdwa v143, v201 dst_sel:DWORD dst_unused:UNUSED_PAD src0_sel:WORD_1
	v_cvt_pk_f16_f32 v85, v84, v85
	v_cvt_pk_f16_f32 v84, v82, v83
	v_add_u32_e32 v82, 0xa0, v162
	v_pk_fma_f32 v[100:101], v[100:101], 0.5, v[184:185] op_sel_hi:[1,0,1]
	v_pk_fma_f32 v[96:97], v[96:97], 0.5, v[186:187] op_sel_hi:[1,0,1]
	v_pk_fma_f32 v[94:95], v[94:95], 0.5, v[220:221] op_sel_hi:[1,0,1]
	v_pk_fma_f32 v[92:93], v[92:93], 0.5, v[120:121] op_sel_hi:[1,0,1]
	v_pk_fma_f32 v[90:91], v[90:91], 0.5, v[222:223] op_sel_hi:[1,0,1]
	v_ashrrev_i32_e32 v83, 31, v82
	v_cvt_pk_f16_f32 v103, v100, v101
	v_cvt_pk_f16_f32 v101, v108, v109
	v_cvt_pk_f16_f32 v100, v110, v111
	v_cvt_pk_f16_f32 v93, v92, v93
	v_cvt_pk_f16_f32 v92, v90, v91
	v_cvt_pk_f16_f32 v91, v96, v97
	v_cvt_pk_f16_f32 v90, v94, v95
	v_lshlrev_b64 v[82:83], 12, v[82:83]
	global_store_dwordx4 v[172:173], v[100:103], off offset:256
	global_load_dwordx4 v[100:103], v[98:99], off offset:256
	v_lshl_add_u64 v[82:83], s[64:65], 0, v[82:83]
	global_store_dwordx4 v[166:167], v[90:93], off
	v_cvt_f32_f16_e32 v108, v194
	v_cvt_f32_f16_sdwa v109, v194 dst_sel:DWORD dst_unused:UNUSED_PAD src0_sel:WORD_1
	v_pk_fma_f32 v[90:91], v[88:89], 0.5, v[124:125] op_sel_hi:[1,0,1]
	v_pk_fma_f32 v[92:93], v[86:87], 0.5, v[122:123] op_sel_hi:[1,0,1]
	v_cvt_f32_f16_e32 v110, v195
	v_cvt_f32_f16_sdwa v111, v195 dst_sel:DWORD dst_unused:UNUSED_PAD src0_sel:WORD_1
	v_cvt_f32_f16_e32 v112, v196
	v_cvt_f32_f16_sdwa v113, v196 dst_sel:DWORD dst_unused:UNUSED_PAD src0_sel:WORD_1
	v_cvt_f32_f16_e32 v134, v197
	v_cvt_f32_f16_sdwa v135, v197 dst_sel:DWORD dst_unused:UNUSED_PAD src0_sel:WORD_1
	v_lshl_add_u64 v[94:95], v[82:83], 0, v[164:165]
	v_cvt_pk_f16_f32 v83, v90, v91
	v_cvt_pk_f16_f32 v82, v92, v93
	v_pk_fma_f32 v[72:73], v[72:73], 0.5, v[138:139] op_sel_hi:[1,0,1]
	v_pk_fma_f32 v[70:71], v[70:71], 0.5, v[136:137] op_sel_hi:[1,0,1]
	v_pk_fma_f32 v[68:69], v[68:69], 0.5, v[142:143] op_sel_hi:[1,0,1]
	v_pk_fma_f32 v[66:67], v[66:67], 0.5, v[140:141] op_sel_hi:[1,0,1]
	global_load_dwordx4 v[86:89], v[94:95], off
	v_cvt_pk_f16_f32 v69, v68, v69
	global_store_dwordx4 v[166:167], v[82:85], off offset:256
	global_load_dwordx4 v[82:85], v[94:95], off offset:256
	v_cvt_pk_f16_f32 v68, v66, v67
	v_cvt_pk_f16_f32 v67, v72, v73
	v_cvt_pk_f16_f32 v66, v70, v71
	global_store_dwordx4 v[170:171], v[66:69], off offset:256
	v_pk_fma_f32 v[80:81], v[80:81], 0.5, v[110:111] op_sel_hi:[1,0,1]
	v_pk_fma_f32 v[78:79], v[78:79], 0.5, v[108:109] op_sel_hi:[1,0,1]
	v_add_u32_e32 v66, 0xb0, v162
	v_ashrrev_i32_e32 v67, 31, v66
	v_pk_fma_f32 v[76:77], v[76:77], 0.5, v[134:135] op_sel_hi:[1,0,1]
	v_pk_fma_f32 v[74:75], v[74:75], 0.5, v[112:113] op_sel_hi:[1,0,1]
	v_lshlrev_b64 v[66:67], 12, v[66:67]
	v_cvt_pk_f16_f32 v77, v76, v77
	v_cvt_pk_f16_f32 v76, v74, v75
	v_cvt_pk_f16_f32 v75, v80, v81
	v_cvt_pk_f16_f32 v74, v78, v79
	v_lshl_add_u64 v[66:67], s[64:65], 0, v[66:67]
	global_store_dwordx4 v[170:171], v[74:77], off
	v_cvt_f32_f16_e32 v90, v130
	v_cvt_f32_f16_sdwa v91, v130 dst_sel:DWORD dst_unused:UNUSED_PAD src0_sel:WORD_1
	s_waitcnt vmcnt(9)
	v_cvt_f32_f16_e32 v74, v104
	v_cvt_f32_f16_sdwa v75, v104 dst_sel:DWORD dst_unused:UNUSED_PAD src0_sel:WORD_1
	v_cvt_f32_f16_e32 v76, v105
	v_cvt_f32_f16_sdwa v77, v105 dst_sel:DWORD dst_unused:UNUSED_PAD src0_sel:WORD_1
	v_lshl_add_u64 v[104:105], v[66:67], 0, v[164:165]
	global_load_dwordx4 v[66:69], v[104:105], off
	global_load_dwordx4 v[70:73], v[104:105], off offset:256
	v_cvt_f32_f16_e32 v92, v131
	v_cvt_f32_f16_sdwa v93, v131 dst_sel:DWORD dst_unused:UNUSED_PAD src0_sel:WORD_1
	v_cvt_f32_f16_e32 v96, v132
	v_cvt_f32_f16_sdwa v97, v132 dst_sel:DWORD dst_unused:UNUSED_PAD src0_sel:WORD_1
	v_cvt_f32_f16_e32 v120, v133
	v_cvt_f32_f16_sdwa v121, v133 dst_sel:DWORD dst_unused:UNUSED_PAD src0_sel:WORD_1
	s_waitcnt vmcnt(10)
	v_cvt_f32_f16_e32 v122, v116
	v_cvt_f32_f16_sdwa v123, v116 dst_sel:DWORD dst_unused:UNUSED_PAD src0_sel:WORD_1
	v_cvt_f32_f16_e32 v116, v117
	v_cvt_f32_f16_sdwa v117, v117 dst_sel:DWORD dst_unused:UNUSED_PAD src0_sel:WORD_1
	v_cvt_f32_f16_e32 v124, v118
	v_cvt_f32_f16_sdwa v125, v118 dst_sel:DWORD dst_unused:UNUSED_PAD src0_sel:WORD_1
	v_cvt_f32_f16_e32 v118, v119
	v_cvt_f32_f16_sdwa v119, v119 dst_sel:DWORD dst_unused:UNUSED_PAD src0_sel:WORD_1
	v_cvt_f32_f16_e32 v78, v106
	v_cvt_f32_f16_sdwa v79, v106 dst_sel:DWORD dst_unused:UNUSED_PAD src0_sel:WORD_1
	v_cvt_f32_f16_e32 v80, v107
	v_cvt_f32_f16_sdwa v81, v107 dst_sel:DWORD dst_unused:UNUSED_PAD src0_sel:WORD_1
	v_pk_fma_f32 v[64:65], v[64:65], 0.5, v[92:93] op_sel_hi:[1,0,1]
	v_pk_fma_f32 v[62:63], v[62:63], 0.5, v[90:91] op_sel_hi:[1,0,1]
	v_pk_fma_f32 v[60:61], v[60:61], 0.5, v[120:121] op_sel_hi:[1,0,1]
	v_pk_fma_f32 v[58:59], v[58:59], 0.5, v[96:97] op_sel_hi:[1,0,1]
	v_pk_fma_f32 v[56:57], v[56:57], 0.5, v[116:117] op_sel_hi:[1,0,1]
	v_pk_fma_f32 v[54:55], v[54:55], 0.5, v[122:123] op_sel_hi:[1,0,1]
	v_pk_fma_f32 v[48:49], v[48:49], 0.5, v[118:119] op_sel_hi:[1,0,1]
	v_pk_fma_f32 v[46:47], v[46:47], 0.5, v[124:125] op_sel_hi:[1,0,1]
	v_cvt_pk_f16_f32 v61, v60, v61
	v_cvt_pk_f16_f32 v60, v58, v59
	v_cvt_pk_f16_f32 v59, v64, v65
	v_cvt_pk_f16_f32 v58, v62, v63
	v_cvt_pk_f16_f32 v49, v48, v49
	s_waitcnt vmcnt(8)
	v_cvt_f32_f16_e32 v106, v100
	v_cvt_f32_f16_sdwa v107, v100 dst_sel:DWORD dst_unused:UNUSED_PAD src0_sel:WORD_1
	v_cvt_f32_f16_e32 v100, v101
	v_cvt_f32_f16_sdwa v101, v101 dst_sel:DWORD dst_unused:UNUSED_PAD src0_sel:WORD_1
	v_cvt_f32_f16_e32 v108, v102
	v_cvt_f32_f16_sdwa v109, v102 dst_sel:DWORD dst_unused:UNUSED_PAD src0_sel:WORD_1
	v_cvt_f32_f16_e32 v102, v103
	v_cvt_f32_f16_sdwa v103, v103 dst_sel:DWORD dst_unused:UNUSED_PAD src0_sel:WORD_1
	v_cvt_pk_f16_f32 v48, v46, v47
	v_cvt_pk_f16_f32 v47, v56, v57
	v_cvt_pk_f16_f32 v46, v54, v55
	global_store_dwordx4 v[168:169], v[58:61], off
	global_store_dwordx4 v[114:115], v[46:49], off offset:256
	v_pk_fma_f32 v[32:33], v[32:33], 0.5, v[100:101] op_sel_hi:[1,0,1]
	v_pk_fma_f32 v[30:31], v[30:31], 0.5, v[106:107] op_sel_hi:[1,0,1]
	v_pk_fma_f32 v[28:29], v[28:29], 0.5, v[102:103] op_sel_hi:[1,0,1]
	v_pk_fma_f32 v[26:27], v[26:27], 0.5, v[108:109] op_sel_hi:[1,0,1]
	v_cvt_pk_f16_f32 v29, v28, v29
	v_cvt_pk_f16_f32 v28, v26, v27
	v_cvt_pk_f16_f32 v27, v32, v33
	s_waitcnt vmcnt(8)
	v_cvt_f32_f16_e32 v46, v86
	v_cvt_f32_f16_sdwa v47, v86 dst_sel:DWORD dst_unused:UNUSED_PAD src0_sel:WORD_1
	v_cvt_f32_f16_e32 v48, v87
	v_cvt_f32_f16_sdwa v49, v87 dst_sel:DWORD dst_unused:UNUSED_PAD src0_sel:WORD_1
	v_cvt_f32_f16_e32 v54, v88
	v_cvt_f32_f16_sdwa v55, v88 dst_sel:DWORD dst_unused:UNUSED_PAD src0_sel:WORD_1
	v_cvt_f32_f16_e32 v56, v89
	v_cvt_f32_f16_sdwa v57, v89 dst_sel:DWORD dst_unused:UNUSED_PAD src0_sel:WORD_1
	s_waitcnt vmcnt(6)
	v_cvt_f32_f16_e32 v58, v82
	v_cvt_f32_f16_sdwa v59, v82 dst_sel:DWORD dst_unused:UNUSED_PAD src0_sel:WORD_1
	v_cvt_f32_f16_e32 v60, v83
	v_cvt_f32_f16_sdwa v61, v83 dst_sel:DWORD dst_unused:UNUSED_PAD src0_sel:WORD_1
	v_cvt_f32_f16_e32 v62, v84
	v_cvt_f32_f16_sdwa v63, v84 dst_sel:DWORD dst_unused:UNUSED_PAD src0_sel:WORD_1
	v_cvt_f32_f16_e32 v64, v85
	v_cvt_f32_f16_sdwa v65, v85 dst_sel:DWORD dst_unused:UNUSED_PAD src0_sel:WORD_1
	v_cvt_pk_f16_f32 v26, v30, v31
	global_store_dwordx4 v[98:99], v[26:29], off offset:256
	v_pk_fma_f32 v[30:31], v[38:39], 0.5, v[46:47] op_sel_hi:[1,0,1]
	v_pk_fma_f32 v[32:33], v[34:35], 0.5, v[54:55] op_sel_hi:[1,0,1]
	v_pk_fma_f32 v[26:27], v[40:41], 0.5, v[48:49] op_sel_hi:[1,0,1]
	v_pk_fma_f32 v[28:29], v[36:37], 0.5, v[56:57] op_sel_hi:[1,0,1]
	v_pk_fma_f32 v[24:25], v[24:25], 0.5, v[60:61] op_sel_hi:[1,0,1]
	v_pk_fma_f32 v[22:23], v[22:23], 0.5, v[58:59] op_sel_hi:[1,0,1]
	v_pk_fma_f32 v[20:21], v[20:21], 0.5, v[64:65] op_sel_hi:[1,0,1]
	v_pk_fma_f32 v[18:19], v[18:19], 0.5, v[62:63] op_sel_hi:[1,0,1]
	v_cvt_pk_f16_f32 v29, v28, v29
	v_cvt_pk_f16_f32 v28, v32, v33
	v_cvt_pk_f16_f32 v27, v26, v27
	v_cvt_pk_f16_f32 v26, v30, v31
	v_cvt_pk_f16_f32 v21, v20, v21
	v_cvt_pk_f16_f32 v20, v18, v19
	v_cvt_pk_f16_f32 v19, v24, v25
	v_cvt_pk_f16_f32 v18, v22, v23
	global_store_dwordx4 v[94:95], v[26:29], off
	global_store_dwordx4 v[94:95], v[18:21], off offset:256
	s_waitcnt vmcnt(5)
	v_cvt_f32_f16_e32 v22, v70
	v_cvt_f32_f16_sdwa v23, v70 dst_sel:DWORD dst_unused:UNUSED_PAD src0_sel:WORD_1
	v_cvt_f32_f16_e32 v18, v72
	v_cvt_f32_f16_sdwa v19, v72 dst_sel:DWORD dst_unused:UNUSED_PAD src0_sel:WORD_1
	v_cvt_f32_f16_e32 v20, v73
	v_cvt_f32_f16_sdwa v21, v73 dst_sel:DWORD dst_unused:UNUSED_PAD src0_sel:WORD_1
	v_cvt_f32_f16_e32 v24, v71
	v_cvt_f32_f16_sdwa v25, v71 dst_sel:DWORD dst_unused:UNUSED_PAD src0_sel:WORD_1
	v_cvt_f32_f16_e32 v26, v68
	v_cvt_f32_f16_e32 v28, v69
	v_cvt_f32_f16_e32 v30, v66
	v_cvt_f32_f16_e32 v32, v67
	v_cvt_f32_f16_sdwa v33, v67 dst_sel:DWORD dst_unused:UNUSED_PAD src0_sel:WORD_1
	v_cvt_f32_f16_sdwa v31, v66 dst_sel:DWORD dst_unused:UNUSED_PAD src0_sel:WORD_1
	v_cvt_f32_f16_sdwa v29, v69 dst_sel:DWORD dst_unused:UNUSED_PAD src0_sel:WORD_1
	v_cvt_f32_f16_sdwa v27, v68 dst_sel:DWORD dst_unused:UNUSED_PAD src0_sel:WORD_1
	v_pk_fma_f32 v[52:53], v[52:53], 0.5, v[76:77] op_sel_hi:[1,0,1]
	v_pk_fma_f32 v[50:51], v[50:51], 0.5, v[74:75] op_sel_hi:[1,0,1]
	v_pk_fma_f32 v[44:45], v[44:45], 0.5, v[80:81] op_sel_hi:[1,0,1]
	v_pk_fma_f32 v[42:43], v[42:43], 0.5, v[78:79] op_sel_hi:[1,0,1]
	v_pk_fma_f32 v[16:17], v[16:17], 0.5, v[32:33] op_sel_hi:[1,0,1]
	v_pk_fma_f32 v[14:15], v[14:15], 0.5, v[30:31] op_sel_hi:[1,0,1]
	v_pk_fma_f32 v[12:13], v[12:13], 0.5, v[28:29] op_sel_hi:[1,0,1]
	v_pk_fma_f32 v[10:11], v[10:11], 0.5, v[26:27] op_sel_hi:[1,0,1]
	v_pk_fma_f32 v[8:9], v[8:9], 0.5, v[24:25] op_sel_hi:[1,0,1]
	v_pk_fma_f32 v[6:7], v[6:7], 0.5, v[22:23] op_sel_hi:[1,0,1]
	v_pk_fma_f32 v[4:5], v[4:5], 0.5, v[20:21] op_sel_hi:[1,0,1]
	v_pk_fma_f32 v[2:3], v[2:3], 0.5, v[18:19] op_sel_hi:[1,0,1]
	v_cvt_pk_f16_f32 v45, v44, v45
	v_cvt_pk_f16_f32 v44, v42, v43
	v_cvt_pk_f16_f32 v43, v52, v53
	v_cvt_pk_f16_f32 v42, v50, v51
	v_cvt_pk_f16_f32 v13, v12, v13
	v_cvt_pk_f16_f32 v12, v10, v11
	v_cvt_pk_f16_f32 v11, v16, v17
	v_cvt_pk_f16_f32 v10, v14, v15
	v_cvt_pk_f16_f32 v5, v4, v5
	v_cvt_pk_f16_f32 v4, v2, v3
	v_cvt_pk_f16_f32 v3, v8, v9
	v_cvt_pk_f16_f32 v2, v6, v7
	s_mov_b64 s[0:1], -1
	global_store_dwordx4 v[98:99], v[42:45], off
	global_store_dwordx4 v[104:105], v[10:13], off
	global_store_dwordx4 v[104:105], v[2:5], off offset:256
	s_cbranch_vccnz .LBB0_2077
	s_andn2_b64 vcc, exec, s[8:9]
	s_cbranch_vccnz .LBB0_2076
	s_barrier
	s_branch .LBB0_2076

.LBB0_2941:
	v_lshl_or_b32 v130, s61, 8, v173
	v_lshl_add_u32 v158, s44, 8, v1
	v_ashrrev_i32_e32 v131, 31, v130
	v_lshlrev_b64 v[160:161], 1, v[130:131]
	v_or_b32_e32 v130, 16, v158
	v_ashrrev_i32_e32 v159, 31, v158
	v_ashrrev_i32_e32 v131, 31, v130
	v_lshlrev_b64 v[132:133], 12, v[158:159]
	v_lshlrev_b64 v[130:131], 12, v[130:131]
	v_lshl_add_u64 v[132:133], s[64:65], 0, v[132:133]
	v_lshl_add_u64 v[130:131], s[64:65], 0, v[130:131]
	v_lshl_add_u64 v[170:171], v[132:133], 0, v[160:161]
	v_lshl_add_u64 v[168:169], v[130:131], 0, v[160:161]
	v_mov_b32_e32 v235, 0
	global_load_dwordx4 v[228:231], v[170:171], off
	global_load_dwordx4 v[228:231], v[170:171], off offset:256
	v_mov_b32_e32 v234, 1
	v_lshl_add_u64 v[232:233], v[234:235], 16, v[170:171]
	global_load_dwordx4 v[228:231], v[232:233], off
	global_load_dwordx4 v[228:231], v[232:233], off offset:256
	v_mov_b32_e32 v234, 2
	v_lshl_add_u64 v[232:233], v[234:235], 16, v[170:171]
	global_load_dwordx4 v[228:231], v[232:233], off
	global_load_dwordx4 v[228:231], v[232:233], off offset:256
	v_mov_b32_e32 v234, 3
	v_lshl_add_u64 v[232:233], v[234:235], 16, v[170:171]
	global_load_dwordx4 v[228:231], v[232:233], off
	global_load_dwordx4 v[228:231], v[232:233], off offset:256
	v_mov_b32_e32 v234, 8
	v_lshl_add_u64 v[232:233], v[234:235], 16, v[170:171]
	global_load_dwordx4 v[228:231], v[232:233], off
	global_load_dwordx4 v[228:231], v[232:233], off offset:256
	v_mov_b32_e32 v234, 9
	v_lshl_add_u64 v[232:233], v[234:235], 16, v[170:171]
	global_load_dwordx4 v[228:231], v[232:233], off
	global_load_dwordx4 v[228:231], v[232:233], off offset:256
	v_mov_b32_e32 v234, 10
	v_lshl_add_u64 v[232:233], v[234:235], 16, v[170:171]
	global_load_dwordx4 v[228:231], v[232:233], off
	global_load_dwordx4 v[228:231], v[232:233], off offset:256
	v_mov_b32_e32 v234, 11
	v_lshl_add_u64 v[232:233], v[234:235], 16, v[170:171]
	global_load_dwordx4 v[228:231], v[232:233], off
	global_load_dwordx4 v[228:231], v[232:233], off offset:256
	global_load_dwordx4 v[134:137], v[170:171], off
	global_load_dwordx4 v[138:141], v[170:171], off offset:256
	global_load_dwordx4 v[178:181], v[168:169], off
	global_load_dwordx4 v[182:185], v[168:169], off offset:256
	v_or_b32_e32 v130, 32, v158
	v_ashrrev_i32_e32 v131, 31, v130
	v_lshlrev_b64 v[130:131], 12, v[130:131]
	v_lshl_add_u64 v[130:131], s[64:65], 0, v[130:131]
	v_lshl_add_u64 v[162:163], v[130:131], 0, v[160:161]
	global_load_dwordx4 v[186:189], v[162:163], off
	global_load_dwordx4 v[190:193], v[162:163], off offset:256
	v_or_b32_e32 v130, 48, v158
	v_ashrrev_i32_e32 v131, 31, v130
	v_lshlrev_b64 v[130:131], 12, v[130:131]
	v_lshl_add_u64 v[130:131], s[64:65], 0, v[130:131]
	v_lshl_add_u64 v[166:167], v[130:131], 0, v[160:161]
	v_add_co_u32_e32 v164, vcc, s60, v170
	s_mov_b64 s[0:1], -1
	s_nop 0
	v_addc_co_u32_e32 v165, vcc, 0, v171, vcc
	global_load_dwordx4 v[194:197], v[166:167], off
	global_load_dwordx4 v[198:201], v[166:167], off offset:256
	global_load_dwordx4 v[130:133], v[164:165], off
	s_andn2_b64 vcc, exec, s[2:3]
	s_waitcnt vmcnt(0)
	v_cvt_f32_f16_e32 v202, v134
	v_cvt_f32_f16_e32 v210, v178
	v_cvt_f32_f16_sdwa v211, v178 dst_sel:DWORD dst_unused:UNUSED_PAD src0_sel:WORD_1
	v_cvt_f32_f16_e32 v212, v180
	v_cvt_f32_f16_sdwa v213, v180 dst_sel:DWORD dst_unused:UNUSED_PAD src0_sel:WORD_1
	v_cvt_f32_f16_e32 v180, v181
	v_cvt_f32_f16_sdwa v181, v181 dst_sel:DWORD dst_unused:UNUSED_PAD src0_sel:WORD_1
	v_cvt_f32_f16_e32 v218, v184
	v_cvt_f32_f16_sdwa v219, v184 dst_sel:DWORD dst_unused:UNUSED_PAD src0_sel:WORD_1
	v_cvt_f32_f16_e32 v214, v182
	v_cvt_f32_f16_sdwa v215, v182 dst_sel:DWORD dst_unused:UNUSED_PAD src0_sel:WORD_1
	v_cvt_f32_f16_sdwa v203, v134 dst_sel:DWORD dst_unused:UNUSED_PAD src0_sel:WORD_1
	v_cvt_f32_f16_e32 v134, v135
	v_cvt_f32_f16_sdwa v135, v135 dst_sel:DWORD dst_unused:UNUSED_PAD src0_sel:WORD_1
	v_cvt_f32_f16_e32 v204, v136
	v_cvt_f32_f16_sdwa v205, v136 dst_sel:DWORD dst_unused:UNUSED_PAD src0_sel:WORD_1
	v_cvt_f32_f16_e32 v136, v137
	v_cvt_f32_f16_sdwa v137, v137 dst_sel:DWORD dst_unused:UNUSED_PAD src0_sel:WORD_1
	v_cvt_f32_f16_e32 v206, v138
	v_cvt_f32_f16_sdwa v207, v138 dst_sel:DWORD dst_unused:UNUSED_PAD src0_sel:WORD_1
	v_cvt_f32_f16_e32 v138, v139
	v_cvt_f32_f16_sdwa v139, v139 dst_sel:DWORD dst_unused:UNUSED_PAD src0_sel:WORD_1
	v_cvt_f32_f16_e32 v208, v140
	v_cvt_f32_f16_sdwa v209, v140 dst_sel:DWORD dst_unused:UNUSED_PAD src0_sel:WORD_1
	v_cvt_f32_f16_e32 v140, v141
	v_cvt_f32_f16_sdwa v141, v141 dst_sel:DWORD dst_unused:UNUSED_PAD src0_sel:WORD_1
	v_cvt_f32_f16_e32 v178, v179
	v_cvt_f32_f16_sdwa v179, v179 dst_sel:DWORD dst_unused:UNUSED_PAD src0_sel:WORD_1
	v_pk_add_f32 v[110:111], v[110:111], v[210:211]
	v_pk_add_f32 v[108:109], v[108:109], v[180:181]
	v_pk_add_f32 v[106:107], v[106:107], v[212:213]
	v_pk_add_f32 v[98:99], v[98:99], v[218:219]
	v_cvt_pk_f16_f32 v109, v108, v109
	v_cvt_pk_f16_f32 v108, v106, v107
	v_cvt_pk_f16_f32 v106, v110, v111
	v_pk_add_f32 v[110:111], v[102:103], v[214:215]
	v_cvt_pk_f16_f32 v102, v98, v99
	v_add_u32_e32 v98, 0x90, v158
	v_cvt_f32_f16_e32 v182, v183
	v_cvt_f32_f16_sdwa v183, v183 dst_sel:DWORD dst_unused:UNUSED_PAD src0_sel:WORD_1
	v_ashrrev_i32_e32 v99, 31, v98
	v_pk_add_f32 v[128:129], v[128:129], v[134:135]
	v_pk_add_f32 v[126:127], v[126:127], v[202:203]
	v_pk_add_f32 v[124:125], v[124:125], v[136:137]
	v_pk_add_f32 v[122:123], v[122:123], v[204:205]
	v_lshlrev_b64 v[98:99], 12, v[98:99]
	v_pk_add_f32 v[134:135], v[120:121], v[138:139]
	v_pk_add_f32 v[136:137], v[118:119], v[206:207]
	v_pk_add_f32 v[118:119], v[116:117], v[140:141]
	v_pk_add_f32 v[138:139], v[114:115], v[208:209]
	v_cvt_pk_f16_f32 v117, v124, v125
	v_cvt_pk_f16_f32 v116, v122, v123
	v_cvt_pk_f16_f32 v115, v128, v129
	v_cvt_pk_f16_f32 v114, v126, v127
	v_pk_add_f32 v[112:113], v[112:113], v[178:179]
	v_lshl_add_u64 v[98:99], s[64:65], 0, v[98:99]
	v_cvt_pk_f16_f32 v121, v118, v119
	v_cvt_pk_f16_f32 v120, v138, v139
	v_cvt_pk_f16_f32 v119, v134, v135
	v_cvt_pk_f16_f32 v118, v136, v137
	global_store_dwordx4 v[170:171], v[114:117], off
	global_store_dwordx4 v[170:171], v[118:121], off offset:256
	v_cvt_pk_f16_f32 v107, v112, v113
	v_lshl_add_u64 v[98:99], v[98:99], 0, v[160:161]
	global_store_dwordx4 v[168:169], v[106:109], off
	v_cvt_f32_f16_e32 v184, v185
	v_cvt_f32_f16_sdwa v185, v185 dst_sel:DWORD dst_unused:UNUSED_PAD src0_sel:WORD_1
	v_pk_add_f32 v[108:109], v[104:105], v[182:183]
	global_load_dwordx4 v[104:107], v[98:99], off
	v_cvt_f32_f16_e32 v126, v192
	v_cvt_f32_f16_sdwa v127, v192 dst_sel:DWORD dst_unused:UNUSED_PAD src0_sel:WORD_1
	v_cvt_f32_f16_e32 v128, v193
	v_cvt_f32_f16_sdwa v129, v193 dst_sel:DWORD dst_unused:UNUSED_PAD src0_sel:WORD_1
	v_cvt_f32_f16_e32 v220, v186
	v_cvt_f32_f16_sdwa v221, v186 dst_sel:DWORD dst_unused:UNUSED_PAD src0_sel:WORD_1
	v_cvt_f32_f16_e32 v186, v187
	v_cvt_f32_f16_sdwa v187, v187 dst_sel:DWORD dst_unused:UNUSED_PAD src0_sel:WORD_1
	v_cvt_f32_f16_e32 v222, v188
	v_cvt_f32_f16_sdwa v223, v188 dst_sel:DWORD dst_unused:UNUSED_PAD src0_sel:WORD_1
	v_cvt_f32_f16_e32 v120, v189
	v_cvt_f32_f16_sdwa v121, v189 dst_sel:DWORD dst_unused:UNUSED_PAD src0_sel:WORD_1
	v_lshl_add_u64 v[114:115], v[170:171], 0, s[6:7]
	v_pk_add_f32 v[100:101], v[100:101], v[184:185]
	v_cvt_f32_f16_e32 v122, v190
	v_cvt_f32_f16_sdwa v123, v190 dst_sel:DWORD dst_unused:UNUSED_PAD src0_sel:WORD_1
	v_cvt_f32_f16_e32 v124, v191
	global_load_dwordx4 v[116:119], v[114:115], off offset:256
	v_cvt_f32_f16_sdwa v125, v191 dst_sel:DWORD dst_unused:UNUSED_PAD src0_sel:WORD_1
	v_cvt_pk_f16_f32 v103, v100, v101
	v_cvt_pk_f16_f32 v101, v108, v109
	v_cvt_pk_f16_f32 v100, v110, v111
	v_pk_add_f32 v[84:85], v[84:85], v[128:129]
	v_pk_add_f32 v[82:83], v[82:83], v[126:127]
	global_store_dwordx4 v[168:169], v[100:103], off offset:256
	v_cvt_f32_f16_e32 v136, v198
	v_cvt_f32_f16_sdwa v137, v198 dst_sel:DWORD dst_unused:UNUSED_PAD src0_sel:WORD_1
	v_cvt_f32_f16_e32 v138, v199
	v_cvt_f32_f16_sdwa v139, v199 dst_sel:DWORD dst_unused:UNUSED_PAD src0_sel:WORD_1
	v_cvt_f32_f16_e32 v140, v200
	v_cvt_f32_f16_sdwa v141, v200 dst_sel:DWORD dst_unused:UNUSED_PAD src0_sel:WORD_1
	v_cvt_f32_f16_e32 v168, v201
	v_cvt_f32_f16_sdwa v169, v201 dst_sel:DWORD dst_unused:UNUSED_PAD src0_sel:WORD_1
	v_cvt_pk_f16_f32 v85, v84, v85
	v_cvt_pk_f16_f32 v84, v82, v83
	v_add_u32_e32 v82, 0xa0, v158
	v_pk_add_f32 v[96:97], v[96:97], v[186:187]
	v_pk_add_f32 v[94:95], v[94:95], v[220:221]
	v_pk_add_f32 v[92:93], v[92:93], v[120:121]
	v_pk_add_f32 v[90:91], v[90:91], v[222:223]
	v_ashrrev_i32_e32 v83, 31, v82
	v_cvt_pk_f16_f32 v93, v92, v93
	v_cvt_pk_f16_f32 v92, v90, v91
	v_cvt_pk_f16_f32 v91, v96, v97
	v_cvt_pk_f16_f32 v90, v94, v95
	v_lshlrev_b64 v[82:83], 12, v[82:83]
	global_load_dwordx4 v[100:103], v[98:99], off offset:256
	v_lshl_add_u64 v[82:83], s[64:65], 0, v[82:83]
	global_store_dwordx4 v[162:163], v[90:93], off
	v_cvt_f32_f16_e32 v108, v194
	v_cvt_f32_f16_sdwa v109, v194 dst_sel:DWORD dst_unused:UNUSED_PAD src0_sel:WORD_1
	v_pk_add_f32 v[90:91], v[88:89], v[124:125]
	v_pk_add_f32 v[92:93], v[86:87], v[122:123]
	v_cvt_f32_f16_e32 v110, v195
	v_cvt_f32_f16_sdwa v111, v195 dst_sel:DWORD dst_unused:UNUSED_PAD src0_sel:WORD_1
	v_cvt_f32_f16_e32 v112, v196
	v_cvt_f32_f16_sdwa v113, v196 dst_sel:DWORD dst_unused:UNUSED_PAD src0_sel:WORD_1
	v_cvt_f32_f16_e32 v134, v197
	v_cvt_f32_f16_sdwa v135, v197 dst_sel:DWORD dst_unused:UNUSED_PAD src0_sel:WORD_1
	v_lshl_add_u64 v[94:95], v[82:83], 0, v[160:161]
	v_cvt_pk_f16_f32 v83, v90, v91
	v_cvt_pk_f16_f32 v82, v92, v93
	v_pk_add_f32 v[72:73], v[72:73], v[138:139]
	v_pk_add_f32 v[70:71], v[70:71], v[136:137]
	v_pk_add_f32 v[68:69], v[68:69], v[168:169]
	v_pk_add_f32 v[66:67], v[66:67], v[140:141]
	global_load_dwordx4 v[86:89], v[94:95], off
	v_cvt_pk_f16_f32 v69, v68, v69
	global_store_dwordx4 v[162:163], v[82:85], off offset:256
	global_load_dwordx4 v[82:85], v[94:95], off offset:256
	v_cvt_pk_f16_f32 v68, v66, v67
	v_cvt_pk_f16_f32 v67, v72, v73
	v_cvt_pk_f16_f32 v66, v70, v71
	global_store_dwordx4 v[166:167], v[66:69], off offset:256
	v_pk_add_f32 v[80:81], v[80:81], v[110:111]
	v_pk_add_f32 v[78:79], v[78:79], v[108:109]
	v_add_u32_e32 v66, 0xb0, v158
	v_ashrrev_i32_e32 v67, 31, v66
	v_pk_add_f32 v[76:77], v[76:77], v[134:135]
	v_pk_add_f32 v[74:75], v[74:75], v[112:113]
	v_lshlrev_b64 v[66:67], 12, v[66:67]
	v_cvt_pk_f16_f32 v77, v76, v77
	v_cvt_pk_f16_f32 v76, v74, v75
	v_cvt_pk_f16_f32 v75, v80, v81
	v_cvt_pk_f16_f32 v74, v78, v79
	v_lshl_add_u64 v[66:67], s[64:65], 0, v[66:67]
	global_store_dwordx4 v[166:167], v[74:77], off
	v_cvt_f32_f16_e32 v90, v130
	v_cvt_f32_f16_sdwa v91, v130 dst_sel:DWORD dst_unused:UNUSED_PAD src0_sel:WORD_1
	s_waitcnt vmcnt(9)
	v_cvt_f32_f16_e32 v74, v104
	v_cvt_f32_f16_sdwa v75, v104 dst_sel:DWORD dst_unused:UNUSED_PAD src0_sel:WORD_1
	v_cvt_f32_f16_e32 v76, v105
	v_cvt_f32_f16_sdwa v77, v105 dst_sel:DWORD dst_unused:UNUSED_PAD src0_sel:WORD_1
	v_lshl_add_u64 v[104:105], v[66:67], 0, v[160:161]
	global_load_dwordx4 v[66:69], v[104:105], off
	global_load_dwordx4 v[70:73], v[104:105], off offset:256
	v_cvt_f32_f16_e32 v92, v131
	v_cvt_f32_f16_sdwa v93, v131 dst_sel:DWORD dst_unused:UNUSED_PAD src0_sel:WORD_1
	v_cvt_f32_f16_e32 v96, v132
	v_cvt_f32_f16_sdwa v97, v132 dst_sel:DWORD dst_unused:UNUSED_PAD src0_sel:WORD_1
	v_cvt_f32_f16_e32 v120, v133
	v_cvt_f32_f16_sdwa v121, v133 dst_sel:DWORD dst_unused:UNUSED_PAD src0_sel:WORD_1
	s_waitcnt vmcnt(10)
	v_cvt_f32_f16_e32 v122, v116
	v_cvt_f32_f16_sdwa v123, v116 dst_sel:DWORD dst_unused:UNUSED_PAD src0_sel:WORD_1
	v_cvt_f32_f16_e32 v116, v117
	v_cvt_f32_f16_sdwa v117, v117 dst_sel:DWORD dst_unused:UNUSED_PAD src0_sel:WORD_1
	v_cvt_f32_f16_e32 v124, v118
	v_cvt_f32_f16_sdwa v125, v118 dst_sel:DWORD dst_unused:UNUSED_PAD src0_sel:WORD_1
	v_cvt_f32_f16_e32 v118, v119
	v_cvt_f32_f16_sdwa v119, v119 dst_sel:DWORD dst_unused:UNUSED_PAD src0_sel:WORD_1
	v_cvt_f32_f16_e32 v78, v106
	v_cvt_f32_f16_sdwa v79, v106 dst_sel:DWORD dst_unused:UNUSED_PAD src0_sel:WORD_1
	v_cvt_f32_f16_e32 v80, v107
	v_cvt_f32_f16_sdwa v81, v107 dst_sel:DWORD dst_unused:UNUSED_PAD src0_sel:WORD_1
	v_pk_add_f32 v[64:65], v[64:65], v[92:93]
	v_pk_add_f32 v[62:63], v[62:63], v[90:91]
	v_pk_add_f32 v[60:61], v[60:61], v[120:121]
	v_pk_add_f32 v[58:59], v[58:59], v[96:97]
	v_pk_add_f32 v[56:57], v[56:57], v[116:117]
	v_pk_add_f32 v[54:55], v[54:55], v[122:123]
	v_pk_add_f32 v[48:49], v[48:49], v[118:119]
	v_pk_add_f32 v[46:47], v[46:47], v[124:125]
	v_cvt_pk_f16_f32 v61, v60, v61
	v_cvt_pk_f16_f32 v60, v58, v59
	v_cvt_pk_f16_f32 v59, v64, v65
	v_cvt_pk_f16_f32 v58, v62, v63
	v_cvt_pk_f16_f32 v49, v48, v49
	s_waitcnt vmcnt(8)
	v_cvt_f32_f16_e32 v106, v100
	v_cvt_f32_f16_sdwa v107, v100 dst_sel:DWORD dst_unused:UNUSED_PAD src0_sel:WORD_1
	v_cvt_f32_f16_e32 v100, v101
	v_cvt_f32_f16_sdwa v101, v101 dst_sel:DWORD dst_unused:UNUSED_PAD src0_sel:WORD_1
	v_cvt_f32_f16_e32 v108, v102
	v_cvt_f32_f16_sdwa v109, v102 dst_sel:DWORD dst_unused:UNUSED_PAD src0_sel:WORD_1
	v_cvt_f32_f16_e32 v102, v103
	v_cvt_f32_f16_sdwa v103, v103 dst_sel:DWORD dst_unused:UNUSED_PAD src0_sel:WORD_1
	v_cvt_pk_f16_f32 v48, v46, v47
	v_cvt_pk_f16_f32 v47, v56, v57
	v_cvt_pk_f16_f32 v46, v54, v55
	global_store_dwordx4 v[164:165], v[58:61], off
	global_store_dwordx4 v[114:115], v[46:49], off offset:256
	v_pk_add_f32 v[32:33], v[32:33], v[100:101]
	v_pk_add_f32 v[30:31], v[30:31], v[106:107]
	v_pk_add_f32 v[28:29], v[28:29], v[102:103]
	v_pk_add_f32 v[26:27], v[26:27], v[108:109]
	v_cvt_pk_f16_f32 v29, v28, v29
	v_cvt_pk_f16_f32 v28, v26, v27
	v_cvt_pk_f16_f32 v27, v32, v33
	s_waitcnt vmcnt(8)
	v_cvt_f32_f16_e32 v46, v86
	v_cvt_f32_f16_sdwa v47, v86 dst_sel:DWORD dst_unused:UNUSED_PAD src0_sel:WORD_1
	v_cvt_f32_f16_e32 v48, v87
	v_cvt_f32_f16_sdwa v49, v87 dst_sel:DWORD dst_unused:UNUSED_PAD src0_sel:WORD_1
	v_cvt_f32_f16_e32 v54, v88
	v_cvt_f32_f16_sdwa v55, v88 dst_sel:DWORD dst_unused:UNUSED_PAD src0_sel:WORD_1
	v_cvt_f32_f16_e32 v56, v89
	v_cvt_f32_f16_sdwa v57, v89 dst_sel:DWORD dst_unused:UNUSED_PAD src0_sel:WORD_1
	s_waitcnt vmcnt(6)
	v_cvt_f32_f16_e32 v58, v82
	v_cvt_f32_f16_sdwa v59, v82 dst_sel:DWORD dst_unused:UNUSED_PAD src0_sel:WORD_1
	v_cvt_f32_f16_e32 v60, v83
	v_cvt_f32_f16_sdwa v61, v83 dst_sel:DWORD dst_unused:UNUSED_PAD src0_sel:WORD_1
	v_cvt_f32_f16_e32 v62, v84
	v_cvt_f32_f16_sdwa v63, v84 dst_sel:DWORD dst_unused:UNUSED_PAD src0_sel:WORD_1
	v_cvt_f32_f16_e32 v64, v85
	v_cvt_f32_f16_sdwa v65, v85 dst_sel:DWORD dst_unused:UNUSED_PAD src0_sel:WORD_1
	v_cvt_pk_f16_f32 v26, v30, v31
	global_store_dwordx4 v[98:99], v[26:29], off offset:256
	v_pk_add_f32 v[30:31], v[38:39], v[46:47]
	v_pk_add_f32 v[32:33], v[34:35], v[54:55]
	v_pk_add_f32 v[26:27], v[40:41], v[48:49]
	v_pk_add_f32 v[28:29], v[36:37], v[56:57]
	v_pk_add_f32 v[24:25], v[24:25], v[60:61]
	v_pk_add_f32 v[22:23], v[22:23], v[58:59]
	v_pk_add_f32 v[20:21], v[20:21], v[64:65]
	v_pk_add_f32 v[18:19], v[18:19], v[62:63]
	v_cvt_pk_f16_f32 v29, v28, v29
	v_cvt_pk_f16_f32 v28, v32, v33
	v_cvt_pk_f16_f32 v27, v26, v27
	v_cvt_pk_f16_f32 v26, v30, v31
	v_cvt_pk_f16_f32 v21, v20, v21
	v_cvt_pk_f16_f32 v20, v18, v19
	v_cvt_pk_f16_f32 v19, v24, v25
	v_cvt_pk_f16_f32 v18, v22, v23
	global_store_dwordx4 v[94:95], v[26:29], off
	global_store_dwordx4 v[94:95], v[18:21], off offset:256
	s_waitcnt vmcnt(5)
	v_cvt_f32_f16_e32 v22, v70
	v_cvt_f32_f16_sdwa v23, v70 dst_sel:DWORD dst_unused:UNUSED_PAD src0_sel:WORD_1
	v_cvt_f32_f16_e32 v18, v72
	v_cvt_f32_f16_sdwa v19, v72 dst_sel:DWORD dst_unused:UNUSED_PAD src0_sel:WORD_1
	v_cvt_f32_f16_e32 v20, v73
	v_cvt_f32_f16_sdwa v21, v73 dst_sel:DWORD dst_unused:UNUSED_PAD src0_sel:WORD_1
	v_cvt_f32_f16_e32 v24, v71
	v_cvt_f32_f16_sdwa v25, v71 dst_sel:DWORD dst_unused:UNUSED_PAD src0_sel:WORD_1
	v_cvt_f32_f16_e32 v26, v68
	v_cvt_f32_f16_e32 v28, v69
	v_cvt_f32_f16_e32 v30, v66
	v_cvt_f32_f16_e32 v32, v67
	v_cvt_f32_f16_sdwa v33, v67 dst_sel:DWORD dst_unused:UNUSED_PAD src0_sel:WORD_1
	v_cvt_f32_f16_sdwa v31, v66 dst_sel:DWORD dst_unused:UNUSED_PAD src0_sel:WORD_1
	v_cvt_f32_f16_sdwa v29, v69 dst_sel:DWORD dst_unused:UNUSED_PAD src0_sel:WORD_1
	v_cvt_f32_f16_sdwa v27, v68 dst_sel:DWORD dst_unused:UNUSED_PAD src0_sel:WORD_1
	v_pk_add_f32 v[52:53], v[52:53], v[76:77]
	v_pk_add_f32 v[50:51], v[50:51], v[74:75]
	v_pk_add_f32 v[44:45], v[44:45], v[80:81]
	v_pk_add_f32 v[42:43], v[42:43], v[78:79]
	v_pk_add_f32 v[16:17], v[16:17], v[32:33]
	v_pk_add_f32 v[14:15], v[14:15], v[30:31]
	v_pk_add_f32 v[12:13], v[12:13], v[28:29]
	v_pk_add_f32 v[10:11], v[10:11], v[26:27]
	v_pk_add_f32 v[8:9], v[8:9], v[24:25]
	v_pk_add_f32 v[6:7], v[6:7], v[22:23]
	v_pk_add_f32 v[4:5], v[4:5], v[20:21]
	v_pk_add_f32 v[2:3], v[2:3], v[18:19]
	v_cvt_pk_f16_f32 v45, v44, v45
	v_cvt_pk_f16_f32 v44, v42, v43
	v_cvt_pk_f16_f32 v43, v52, v53
	v_cvt_pk_f16_f32 v42, v50, v51
	v_cvt_pk_f16_f32 v13, v12, v13
	v_cvt_pk_f16_f32 v12, v10, v11
	v_cvt_pk_f16_f32 v11, v16, v17
	v_cvt_pk_f16_f32 v10, v14, v15
	v_cvt_pk_f16_f32 v5, v4, v5
	v_cvt_pk_f16_f32 v4, v2, v3
	v_cvt_pk_f16_f32 v3, v8, v9
	v_cvt_pk_f16_f32 v2, v6, v7
	global_store_dwordx4 v[98:99], v[42:45], off
	global_store_dwordx4 v[104:105], v[10:13], off
	global_store_dwordx4 v[104:105], v[2:5], off offset:256
	s_cbranch_vccnz .LBB0_2930
	s_andn2_b64 vcc, exec, s[8:9]
	s_cbranch_vccnz .LBB0_2929
	s_barrier
	s_branch .LBB0_2929

.LBB0_3183:
	v_lshl_or_b32 v130, s59, 8, v173
	v_lshl_add_u32 v158, s58, 8, v1
	v_ashrrev_i32_e32 v131, 31, v130
	v_lshlrev_b64 v[160:161], 1, v[130:131]
	v_or_b32_e32 v130, 16, v158
	v_ashrrev_i32_e32 v159, 31, v158
	v_ashrrev_i32_e32 v131, 31, v130
	v_lshlrev_b64 v[132:133], 12, v[158:159]
	v_lshlrev_b64 v[130:131], 12, v[130:131]
	v_lshl_add_u64 v[132:133], s[64:65], 0, v[132:133]
	v_lshl_add_u64 v[130:131], s[64:65], 0, v[130:131]
	v_lshl_add_u64 v[170:171], v[132:133], 0, v[160:161]
	v_lshl_add_u64 v[168:169], v[130:131], 0, v[160:161]
	v_mov_b32_e32 v235, 0
	global_load_dwordx4 v[228:231], v[170:171], off
	global_load_dwordx4 v[228:231], v[170:171], off offset:256
	v_mov_b32_e32 v234, 1
	v_lshl_add_u64 v[232:233], v[234:235], 16, v[170:171]
	global_load_dwordx4 v[228:231], v[232:233], off
	global_load_dwordx4 v[228:231], v[232:233], off offset:256
	v_mov_b32_e32 v234, 2
	v_lshl_add_u64 v[232:233], v[234:235], 16, v[170:171]
	global_load_dwordx4 v[228:231], v[232:233], off
	global_load_dwordx4 v[228:231], v[232:233], off offset:256
	v_mov_b32_e32 v234, 3
	v_lshl_add_u64 v[232:233], v[234:235], 16, v[170:171]
	global_load_dwordx4 v[228:231], v[232:233], off
	global_load_dwordx4 v[228:231], v[232:233], off offset:256
	v_mov_b32_e32 v234, 8
	v_lshl_add_u64 v[232:233], v[234:235], 16, v[170:171]
	global_load_dwordx4 v[228:231], v[232:233], off
	global_load_dwordx4 v[228:231], v[232:233], off offset:256
	v_mov_b32_e32 v234, 9
	v_lshl_add_u64 v[232:233], v[234:235], 16, v[170:171]
	global_load_dwordx4 v[228:231], v[232:233], off
	global_load_dwordx4 v[228:231], v[232:233], off offset:256
	v_mov_b32_e32 v234, 10
	v_lshl_add_u64 v[232:233], v[234:235], 16, v[170:171]
	global_load_dwordx4 v[228:231], v[232:233], off
	global_load_dwordx4 v[228:231], v[232:233], off offset:256
	v_mov_b32_e32 v234, 11
	v_lshl_add_u64 v[232:233], v[234:235], 16, v[170:171]
	global_load_dwordx4 v[228:231], v[232:233], off
	global_load_dwordx4 v[228:231], v[232:233], off offset:256
	global_load_dwordx4 v[134:137], v[170:171], off
	global_load_dwordx4 v[138:141], v[170:171], off offset:256
	global_load_dwordx4 v[178:181], v[168:169], off
	global_load_dwordx4 v[182:185], v[168:169], off offset:256
	v_or_b32_e32 v130, 32, v158
	v_ashrrev_i32_e32 v131, 31, v130
	v_lshlrev_b64 v[130:131], 12, v[130:131]
	v_lshl_add_u64 v[130:131], s[64:65], 0, v[130:131]
	v_lshl_add_u64 v[162:163], v[130:131], 0, v[160:161]
	global_load_dwordx4 v[186:189], v[162:163], off
	global_load_dwordx4 v[190:193], v[162:163], off offset:256
	v_or_b32_e32 v130, 48, v158
	v_ashrrev_i32_e32 v131, 31, v130
	v_lshlrev_b64 v[130:131], 12, v[130:131]
	v_lshl_add_u64 v[130:131], s[64:65], 0, v[130:131]
	v_lshl_add_u64 v[166:167], v[130:131], 0, v[160:161]
	v_add_co_u32_e32 v164, vcc, s55, v170
	s_mov_b64 s[0:1], -1
	s_nop 0
	v_addc_co_u32_e32 v165, vcc, 0, v171, vcc
	global_load_dwordx4 v[194:197], v[166:167], off
	global_load_dwordx4 v[198:201], v[166:167], off offset:256
	global_load_dwordx4 v[130:133], v[164:165], off
	s_and_b64 vcc, exec, s[2:3]
	s_waitcnt vmcnt(0)
	v_cvt_f32_f16_e32 v202, v134
	v_cvt_f32_f16_e32 v210, v178
	v_cvt_f32_f16_sdwa v211, v178 dst_sel:DWORD dst_unused:UNUSED_PAD src0_sel:WORD_1
	v_cvt_f32_f16_e32 v212, v180
	v_cvt_f32_f16_sdwa v213, v180 dst_sel:DWORD dst_unused:UNUSED_PAD src0_sel:WORD_1
	v_cvt_f32_f16_e32 v180, v181
	v_cvt_f32_f16_sdwa v181, v181 dst_sel:DWORD dst_unused:UNUSED_PAD src0_sel:WORD_1
	v_cvt_f32_f16_e32 v218, v184
	v_cvt_f32_f16_sdwa v219, v184 dst_sel:DWORD dst_unused:UNUSED_PAD src0_sel:WORD_1
	v_cvt_f32_f16_e32 v214, v182
	v_cvt_f32_f16_sdwa v215, v182 dst_sel:DWORD dst_unused:UNUSED_PAD src0_sel:WORD_1
	v_cvt_f32_f16_sdwa v203, v134 dst_sel:DWORD dst_unused:UNUSED_PAD src0_sel:WORD_1
	v_cvt_f32_f16_e32 v134, v135
	v_cvt_f32_f16_sdwa v135, v135 dst_sel:DWORD dst_unused:UNUSED_PAD src0_sel:WORD_1
	v_cvt_f32_f16_e32 v204, v136
	v_cvt_f32_f16_sdwa v205, v136 dst_sel:DWORD dst_unused:UNUSED_PAD src0_sel:WORD_1
	v_cvt_f32_f16_e32 v136, v137
	v_cvt_f32_f16_sdwa v137, v137 dst_sel:DWORD dst_unused:UNUSED_PAD src0_sel:WORD_1
	v_cvt_f32_f16_e32 v206, v138
	v_cvt_f32_f16_sdwa v207, v138 dst_sel:DWORD dst_unused:UNUSED_PAD src0_sel:WORD_1
	v_cvt_f32_f16_e32 v138, v139
	v_cvt_f32_f16_sdwa v139, v139 dst_sel:DWORD dst_unused:UNUSED_PAD src0_sel:WORD_1
	v_cvt_f32_f16_e32 v208, v140
	v_cvt_f32_f16_sdwa v209, v140 dst_sel:DWORD dst_unused:UNUSED_PAD src0_sel:WORD_1
	v_cvt_f32_f16_e32 v140, v141
	v_cvt_f32_f16_sdwa v141, v141 dst_sel:DWORD dst_unused:UNUSED_PAD src0_sel:WORD_1
	v_cvt_f32_f16_e32 v178, v179
	v_cvt_f32_f16_sdwa v179, v179 dst_sel:DWORD dst_unused:UNUSED_PAD src0_sel:WORD_1
	v_pk_fma_f32 v[110:111], v[110:111], 0.5, v[210:211] op_sel_hi:[1,0,1]
	v_pk_fma_f32 v[108:109], v[108:109], 0.5, v[180:181] op_sel_hi:[1,0,1]
	v_pk_fma_f32 v[106:107], v[106:107], 0.5, v[212:213] op_sel_hi:[1,0,1]
	v_pk_fma_f32 v[98:99], v[98:99], 0.5, v[218:219] op_sel_hi:[1,0,1]
	v_cvt_pk_f16_f32 v109, v108, v109
	v_cvt_pk_f16_f32 v108, v106, v107
	v_cvt_pk_f16_f32 v106, v110, v111
	v_pk_fma_f32 v[110:111], v[102:103], 0.5, v[214:215] op_sel_hi:[1,0,1]
	v_cvt_pk_f16_f32 v102, v98, v99
	v_add_u32_e32 v98, 0x90, v158
	v_cvt_f32_f16_e32 v182, v183
	v_cvt_f32_f16_sdwa v183, v183 dst_sel:DWORD dst_unused:UNUSED_PAD src0_sel:WORD_1
	v_ashrrev_i32_e32 v99, 31, v98
	v_pk_fma_f32 v[128:129], v[128:129], 0.5, v[134:135] op_sel_hi:[1,0,1]
	v_pk_fma_f32 v[126:127], v[126:127], 0.5, v[202:203] op_sel_hi:[1,0,1]
	v_pk_fma_f32 v[124:125], v[124:125], 0.5, v[136:137] op_sel_hi:[1,0,1]
	v_pk_fma_f32 v[122:123], v[122:123], 0.5, v[204:205] op_sel_hi:[1,0,1]
	v_lshlrev_b64 v[98:99], 12, v[98:99]
	v_pk_fma_f32 v[134:135], v[120:121], 0.5, v[138:139] op_sel_hi:[1,0,1]
	v_pk_fma_f32 v[136:137], v[118:119], 0.5, v[206:207] op_sel_hi:[1,0,1]
	v_pk_fma_f32 v[118:119], v[116:117], 0.5, v[140:141] op_sel_hi:[1,0,1]
	v_pk_fma_f32 v[138:139], v[114:115], 0.5, v[208:209] op_sel_hi:[1,0,1]
	v_cvt_pk_f16_f32 v117, v124, v125
	v_cvt_pk_f16_f32 v116, v122, v123
	v_cvt_pk_f16_f32 v115, v128, v129
	v_cvt_pk_f16_f32 v114, v126, v127
	v_pk_fma_f32 v[112:113], v[112:113], 0.5, v[178:179] op_sel_hi:[1,0,1]
	v_lshl_add_u64 v[98:99], s[64:65], 0, v[98:99]
	v_cvt_pk_f16_f32 v121, v118, v119
	v_cvt_pk_f16_f32 v120, v138, v139
	v_cvt_pk_f16_f32 v119, v134, v135
	v_cvt_pk_f16_f32 v118, v136, v137
	global_store_dwordx4 v[170:171], v[114:117], off
	global_store_dwordx4 v[170:171], v[118:121], off offset:256
	v_cvt_pk_f16_f32 v107, v112, v113
	v_lshl_add_u64 v[98:99], v[98:99], 0, v[160:161]
	global_store_dwordx4 v[168:169], v[106:109], off
	v_cvt_f32_f16_e32 v184, v185
	v_cvt_f32_f16_sdwa v185, v185 dst_sel:DWORD dst_unused:UNUSED_PAD src0_sel:WORD_1
	v_pk_fma_f32 v[108:109], v[104:105], 0.5, v[182:183] op_sel_hi:[1,0,1]
	global_load_dwordx4 v[104:107], v[98:99], off
	v_cvt_f32_f16_e32 v126, v192
	v_cvt_f32_f16_sdwa v127, v192 dst_sel:DWORD dst_unused:UNUSED_PAD src0_sel:WORD_1
	v_cvt_f32_f16_e32 v128, v193
	v_cvt_f32_f16_sdwa v129, v193 dst_sel:DWORD dst_unused:UNUSED_PAD src0_sel:WORD_1
	v_cvt_f32_f16_e32 v220, v186
	v_cvt_f32_f16_sdwa v221, v186 dst_sel:DWORD dst_unused:UNUSED_PAD src0_sel:WORD_1
	v_cvt_f32_f16_e32 v186, v187
	v_cvt_f32_f16_sdwa v187, v187 dst_sel:DWORD dst_unused:UNUSED_PAD src0_sel:WORD_1
	v_cvt_f32_f16_e32 v222, v188
	v_cvt_f32_f16_sdwa v223, v188 dst_sel:DWORD dst_unused:UNUSED_PAD src0_sel:WORD_1
	v_cvt_f32_f16_e32 v120, v189
	v_cvt_f32_f16_sdwa v121, v189 dst_sel:DWORD dst_unused:UNUSED_PAD src0_sel:WORD_1
	v_lshl_add_u64 v[114:115], v[170:171], 0, s[36:37]
	v_pk_fma_f32 v[100:101], v[100:101], 0.5, v[184:185] op_sel_hi:[1,0,1]
	v_cvt_f32_f16_e32 v122, v190
	v_cvt_f32_f16_sdwa v123, v190 dst_sel:DWORD dst_unused:UNUSED_PAD src0_sel:WORD_1
	v_cvt_f32_f16_e32 v124, v191
	global_load_dwordx4 v[116:119], v[114:115], off offset:256
	v_cvt_f32_f16_sdwa v125, v191 dst_sel:DWORD dst_unused:UNUSED_PAD src0_sel:WORD_1
	v_cvt_pk_f16_f32 v103, v100, v101
	v_cvt_pk_f16_f32 v101, v108, v109
	v_cvt_pk_f16_f32 v100, v110, v111
	v_pk_fma_f32 v[84:85], v[84:85], 0.5, v[128:129] op_sel_hi:[1,0,1]
	v_pk_fma_f32 v[82:83], v[82:83], 0.5, v[126:127] op_sel_hi:[1,0,1]
	global_store_dwordx4 v[168:169], v[100:103], off offset:256
	v_cvt_f32_f16_e32 v136, v198
	v_cvt_f32_f16_sdwa v137, v198 dst_sel:DWORD dst_unused:UNUSED_PAD src0_sel:WORD_1
	v_cvt_f32_f16_e32 v138, v199
	v_cvt_f32_f16_sdwa v139, v199 dst_sel:DWORD dst_unused:UNUSED_PAD src0_sel:WORD_1
	v_cvt_f32_f16_e32 v140, v200
	v_cvt_f32_f16_sdwa v141, v200 dst_sel:DWORD dst_unused:UNUSED_PAD src0_sel:WORD_1
	v_cvt_f32_f16_e32 v168, v201
	v_cvt_f32_f16_sdwa v169, v201 dst_sel:DWORD dst_unused:UNUSED_PAD src0_sel:WORD_1
	v_cvt_pk_f16_f32 v85, v84, v85
	v_cvt_pk_f16_f32 v84, v82, v83
	v_add_u32_e32 v82, 0xa0, v158
	v_pk_fma_f32 v[96:97], v[96:97], 0.5, v[186:187] op_sel_hi:[1,0,1]
	v_pk_fma_f32 v[94:95], v[94:95], 0.5, v[220:221] op_sel_hi:[1,0,1]
	v_pk_fma_f32 v[92:93], v[92:93], 0.5, v[120:121] op_sel_hi:[1,0,1]
	v_pk_fma_f32 v[90:91], v[90:91], 0.5, v[222:223] op_sel_hi:[1,0,1]
	v_ashrrev_i32_e32 v83, 31, v82
	v_cvt_pk_f16_f32 v93, v92, v93
	v_cvt_pk_f16_f32 v92, v90, v91
	v_cvt_pk_f16_f32 v91, v96, v97
	v_cvt_pk_f16_f32 v90, v94, v95
	v_lshlrev_b64 v[82:83], 12, v[82:83]
	global_load_dwordx4 v[100:103], v[98:99], off offset:256
	v_lshl_add_u64 v[82:83], s[64:65], 0, v[82:83]
	global_store_dwordx4 v[162:163], v[90:93], off
	v_cvt_f32_f16_e32 v108, v194
	v_cvt_f32_f16_sdwa v109, v194 dst_sel:DWORD dst_unused:UNUSED_PAD src0_sel:WORD_1
	v_pk_fma_f32 v[90:91], v[88:89], 0.5, v[124:125] op_sel_hi:[1,0,1]
	v_pk_fma_f32 v[92:93], v[86:87], 0.5, v[122:123] op_sel_hi:[1,0,1]
	v_cvt_f32_f16_e32 v110, v195
	v_cvt_f32_f16_sdwa v111, v195 dst_sel:DWORD dst_unused:UNUSED_PAD src0_sel:WORD_1
	v_cvt_f32_f16_e32 v112, v196
	v_cvt_f32_f16_sdwa v113, v196 dst_sel:DWORD dst_unused:UNUSED_PAD src0_sel:WORD_1
	v_cvt_f32_f16_e32 v134, v197
	v_cvt_f32_f16_sdwa v135, v197 dst_sel:DWORD dst_unused:UNUSED_PAD src0_sel:WORD_1
	v_lshl_add_u64 v[94:95], v[82:83], 0, v[160:161]
	v_cvt_pk_f16_f32 v83, v90, v91
	v_cvt_pk_f16_f32 v82, v92, v93
	v_pk_fma_f32 v[72:73], v[72:73], 0.5, v[138:139] op_sel_hi:[1,0,1]
	v_pk_fma_f32 v[70:71], v[70:71], 0.5, v[136:137] op_sel_hi:[1,0,1]
	v_pk_fma_f32 v[68:69], v[68:69], 0.5, v[168:169] op_sel_hi:[1,0,1]
	v_pk_fma_f32 v[66:67], v[66:67], 0.5, v[140:141] op_sel_hi:[1,0,1]
	global_load_dwordx4 v[86:89], v[94:95], off
	v_cvt_pk_f16_f32 v69, v68, v69
	global_store_dwordx4 v[162:163], v[82:85], off offset:256
	global_load_dwordx4 v[82:85], v[94:95], off offset:256
	v_cvt_pk_f16_f32 v68, v66, v67
	v_cvt_pk_f16_f32 v67, v72, v73
	v_cvt_pk_f16_f32 v66, v70, v71
	global_store_dwordx4 v[166:167], v[66:69], off offset:256
	v_pk_fma_f32 v[80:81], v[80:81], 0.5, v[110:111] op_sel_hi:[1,0,1]
	v_pk_fma_f32 v[78:79], v[78:79], 0.5, v[108:109] op_sel_hi:[1,0,1]
	v_add_u32_e32 v66, 0xb0, v158
	v_ashrrev_i32_e32 v67, 31, v66
	v_pk_fma_f32 v[76:77], v[76:77], 0.5, v[134:135] op_sel_hi:[1,0,1]
	v_pk_fma_f32 v[74:75], v[74:75], 0.5, v[112:113] op_sel_hi:[1,0,1]
	v_lshlrev_b64 v[66:67], 12, v[66:67]
	v_cvt_pk_f16_f32 v77, v76, v77
	v_cvt_pk_f16_f32 v76, v74, v75
	v_cvt_pk_f16_f32 v75, v80, v81
	v_cvt_pk_f16_f32 v74, v78, v79
	v_lshl_add_u64 v[66:67], s[64:65], 0, v[66:67]
	global_store_dwordx4 v[166:167], v[74:77], off
	v_cvt_f32_f16_e32 v90, v130
	v_cvt_f32_f16_sdwa v91, v130 dst_sel:DWORD dst_unused:UNUSED_PAD src0_sel:WORD_1
	s_waitcnt vmcnt(9)
	v_cvt_f32_f16_e32 v74, v104
	v_cvt_f32_f16_sdwa v75, v104 dst_sel:DWORD dst_unused:UNUSED_PAD src0_sel:WORD_1
	v_cvt_f32_f16_e32 v76, v105
	v_cvt_f32_f16_sdwa v77, v105 dst_sel:DWORD dst_unused:UNUSED_PAD src0_sel:WORD_1
	v_lshl_add_u64 v[104:105], v[66:67], 0, v[160:161]
	global_load_dwordx4 v[66:69], v[104:105], off
	global_load_dwordx4 v[70:73], v[104:105], off offset:256
	v_cvt_f32_f16_e32 v92, v131
	v_cvt_f32_f16_sdwa v93, v131 dst_sel:DWORD dst_unused:UNUSED_PAD src0_sel:WORD_1
	v_cvt_f32_f16_e32 v96, v132
	v_cvt_f32_f16_sdwa v97, v132 dst_sel:DWORD dst_unused:UNUSED_PAD src0_sel:WORD_1
	v_cvt_f32_f16_e32 v120, v133
	v_cvt_f32_f16_sdwa v121, v133 dst_sel:DWORD dst_unused:UNUSED_PAD src0_sel:WORD_1
	s_waitcnt vmcnt(10)
	v_cvt_f32_f16_e32 v122, v116
	v_cvt_f32_f16_sdwa v123, v116 dst_sel:DWORD dst_unused:UNUSED_PAD src0_sel:WORD_1
	v_cvt_f32_f16_e32 v116, v117
	v_cvt_f32_f16_sdwa v117, v117 dst_sel:DWORD dst_unused:UNUSED_PAD src0_sel:WORD_1
	v_cvt_f32_f16_e32 v124, v118
	v_cvt_f32_f16_sdwa v125, v118 dst_sel:DWORD dst_unused:UNUSED_PAD src0_sel:WORD_1
	v_cvt_f32_f16_e32 v118, v119
	v_cvt_f32_f16_sdwa v119, v119 dst_sel:DWORD dst_unused:UNUSED_PAD src0_sel:WORD_1
	v_cvt_f32_f16_e32 v78, v106
	v_cvt_f32_f16_sdwa v79, v106 dst_sel:DWORD dst_unused:UNUSED_PAD src0_sel:WORD_1
	v_cvt_f32_f16_e32 v80, v107
	v_cvt_f32_f16_sdwa v81, v107 dst_sel:DWORD dst_unused:UNUSED_PAD src0_sel:WORD_1
	v_pk_fma_f32 v[64:65], v[64:65], 0.5, v[92:93] op_sel_hi:[1,0,1]
	v_pk_fma_f32 v[62:63], v[62:63], 0.5, v[90:91] op_sel_hi:[1,0,1]
	v_pk_fma_f32 v[60:61], v[60:61], 0.5, v[120:121] op_sel_hi:[1,0,1]
	v_pk_fma_f32 v[58:59], v[58:59], 0.5, v[96:97] op_sel_hi:[1,0,1]
	v_pk_fma_f32 v[56:57], v[56:57], 0.5, v[116:117] op_sel_hi:[1,0,1]
	v_pk_fma_f32 v[54:55], v[54:55], 0.5, v[122:123] op_sel_hi:[1,0,1]
	v_pk_fma_f32 v[48:49], v[48:49], 0.5, v[118:119] op_sel_hi:[1,0,1]
	v_pk_fma_f32 v[46:47], v[46:47], 0.5, v[124:125] op_sel_hi:[1,0,1]
	v_cvt_pk_f16_f32 v61, v60, v61
	v_cvt_pk_f16_f32 v60, v58, v59
	v_cvt_pk_f16_f32 v59, v64, v65
	v_cvt_pk_f16_f32 v58, v62, v63
	v_cvt_pk_f16_f32 v49, v48, v49
	s_waitcnt vmcnt(8)
	v_cvt_f32_f16_e32 v106, v100
	v_cvt_f32_f16_sdwa v107, v100 dst_sel:DWORD dst_unused:UNUSED_PAD src0_sel:WORD_1
	v_cvt_f32_f16_e32 v100, v101
	v_cvt_f32_f16_sdwa v101, v101 dst_sel:DWORD dst_unused:UNUSED_PAD src0_sel:WORD_1
	v_cvt_f32_f16_e32 v108, v102
	v_cvt_f32_f16_sdwa v109, v102 dst_sel:DWORD dst_unused:UNUSED_PAD src0_sel:WORD_1
	v_cvt_f32_f16_e32 v102, v103
	v_cvt_f32_f16_sdwa v103, v103 dst_sel:DWORD dst_unused:UNUSED_PAD src0_sel:WORD_1
	v_cvt_pk_f16_f32 v48, v46, v47
	v_cvt_pk_f16_f32 v47, v56, v57
	v_cvt_pk_f16_f32 v46, v54, v55
	global_store_dwordx4 v[164:165], v[58:61], off
	global_store_dwordx4 v[114:115], v[46:49], off offset:256
	v_pk_fma_f32 v[32:33], v[32:33], 0.5, v[100:101] op_sel_hi:[1,0,1]
	v_pk_fma_f32 v[30:31], v[30:31], 0.5, v[106:107] op_sel_hi:[1,0,1]
	v_pk_fma_f32 v[28:29], v[28:29], 0.5, v[102:103] op_sel_hi:[1,0,1]
	v_pk_fma_f32 v[26:27], v[26:27], 0.5, v[108:109] op_sel_hi:[1,0,1]
	v_cvt_pk_f16_f32 v29, v28, v29
	v_cvt_pk_f16_f32 v28, v26, v27
	v_cvt_pk_f16_f32 v27, v32, v33
	s_waitcnt vmcnt(8)
	v_cvt_f32_f16_e32 v46, v86
	v_cvt_f32_f16_sdwa v47, v86 dst_sel:DWORD dst_unused:UNUSED_PAD src0_sel:WORD_1
	v_cvt_f32_f16_e32 v48, v87
	v_cvt_f32_f16_sdwa v49, v87 dst_sel:DWORD dst_unused:UNUSED_PAD src0_sel:WORD_1
	v_cvt_f32_f16_e32 v54, v88
	v_cvt_f32_f16_sdwa v55, v88 dst_sel:DWORD dst_unused:UNUSED_PAD src0_sel:WORD_1
	v_cvt_f32_f16_e32 v56, v89
	v_cvt_f32_f16_sdwa v57, v89 dst_sel:DWORD dst_unused:UNUSED_PAD src0_sel:WORD_1
	s_waitcnt vmcnt(6)
	v_cvt_f32_f16_e32 v58, v82
	v_cvt_f32_f16_sdwa v59, v82 dst_sel:DWORD dst_unused:UNUSED_PAD src0_sel:WORD_1
	v_cvt_f32_f16_e32 v60, v83
	v_cvt_f32_f16_sdwa v61, v83 dst_sel:DWORD dst_unused:UNUSED_PAD src0_sel:WORD_1
	v_cvt_f32_f16_e32 v62, v84
	v_cvt_f32_f16_sdwa v63, v84 dst_sel:DWORD dst_unused:UNUSED_PAD src0_sel:WORD_1
	v_cvt_f32_f16_e32 v64, v85
	v_cvt_f32_f16_sdwa v65, v85 dst_sel:DWORD dst_unused:UNUSED_PAD src0_sel:WORD_1
	v_cvt_pk_f16_f32 v26, v30, v31
	global_store_dwordx4 v[98:99], v[26:29], off offset:256
	v_pk_fma_f32 v[30:31], v[38:39], 0.5, v[46:47] op_sel_hi:[1,0,1]
	v_pk_fma_f32 v[32:33], v[34:35], 0.5, v[54:55] op_sel_hi:[1,0,1]
	v_pk_fma_f32 v[26:27], v[40:41], 0.5, v[48:49] op_sel_hi:[1,0,1]
	v_pk_fma_f32 v[28:29], v[36:37], 0.5, v[56:57] op_sel_hi:[1,0,1]
	v_pk_fma_f32 v[24:25], v[24:25], 0.5, v[60:61] op_sel_hi:[1,0,1]
	v_pk_fma_f32 v[22:23], v[22:23], 0.5, v[58:59] op_sel_hi:[1,0,1]
	v_pk_fma_f32 v[20:21], v[20:21], 0.5, v[64:65] op_sel_hi:[1,0,1]
	v_pk_fma_f32 v[18:19], v[18:19], 0.5, v[62:63] op_sel_hi:[1,0,1]
	v_cvt_pk_f16_f32 v29, v28, v29
	v_cvt_pk_f16_f32 v28, v32, v33
	v_cvt_pk_f16_f32 v27, v26, v27
	v_cvt_pk_f16_f32 v26, v30, v31
	v_cvt_pk_f16_f32 v21, v20, v21
	v_cvt_pk_f16_f32 v20, v18, v19
	v_cvt_pk_f16_f32 v19, v24, v25
	v_cvt_pk_f16_f32 v18, v22, v23
	global_store_dwordx4 v[94:95], v[26:29], off
	global_store_dwordx4 v[94:95], v[18:21], off offset:256
	s_waitcnt vmcnt(5)
	v_cvt_f32_f16_e32 v22, v70
	v_cvt_f32_f16_sdwa v23, v70 dst_sel:DWORD dst_unused:UNUSED_PAD src0_sel:WORD_1
	v_cvt_f32_f16_e32 v18, v72
	v_cvt_f32_f16_sdwa v19, v72 dst_sel:DWORD dst_unused:UNUSED_PAD src0_sel:WORD_1
	v_cvt_f32_f16_e32 v20, v73
	v_cvt_f32_f16_sdwa v21, v73 dst_sel:DWORD dst_unused:UNUSED_PAD src0_sel:WORD_1
	v_cvt_f32_f16_e32 v24, v71
	v_cvt_f32_f16_sdwa v25, v71 dst_sel:DWORD dst_unused:UNUSED_PAD src0_sel:WORD_1
	v_cvt_f32_f16_e32 v26, v68
	v_cvt_f32_f16_e32 v28, v69
	v_cvt_f32_f16_e32 v30, v66
	v_cvt_f32_f16_e32 v32, v67
	v_cvt_f32_f16_sdwa v33, v67 dst_sel:DWORD dst_unused:UNUSED_PAD src0_sel:WORD_1
	v_cvt_f32_f16_sdwa v31, v66 dst_sel:DWORD dst_unused:UNUSED_PAD src0_sel:WORD_1
	v_cvt_f32_f16_sdwa v29, v69 dst_sel:DWORD dst_unused:UNUSED_PAD src0_sel:WORD_1
	v_cvt_f32_f16_sdwa v27, v68 dst_sel:DWORD dst_unused:UNUSED_PAD src0_sel:WORD_1
	v_pk_fma_f32 v[52:53], v[52:53], 0.5, v[76:77] op_sel_hi:[1,0,1]
	v_pk_fma_f32 v[50:51], v[50:51], 0.5, v[74:75] op_sel_hi:[1,0,1]
	v_pk_fma_f32 v[44:45], v[44:45], 0.5, v[80:81] op_sel_hi:[1,0,1]
	v_pk_fma_f32 v[42:43], v[42:43], 0.5, v[78:79] op_sel_hi:[1,0,1]
	v_pk_fma_f32 v[16:17], v[16:17], 0.5, v[32:33] op_sel_hi:[1,0,1]
	v_pk_fma_f32 v[14:15], v[14:15], 0.5, v[30:31] op_sel_hi:[1,0,1]
	v_pk_fma_f32 v[12:13], v[12:13], 0.5, v[28:29] op_sel_hi:[1,0,1]
	v_pk_fma_f32 v[10:11], v[10:11], 0.5, v[26:27] op_sel_hi:[1,0,1]
	v_pk_fma_f32 v[8:9], v[8:9], 0.5, v[24:25] op_sel_hi:[1,0,1]
	v_pk_fma_f32 v[6:7], v[6:7], 0.5, v[22:23] op_sel_hi:[1,0,1]
	v_pk_fma_f32 v[4:5], v[4:5], 0.5, v[20:21] op_sel_hi:[1,0,1]
	v_pk_fma_f32 v[2:3], v[2:3], 0.5, v[18:19] op_sel_hi:[1,0,1]
	v_cvt_pk_f16_f32 v45, v44, v45
	v_cvt_pk_f16_f32 v44, v42, v43
	v_cvt_pk_f16_f32 v43, v52, v53
	v_cvt_pk_f16_f32 v42, v50, v51
	v_cvt_pk_f16_f32 v13, v12, v13
	v_cvt_pk_f16_f32 v12, v10, v11
	v_cvt_pk_f16_f32 v11, v16, v17
	v_cvt_pk_f16_f32 v10, v14, v15
	v_cvt_pk_f16_f32 v5, v4, v5
	v_cvt_pk_f16_f32 v4, v2, v3
	v_cvt_pk_f16_f32 v3, v8, v9
	v_cvt_pk_f16_f32 v2, v6, v7
	global_store_dwordx4 v[98:99], v[42:45], off
	global_store_dwordx4 v[104:105], v[10:13], off
	global_store_dwordx4 v[104:105], v[2:5], off offset:256
	s_cbranch_vccnz .LBB0_3168
	s_andn2_b64 vcc, exec, s[8:9]
	s_cbranch_vccnz .LBB0_3167
	s_barrier
	s_branch .LBB0_3167

.LBB0_3709:
	v_lshl_or_b32 v130, s57, 8, v173
	v_lshl_add_u32 v158, s40, 8, v1
	v_ashrrev_i32_e32 v131, 31, v130
	v_lshlrev_b64 v[160:161], 1, v[130:131]
	v_or_b32_e32 v130, 16, v158
	v_ashrrev_i32_e32 v159, 31, v158
	v_ashrrev_i32_e32 v131, 31, v130
	v_lshlrev_b64 v[132:133], 12, v[158:159]
	v_lshlrev_b64 v[130:131], 12, v[130:131]
	v_lshl_add_u64 v[132:133], s[64:65], 0, v[132:133]
	v_lshl_add_u64 v[130:131], s[64:65], 0, v[130:131]
	v_lshl_add_u64 v[170:171], v[132:133], 0, v[160:161]
	v_lshl_add_u64 v[168:169], v[130:131], 0, v[160:161]
	v_mov_b32_e32 v235, 0
	global_load_dwordx4 v[228:231], v[170:171], off
	global_load_dwordx4 v[228:231], v[170:171], off offset:256
	v_mov_b32_e32 v234, 1
	v_lshl_add_u64 v[232:233], v[234:235], 16, v[170:171]
	global_load_dwordx4 v[228:231], v[232:233], off
	global_load_dwordx4 v[228:231], v[232:233], off offset:256
	v_mov_b32_e32 v234, 2
	v_lshl_add_u64 v[232:233], v[234:235], 16, v[170:171]
	global_load_dwordx4 v[228:231], v[232:233], off
	global_load_dwordx4 v[228:231], v[232:233], off offset:256
	v_mov_b32_e32 v234, 3
	v_lshl_add_u64 v[232:233], v[234:235], 16, v[170:171]
	global_load_dwordx4 v[228:231], v[232:233], off
	global_load_dwordx4 v[228:231], v[232:233], off offset:256
	v_mov_b32_e32 v234, 8
	v_lshl_add_u64 v[232:233], v[234:235], 16, v[170:171]
	global_load_dwordx4 v[228:231], v[232:233], off
	global_load_dwordx4 v[228:231], v[232:233], off offset:256
	v_mov_b32_e32 v234, 9
	v_lshl_add_u64 v[232:233], v[234:235], 16, v[170:171]
	global_load_dwordx4 v[228:231], v[232:233], off
	global_load_dwordx4 v[228:231], v[232:233], off offset:256
	v_mov_b32_e32 v234, 10
	v_lshl_add_u64 v[232:233], v[234:235], 16, v[170:171]
	global_load_dwordx4 v[228:231], v[232:233], off
	global_load_dwordx4 v[228:231], v[232:233], off offset:256
	v_mov_b32_e32 v234, 11
	v_lshl_add_u64 v[232:233], v[234:235], 16, v[170:171]
	global_load_dwordx4 v[228:231], v[232:233], off
	global_load_dwordx4 v[228:231], v[232:233], off offset:256
	global_load_dwordx4 v[134:137], v[170:171], off
	global_load_dwordx4 v[138:141], v[170:171], off offset:256
	global_load_dwordx4 v[178:181], v[168:169], off
	global_load_dwordx4 v[182:185], v[168:169], off offset:256
	v_or_b32_e32 v130, 32, v158
	v_ashrrev_i32_e32 v131, 31, v130
	v_lshlrev_b64 v[130:131], 12, v[130:131]
	v_lshl_add_u64 v[130:131], s[64:65], 0, v[130:131]
	v_lshl_add_u64 v[162:163], v[130:131], 0, v[160:161]
	global_load_dwordx4 v[186:189], v[162:163], off
	global_load_dwordx4 v[190:193], v[162:163], off offset:256
	v_or_b32_e32 v130, 48, v158
	v_ashrrev_i32_e32 v131, 31, v130
	v_lshlrev_b64 v[130:131], 12, v[130:131]
	v_lshl_add_u64 v[130:131], s[64:65], 0, v[130:131]
	v_lshl_add_u64 v[166:167], v[130:131], 0, v[160:161]
	v_add_co_u32_e32 v164, vcc, s56, v170
	s_mov_b64 s[0:1], -1
	s_nop 0
	v_addc_co_u32_e32 v165, vcc, 0, v171, vcc
	global_load_dwordx4 v[194:197], v[166:167], off
	global_load_dwordx4 v[198:201], v[166:167], off offset:256
	global_load_dwordx4 v[130:133], v[164:165], off
	s_andn2_b64 vcc, exec, s[2:3]
	s_waitcnt vmcnt(0)
	v_cvt_f32_f16_e32 v202, v134
	v_cvt_f32_f16_e32 v210, v178
	v_cvt_f32_f16_sdwa v211, v178 dst_sel:DWORD dst_unused:UNUSED_PAD src0_sel:WORD_1
	v_cvt_f32_f16_e32 v212, v180
	v_cvt_f32_f16_sdwa v213, v180 dst_sel:DWORD dst_unused:UNUSED_PAD src0_sel:WORD_1
	v_cvt_f32_f16_e32 v180, v181
	v_cvt_f32_f16_sdwa v181, v181 dst_sel:DWORD dst_unused:UNUSED_PAD src0_sel:WORD_1
	v_cvt_f32_f16_e32 v218, v184
	v_cvt_f32_f16_sdwa v219, v184 dst_sel:DWORD dst_unused:UNUSED_PAD src0_sel:WORD_1
	v_cvt_f32_f16_e32 v214, v182
	v_cvt_f32_f16_sdwa v215, v182 dst_sel:DWORD dst_unused:UNUSED_PAD src0_sel:WORD_1
	v_cvt_f32_f16_sdwa v203, v134 dst_sel:DWORD dst_unused:UNUSED_PAD src0_sel:WORD_1
	v_cvt_f32_f16_e32 v134, v135
	v_cvt_f32_f16_sdwa v135, v135 dst_sel:DWORD dst_unused:UNUSED_PAD src0_sel:WORD_1
	v_cvt_f32_f16_e32 v204, v136
	v_cvt_f32_f16_sdwa v205, v136 dst_sel:DWORD dst_unused:UNUSED_PAD src0_sel:WORD_1
	v_cvt_f32_f16_e32 v136, v137
	v_cvt_f32_f16_sdwa v137, v137 dst_sel:DWORD dst_unused:UNUSED_PAD src0_sel:WORD_1
	v_cvt_f32_f16_e32 v206, v138
	v_cvt_f32_f16_sdwa v207, v138 dst_sel:DWORD dst_unused:UNUSED_PAD src0_sel:WORD_1
	v_cvt_f32_f16_e32 v138, v139
	v_cvt_f32_f16_sdwa v139, v139 dst_sel:DWORD dst_unused:UNUSED_PAD src0_sel:WORD_1
	v_cvt_f32_f16_e32 v208, v140
	v_cvt_f32_f16_sdwa v209, v140 dst_sel:DWORD dst_unused:UNUSED_PAD src0_sel:WORD_1
	v_cvt_f32_f16_e32 v140, v141
	v_cvt_f32_f16_sdwa v141, v141 dst_sel:DWORD dst_unused:UNUSED_PAD src0_sel:WORD_1
	v_cvt_f32_f16_e32 v178, v179
	v_cvt_f32_f16_sdwa v179, v179 dst_sel:DWORD dst_unused:UNUSED_PAD src0_sel:WORD_1
	v_pk_add_f32 v[110:111], v[110:111], v[210:211]
	v_pk_add_f32 v[108:109], v[108:109], v[180:181]
	v_pk_add_f32 v[106:107], v[106:107], v[212:213]
	v_pk_add_f32 v[98:99], v[98:99], v[218:219]
	v_cvt_pk_f16_f32 v109, v108, v109
	v_cvt_pk_f16_f32 v108, v106, v107
	v_cvt_pk_f16_f32 v106, v110, v111
	v_pk_add_f32 v[110:111], v[102:103], v[214:215]
	v_cvt_pk_f16_f32 v102, v98, v99
	v_add_u32_e32 v98, 0x90, v158
	v_cvt_f32_f16_e32 v182, v183
	v_cvt_f32_f16_sdwa v183, v183 dst_sel:DWORD dst_unused:UNUSED_PAD src0_sel:WORD_1
	v_ashrrev_i32_e32 v99, 31, v98
	v_pk_add_f32 v[128:129], v[128:129], v[134:135]
	v_pk_add_f32 v[126:127], v[126:127], v[202:203]
	v_pk_add_f32 v[124:125], v[124:125], v[136:137]
	v_pk_add_f32 v[122:123], v[122:123], v[204:205]
	v_lshlrev_b64 v[98:99], 12, v[98:99]
	v_pk_add_f32 v[134:135], v[120:121], v[138:139]
	v_pk_add_f32 v[136:137], v[118:119], v[206:207]
	v_pk_add_f32 v[118:119], v[116:117], v[140:141]
	v_pk_add_f32 v[138:139], v[114:115], v[208:209]
	v_cvt_pk_f16_f32 v117, v124, v125
	v_cvt_pk_f16_f32 v116, v122, v123
	v_cvt_pk_f16_f32 v115, v128, v129
	v_cvt_pk_f16_f32 v114, v126, v127
	v_pk_add_f32 v[112:113], v[112:113], v[178:179]
	v_lshl_add_u64 v[98:99], s[64:65], 0, v[98:99]
	v_cvt_pk_f16_f32 v121, v118, v119
	v_cvt_pk_f16_f32 v120, v138, v139
	v_cvt_pk_f16_f32 v119, v134, v135
	v_cvt_pk_f16_f32 v118, v136, v137
	global_store_dwordx4 v[170:171], v[114:117], off
	global_store_dwordx4 v[170:171], v[118:121], off offset:256
	v_cvt_pk_f16_f32 v107, v112, v113
	v_lshl_add_u64 v[98:99], v[98:99], 0, v[160:161]
	global_store_dwordx4 v[168:169], v[106:109], off
	v_cvt_f32_f16_e32 v184, v185
	v_cvt_f32_f16_sdwa v185, v185 dst_sel:DWORD dst_unused:UNUSED_PAD src0_sel:WORD_1
	v_pk_add_f32 v[108:109], v[104:105], v[182:183]
	global_load_dwordx4 v[104:107], v[98:99], off
	v_cvt_f32_f16_e32 v126, v192
	v_cvt_f32_f16_sdwa v127, v192 dst_sel:DWORD dst_unused:UNUSED_PAD src0_sel:WORD_1
	v_cvt_f32_f16_e32 v128, v193
	v_cvt_f32_f16_sdwa v129, v193 dst_sel:DWORD dst_unused:UNUSED_PAD src0_sel:WORD_1
	v_cvt_f32_f16_e32 v220, v186
	v_cvt_f32_f16_sdwa v221, v186 dst_sel:DWORD dst_unused:UNUSED_PAD src0_sel:WORD_1
	v_cvt_f32_f16_e32 v186, v187
	v_cvt_f32_f16_sdwa v187, v187 dst_sel:DWORD dst_unused:UNUSED_PAD src0_sel:WORD_1
	v_cvt_f32_f16_e32 v222, v188
	v_cvt_f32_f16_sdwa v223, v188 dst_sel:DWORD dst_unused:UNUSED_PAD src0_sel:WORD_1
	v_cvt_f32_f16_e32 v120, v189
	v_cvt_f32_f16_sdwa v121, v189 dst_sel:DWORD dst_unused:UNUSED_PAD src0_sel:WORD_1
	v_lshl_add_u64 v[114:115], v[170:171], 0, s[6:7]
	v_pk_add_f32 v[100:101], v[100:101], v[184:185]
	v_cvt_f32_f16_e32 v122, v190
	v_cvt_f32_f16_sdwa v123, v190 dst_sel:DWORD dst_unused:UNUSED_PAD src0_sel:WORD_1
	v_cvt_f32_f16_e32 v124, v191
	global_load_dwordx4 v[116:119], v[114:115], off offset:256
	v_cvt_f32_f16_sdwa v125, v191 dst_sel:DWORD dst_unused:UNUSED_PAD src0_sel:WORD_1
	v_cvt_pk_f16_f32 v103, v100, v101
	v_cvt_pk_f16_f32 v101, v108, v109
	v_cvt_pk_f16_f32 v100, v110, v111
	v_pk_add_f32 v[84:85], v[84:85], v[128:129]
	v_pk_add_f32 v[82:83], v[82:83], v[126:127]
	global_store_dwordx4 v[168:169], v[100:103], off offset:256
	v_cvt_f32_f16_e32 v136, v198
	v_cvt_f32_f16_sdwa v137, v198 dst_sel:DWORD dst_unused:UNUSED_PAD src0_sel:WORD_1
	v_cvt_f32_f16_e32 v138, v199
	v_cvt_f32_f16_sdwa v139, v199 dst_sel:DWORD dst_unused:UNUSED_PAD src0_sel:WORD_1
	v_cvt_f32_f16_e32 v140, v200
	v_cvt_f32_f16_sdwa v141, v200 dst_sel:DWORD dst_unused:UNUSED_PAD src0_sel:WORD_1
	v_cvt_f32_f16_e32 v168, v201
	v_cvt_f32_f16_sdwa v169, v201 dst_sel:DWORD dst_unused:UNUSED_PAD src0_sel:WORD_1
	v_cvt_pk_f16_f32 v85, v84, v85
	v_cvt_pk_f16_f32 v84, v82, v83
	v_add_u32_e32 v82, 0xa0, v158
	v_pk_add_f32 v[96:97], v[96:97], v[186:187]
	v_pk_add_f32 v[94:95], v[94:95], v[220:221]
	v_pk_add_f32 v[92:93], v[92:93], v[120:121]
	v_pk_add_f32 v[90:91], v[90:91], v[222:223]
	v_ashrrev_i32_e32 v83, 31, v82
	v_cvt_pk_f16_f32 v93, v92, v93
	v_cvt_pk_f16_f32 v92, v90, v91
	v_cvt_pk_f16_f32 v91, v96, v97
	v_cvt_pk_f16_f32 v90, v94, v95
	v_lshlrev_b64 v[82:83], 12, v[82:83]
	global_load_dwordx4 v[100:103], v[98:99], off offset:256
	v_lshl_add_u64 v[82:83], s[64:65], 0, v[82:83]
	global_store_dwordx4 v[162:163], v[90:93], off
	v_cvt_f32_f16_e32 v108, v194
	v_cvt_f32_f16_sdwa v109, v194 dst_sel:DWORD dst_unused:UNUSED_PAD src0_sel:WORD_1
	v_pk_add_f32 v[90:91], v[88:89], v[124:125]
	v_pk_add_f32 v[92:93], v[86:87], v[122:123]
	v_cvt_f32_f16_e32 v110, v195
	v_cvt_f32_f16_sdwa v111, v195 dst_sel:DWORD dst_unused:UNUSED_PAD src0_sel:WORD_1
	v_cvt_f32_f16_e32 v112, v196
	v_cvt_f32_f16_sdwa v113, v196 dst_sel:DWORD dst_unused:UNUSED_PAD src0_sel:WORD_1
	v_cvt_f32_f16_e32 v134, v197
	v_cvt_f32_f16_sdwa v135, v197 dst_sel:DWORD dst_unused:UNUSED_PAD src0_sel:WORD_1
	v_lshl_add_u64 v[94:95], v[82:83], 0, v[160:161]
	v_cvt_pk_f16_f32 v83, v90, v91
	v_cvt_pk_f16_f32 v82, v92, v93
	v_pk_add_f32 v[72:73], v[72:73], v[138:139]
	v_pk_add_f32 v[70:71], v[70:71], v[136:137]
	v_pk_add_f32 v[68:69], v[68:69], v[168:169]
	v_pk_add_f32 v[66:67], v[66:67], v[140:141]
	global_load_dwordx4 v[86:89], v[94:95], off
	v_cvt_pk_f16_f32 v69, v68, v69
	global_store_dwordx4 v[162:163], v[82:85], off offset:256
	global_load_dwordx4 v[82:85], v[94:95], off offset:256
	v_cvt_pk_f16_f32 v68, v66, v67
	v_cvt_pk_f16_f32 v67, v72, v73
	v_cvt_pk_f16_f32 v66, v70, v71
	global_store_dwordx4 v[166:167], v[66:69], off offset:256
	v_pk_add_f32 v[80:81], v[80:81], v[110:111]
	v_pk_add_f32 v[78:79], v[78:79], v[108:109]
	v_add_u32_e32 v66, 0xb0, v158
	v_ashrrev_i32_e32 v67, 31, v66
	v_pk_add_f32 v[76:77], v[76:77], v[134:135]
	v_pk_add_f32 v[74:75], v[74:75], v[112:113]
	v_lshlrev_b64 v[66:67], 12, v[66:67]
	v_cvt_pk_f16_f32 v77, v76, v77
	v_cvt_pk_f16_f32 v76, v74, v75
	v_cvt_pk_f16_f32 v75, v80, v81
	v_cvt_pk_f16_f32 v74, v78, v79
	v_lshl_add_u64 v[66:67], s[64:65], 0, v[66:67]
	global_store_dwordx4 v[166:167], v[74:77], off
	v_cvt_f32_f16_e32 v90, v130
	v_cvt_f32_f16_sdwa v91, v130 dst_sel:DWORD dst_unused:UNUSED_PAD src0_sel:WORD_1
	s_waitcnt vmcnt(9)
	v_cvt_f32_f16_e32 v74, v104
	v_cvt_f32_f16_sdwa v75, v104 dst_sel:DWORD dst_unused:UNUSED_PAD src0_sel:WORD_1
	v_cvt_f32_f16_e32 v76, v105
	v_cvt_f32_f16_sdwa v77, v105 dst_sel:DWORD dst_unused:UNUSED_PAD src0_sel:WORD_1
	v_lshl_add_u64 v[104:105], v[66:67], 0, v[160:161]
	global_load_dwordx4 v[66:69], v[104:105], off
	global_load_dwordx4 v[70:73], v[104:105], off offset:256
	v_cvt_f32_f16_e32 v92, v131
	v_cvt_f32_f16_sdwa v93, v131 dst_sel:DWORD dst_unused:UNUSED_PAD src0_sel:WORD_1
	v_cvt_f32_f16_e32 v96, v132
	v_cvt_f32_f16_sdwa v97, v132 dst_sel:DWORD dst_unused:UNUSED_PAD src0_sel:WORD_1
	v_cvt_f32_f16_e32 v120, v133
	v_cvt_f32_f16_sdwa v121, v133 dst_sel:DWORD dst_unused:UNUSED_PAD src0_sel:WORD_1
	s_waitcnt vmcnt(10)
	v_cvt_f32_f16_e32 v122, v116
	v_cvt_f32_f16_sdwa v123, v116 dst_sel:DWORD dst_unused:UNUSED_PAD src0_sel:WORD_1
	v_cvt_f32_f16_e32 v116, v117
	v_cvt_f32_f16_sdwa v117, v117 dst_sel:DWORD dst_unused:UNUSED_PAD src0_sel:WORD_1
	v_cvt_f32_f16_e32 v124, v118
	v_cvt_f32_f16_sdwa v125, v118 dst_sel:DWORD dst_unused:UNUSED_PAD src0_sel:WORD_1
	v_cvt_f32_f16_e32 v118, v119
	v_cvt_f32_f16_sdwa v119, v119 dst_sel:DWORD dst_unused:UNUSED_PAD src0_sel:WORD_1
	v_cvt_f32_f16_e32 v78, v106
	v_cvt_f32_f16_sdwa v79, v106 dst_sel:DWORD dst_unused:UNUSED_PAD src0_sel:WORD_1
	v_cvt_f32_f16_e32 v80, v107
	v_cvt_f32_f16_sdwa v81, v107 dst_sel:DWORD dst_unused:UNUSED_PAD src0_sel:WORD_1
	v_pk_add_f32 v[64:65], v[64:65], v[92:93]
	v_pk_add_f32 v[62:63], v[62:63], v[90:91]
	v_pk_add_f32 v[60:61], v[60:61], v[120:121]
	v_pk_add_f32 v[58:59], v[58:59], v[96:97]
	v_pk_add_f32 v[56:57], v[56:57], v[116:117]
	v_pk_add_f32 v[54:55], v[54:55], v[122:123]
	v_pk_add_f32 v[48:49], v[48:49], v[118:119]
	v_pk_add_f32 v[46:47], v[46:47], v[124:125]
	v_cvt_pk_f16_f32 v61, v60, v61
	v_cvt_pk_f16_f32 v60, v58, v59
	v_cvt_pk_f16_f32 v59, v64, v65
	v_cvt_pk_f16_f32 v58, v62, v63
	v_cvt_pk_f16_f32 v49, v48, v49
	s_waitcnt vmcnt(8)
	v_cvt_f32_f16_e32 v106, v100
	v_cvt_f32_f16_sdwa v107, v100 dst_sel:DWORD dst_unused:UNUSED_PAD src0_sel:WORD_1
	v_cvt_f32_f16_e32 v100, v101
	v_cvt_f32_f16_sdwa v101, v101 dst_sel:DWORD dst_unused:UNUSED_PAD src0_sel:WORD_1
	v_cvt_f32_f16_e32 v108, v102
	v_cvt_f32_f16_sdwa v109, v102 dst_sel:DWORD dst_unused:UNUSED_PAD src0_sel:WORD_1
	v_cvt_f32_f16_e32 v102, v103
	v_cvt_f32_f16_sdwa v103, v103 dst_sel:DWORD dst_unused:UNUSED_PAD src0_sel:WORD_1
	v_cvt_pk_f16_f32 v48, v46, v47
	v_cvt_pk_f16_f32 v47, v56, v57
	v_cvt_pk_f16_f32 v46, v54, v55
	global_store_dwordx4 v[164:165], v[58:61], off
	global_store_dwordx4 v[114:115], v[46:49], off offset:256
	v_pk_add_f32 v[32:33], v[32:33], v[100:101]
	v_pk_add_f32 v[30:31], v[30:31], v[106:107]
	v_pk_add_f32 v[28:29], v[28:29], v[102:103]
	v_pk_add_f32 v[26:27], v[26:27], v[108:109]
	v_cvt_pk_f16_f32 v29, v28, v29
	v_cvt_pk_f16_f32 v28, v26, v27
	v_cvt_pk_f16_f32 v27, v32, v33
	s_waitcnt vmcnt(8)
	v_cvt_f32_f16_e32 v46, v86
	v_cvt_f32_f16_sdwa v47, v86 dst_sel:DWORD dst_unused:UNUSED_PAD src0_sel:WORD_1
	v_cvt_f32_f16_e32 v48, v87
	v_cvt_f32_f16_sdwa v49, v87 dst_sel:DWORD dst_unused:UNUSED_PAD src0_sel:WORD_1
	v_cvt_f32_f16_e32 v54, v88
	v_cvt_f32_f16_sdwa v55, v88 dst_sel:DWORD dst_unused:UNUSED_PAD src0_sel:WORD_1
	v_cvt_f32_f16_e32 v56, v89
	v_cvt_f32_f16_sdwa v57, v89 dst_sel:DWORD dst_unused:UNUSED_PAD src0_sel:WORD_1
	s_waitcnt vmcnt(6)
	v_cvt_f32_f16_e32 v58, v82
	v_cvt_f32_f16_sdwa v59, v82 dst_sel:DWORD dst_unused:UNUSED_PAD src0_sel:WORD_1
	v_cvt_f32_f16_e32 v60, v83
	v_cvt_f32_f16_sdwa v61, v83 dst_sel:DWORD dst_unused:UNUSED_PAD src0_sel:WORD_1
	v_cvt_f32_f16_e32 v62, v84
	v_cvt_f32_f16_sdwa v63, v84 dst_sel:DWORD dst_unused:UNUSED_PAD src0_sel:WORD_1
	v_cvt_f32_f16_e32 v64, v85
	v_cvt_f32_f16_sdwa v65, v85 dst_sel:DWORD dst_unused:UNUSED_PAD src0_sel:WORD_1
	v_cvt_pk_f16_f32 v26, v30, v31
	global_store_dwordx4 v[98:99], v[26:29], off offset:256
	v_pk_add_f32 v[30:31], v[38:39], v[46:47]
	v_pk_add_f32 v[32:33], v[34:35], v[54:55]
	v_pk_add_f32 v[26:27], v[40:41], v[48:49]
	v_pk_add_f32 v[28:29], v[36:37], v[56:57]
	v_pk_add_f32 v[24:25], v[24:25], v[60:61]
	v_pk_add_f32 v[22:23], v[22:23], v[58:59]
	v_pk_add_f32 v[20:21], v[20:21], v[64:65]
	v_pk_add_f32 v[18:19], v[18:19], v[62:63]
	v_cvt_pk_f16_f32 v29, v28, v29
	v_cvt_pk_f16_f32 v28, v32, v33
	v_cvt_pk_f16_f32 v27, v26, v27
	v_cvt_pk_f16_f32 v26, v30, v31
	v_cvt_pk_f16_f32 v21, v20, v21
	v_cvt_pk_f16_f32 v20, v18, v19
	v_cvt_pk_f16_f32 v19, v24, v25
	v_cvt_pk_f16_f32 v18, v22, v23
	global_store_dwordx4 v[94:95], v[26:29], off
	global_store_dwordx4 v[94:95], v[18:21], off offset:256
	s_waitcnt vmcnt(5)
	v_cvt_f32_f16_e32 v22, v70
	v_cvt_f32_f16_sdwa v23, v70 dst_sel:DWORD dst_unused:UNUSED_PAD src0_sel:WORD_1
	v_cvt_f32_f16_e32 v18, v72
	v_cvt_f32_f16_sdwa v19, v72 dst_sel:DWORD dst_unused:UNUSED_PAD src0_sel:WORD_1
	v_cvt_f32_f16_e32 v20, v73
	v_cvt_f32_f16_sdwa v21, v73 dst_sel:DWORD dst_unused:UNUSED_PAD src0_sel:WORD_1
	v_cvt_f32_f16_e32 v24, v71
	v_cvt_f32_f16_sdwa v25, v71 dst_sel:DWORD dst_unused:UNUSED_PAD src0_sel:WORD_1
	v_cvt_f32_f16_e32 v26, v68
	v_cvt_f32_f16_e32 v28, v69
	v_cvt_f32_f16_e32 v30, v66
	v_cvt_f32_f16_e32 v32, v67
	v_cvt_f32_f16_sdwa v33, v67 dst_sel:DWORD dst_unused:UNUSED_PAD src0_sel:WORD_1
	v_cvt_f32_f16_sdwa v31, v66 dst_sel:DWORD dst_unused:UNUSED_PAD src0_sel:WORD_1
	v_cvt_f32_f16_sdwa v29, v69 dst_sel:DWORD dst_unused:UNUSED_PAD src0_sel:WORD_1
	v_cvt_f32_f16_sdwa v27, v68 dst_sel:DWORD dst_unused:UNUSED_PAD src0_sel:WORD_1
	v_pk_add_f32 v[52:53], v[52:53], v[76:77]
	v_pk_add_f32 v[50:51], v[50:51], v[74:75]
	v_pk_add_f32 v[44:45], v[44:45], v[80:81]
	v_pk_add_f32 v[42:43], v[42:43], v[78:79]
	v_pk_add_f32 v[16:17], v[16:17], v[32:33]
	v_pk_add_f32 v[14:15], v[14:15], v[30:31]
	v_pk_add_f32 v[12:13], v[12:13], v[28:29]
	v_pk_add_f32 v[10:11], v[10:11], v[26:27]
	v_pk_add_f32 v[8:9], v[8:9], v[24:25]
	v_pk_add_f32 v[6:7], v[6:7], v[22:23]
	v_pk_add_f32 v[4:5], v[4:5], v[20:21]
	v_pk_add_f32 v[2:3], v[2:3], v[18:19]
	v_cvt_pk_f16_f32 v45, v44, v45
	v_cvt_pk_f16_f32 v44, v42, v43
	v_cvt_pk_f16_f32 v43, v52, v53
	v_cvt_pk_f16_f32 v42, v50, v51
	v_cvt_pk_f16_f32 v13, v12, v13
	v_cvt_pk_f16_f32 v12, v10, v11
	v_cvt_pk_f16_f32 v11, v16, v17
	v_cvt_pk_f16_f32 v10, v14, v15
	v_cvt_pk_f16_f32 v5, v4, v5
	v_cvt_pk_f16_f32 v4, v2, v3
	v_cvt_pk_f16_f32 v3, v8, v9
	v_cvt_pk_f16_f32 v2, v6, v7
	global_store_dwordx4 v[98:99], v[42:45], off
	global_store_dwordx4 v[104:105], v[10:13], off
	global_store_dwordx4 v[104:105], v[2:5], off offset:256
	s_cbranch_vccnz .LBB0_3698
	s_andn2_b64 vcc, exec, s[8:9]
	s_cbranch_vccnz .LBB0_3697
	s_barrier
	s_branch .LBB0_3697

.LBB0_3933:
	v_lshl_add_u32 v146, s43, 8, v152
	v_lshl_or_b32 v148, s44, 8, v154
	v_ashrrev_i32_e32 v147, 31, v146
	v_ashrrev_i32_e32 v149, 31, v148
	v_lshlrev_b64 v[144:145], 12, v[146:147]
	v_lshl_add_u64 v[150:151], s[64:65], 0, v[144:145]
	v_lshlrev_b64 v[144:145], 1, v[148:149]
	v_or_b32_e32 v174, 16, v146
	v_lshl_add_u64 v[150:151], v[150:151], 0, v[144:145]
	v_ashrrev_i32_e32 v175, 31, v174
	v_mov_b32_e32 v235, 0
	global_load_dwordx4 v[228:231], v[150:151], off
	global_load_dwordx4 v[228:231], v[150:151], off offset:256
	v_mov_b32_e32 v234, 1
	v_lshl_add_u64 v[232:233], v[234:235], 16, v[150:151]
	global_load_dwordx4 v[228:231], v[232:233], off
	global_load_dwordx4 v[228:231], v[232:233], off offset:256
	v_mov_b32_e32 v234, 2
	v_lshl_add_u64 v[232:233], v[234:235], 16, v[150:151]
	global_load_dwordx4 v[228:231], v[232:233], off
	global_load_dwordx4 v[228:231], v[232:233], off offset:256
	v_mov_b32_e32 v234, 3
	v_lshl_add_u64 v[232:233], v[234:235], 16, v[150:151]
	global_load_dwordx4 v[228:231], v[232:233], off
	global_load_dwordx4 v[228:231], v[232:233], off offset:256
	v_mov_b32_e32 v234, 8
	v_lshl_add_u64 v[232:233], v[234:235], 16, v[150:151]
	global_load_dwordx4 v[228:231], v[232:233], off
	global_load_dwordx4 v[228:231], v[232:233], off offset:256
	v_mov_b32_e32 v234, 9
	v_lshl_add_u64 v[232:233], v[234:235], 16, v[150:151]
	global_load_dwordx4 v[228:231], v[232:233], off
	global_load_dwordx4 v[228:231], v[232:233], off offset:256
	v_mov_b32_e32 v234, 10
	v_lshl_add_u64 v[232:233], v[234:235], 16, v[150:151]
	global_load_dwordx4 v[228:231], v[232:233], off
	global_load_dwordx4 v[228:231], v[232:233], off offset:256
	v_mov_b32_e32 v234, 11
	v_lshl_add_u64 v[232:233], v[234:235], 16, v[150:151]
	global_load_dwordx4 v[228:231], v[232:233], off
	global_load_dwordx4 v[228:231], v[232:233], off offset:256
	global_load_dwordx4 v[158:161], v[150:151], off
	global_load_dwordx4 v[162:165], v[150:151], off offset:256
	v_lshlrev_b64 v[150:151], 12, v[174:175]
	v_lshl_add_u64 v[150:151], s[64:65], 0, v[150:151]
	v_lshl_add_u64 v[150:151], v[150:151], 0, v[144:145]
	global_load_dwordx4 v[166:169], v[150:151], off
	global_load_dwordx4 v[170:173], v[150:151], off offset:256
	v_readlane_b32 s44, v247, 3
	v_or_b32_e32 v150, 32, v146
	v_readlane_b32 s50, v247, 9
	v_readlane_b32 s51, v247, 10
	v_lshlrev_b64 v[178:179], 13, v[146:147]
	v_ashrrev_i32_e32 v151, 31, v150
	s_mov_b64 s[18:19], s[50:51]
	v_lshlrev_b64 v[148:149], 2, v[148:149]
	v_lshl_add_u64 v[178:179], s[18:19], 0, v[178:179]
	v_lshlrev_b64 v[180:181], 12, v[150:151]
	v_lshl_add_u64 v[178:179], v[178:179], 0, v[148:149]
	v_lshl_add_u64 v[180:181], s[64:65], 0, v[180:181]
	v_or_b32_e32 v176, 48, v146
	v_lshl_add_u64 v[180:181], v[180:181], 0, v[144:145]
	v_ashrrev_i32_e32 v177, 31, v176
	v_lshlrev_b64 v[174:175], 13, v[174:175]
	v_lshlrev_b64 v[182:183], 12, v[176:177]
	v_lshl_add_u64 v[174:175], s[18:19], 0, v[174:175]
	v_lshl_add_u64 v[182:183], s[64:65], 0, v[182:183]
	v_lshl_add_u64 v[174:175], v[174:175], 0, v[148:149]
	v_lshl_add_u64 v[182:183], v[182:183], 0, v[144:145]
	s_and_b64 vcc, exec, s[2:3]
	s_mov_b64 s[0:1], -1
	v_readlane_b32 s45, v247, 4
	v_readlane_b32 s46, v247, 5
	v_readlane_b32 s47, v247, 6
	v_readlane_b32 s48, v247, 7
	v_readlane_b32 s49, v247, 8
	s_waitcnt vmcnt(0)
	v_cvt_f32_f16_e32 v184, v158
	v_cvt_f32_f16_sdwa v185, v158 dst_sel:DWORD dst_unused:UNUSED_PAD src0_sel:WORD_1
	v_cvt_f32_f16_e32 v158, v159
	v_cvt_f32_f16_sdwa v159, v159 dst_sel:DWORD dst_unused:UNUSED_PAD src0_sel:WORD_1
	v_cvt_f32_f16_e32 v186, v160
	v_cvt_f32_f16_sdwa v187, v160 dst_sel:DWORD dst_unused:UNUSED_PAD src0_sel:WORD_1
	v_cvt_f32_f16_e32 v160, v161
	v_cvt_f32_f16_sdwa v161, v161 dst_sel:DWORD dst_unused:UNUSED_PAD src0_sel:WORD_1
	v_cvt_f32_f16_e32 v188, v162
	v_cvt_f32_f16_sdwa v189, v162 dst_sel:DWORD dst_unused:UNUSED_PAD src0_sel:WORD_1
	v_cvt_f32_f16_e32 v162, v163
	v_cvt_f32_f16_sdwa v163, v163 dst_sel:DWORD dst_unused:UNUSED_PAD src0_sel:WORD_1
	v_cvt_f32_f16_e32 v190, v164
	v_cvt_f32_f16_sdwa v191, v164 dst_sel:DWORD dst_unused:UNUSED_PAD src0_sel:WORD_1
	v_cvt_f32_f16_e32 v164, v165
	v_cvt_f32_f16_sdwa v165, v165 dst_sel:DWORD dst_unused:UNUSED_PAD src0_sel:WORD_1
	v_cvt_f32_f16_e32 v192, v166
	v_cvt_f32_f16_sdwa v193, v166 dst_sel:DWORD dst_unused:UNUSED_PAD src0_sel:WORD_1
	v_cvt_f32_f16_e32 v166, v167
	v_cvt_f32_f16_sdwa v167, v167 dst_sel:DWORD dst_unused:UNUSED_PAD src0_sel:WORD_1
	v_pk_fma_f32 v[126:127], v[126:127], 0.5, v[158:159] op_sel_hi:[1,0,1]
	v_pk_fma_f32 v[124:125], v[124:125], 0.5, v[184:185] op_sel_hi:[1,0,1]
	v_pk_fma_f32 v[120:121], v[120:121], 0.5, v[186:187] op_sel_hi:[1,0,1]
	v_cvt_f32_f16_e32 v194, v168
	v_cvt_f32_f16_sdwa v195, v168 dst_sel:DWORD dst_unused:UNUSED_PAD src0_sel:WORD_1
	v_cvt_f32_f16_e32 v168, v169
	v_cvt_f32_f16_sdwa v169, v169 dst_sel:DWORD dst_unused:UNUSED_PAD src0_sel:WORD_1
	v_cvt_f32_f16_e32 v196, v170
	v_cvt_f32_f16_sdwa v197, v170 dst_sel:DWORD dst_unused:UNUSED_PAD src0_sel:WORD_1
	v_cvt_f32_f16_e32 v170, v171
	v_cvt_f32_f16_sdwa v171, v171 dst_sel:DWORD dst_unused:UNUSED_PAD src0_sel:WORD_1
	v_cvt_f32_f16_e32 v198, v172
	v_cvt_f32_f16_sdwa v199, v172 dst_sel:DWORD dst_unused:UNUSED_PAD src0_sel:WORD_1
	v_pk_fma_f32 v[122:123], v[122:123], 0.5, v[160:161] op_sel_hi:[1,0,1]
	v_pk_fma_f32 v[110:111], v[110:111], 0.5, v[162:163] op_sel_hi:[1,0,1]
	v_pk_fma_f32 v[108:109], v[108:109], 0.5, v[188:189] op_sel_hi:[1,0,1]
	v_pk_fma_f32 v[106:107], v[106:107], 0.5, v[164:165] op_sel_hi:[1,0,1]
	v_pk_fma_f32 v[104:105], v[104:105], 0.5, v[190:191] op_sel_hi:[1,0,1]
	global_store_dwordx4 v[178:179], v[124:127], off
	global_store_dwordx4 v[178:179], v[120:123], off offset:16
	global_store_dwordx4 v[178:179], v[108:111], off offset:512
	global_store_dwordx4 v[178:179], v[104:107], off offset:528
	v_cvt_f32_f16_e32 v120, v173
	v_cvt_f32_f16_sdwa v121, v173 dst_sel:DWORD dst_unused:UNUSED_PAD src0_sel:WORD_1
	global_load_dwordx4 v[104:107], v[180:181], off
	v_pk_fma_f32 v[110:111], v[118:119], 0.5, v[166:167] op_sel_hi:[1,0,1]
	v_pk_fma_f32 v[108:109], v[116:117], 0.5, v[192:193] op_sel_hi:[1,0,1]
	global_load_dwordx4 v[116:119], v[180:181], off offset:256
	v_pk_fma_f32 v[114:115], v[114:115], 0.5, v[168:169] op_sel_hi:[1,0,1]
	v_pk_fma_f32 v[112:113], v[112:113], 0.5, v[194:195] op_sel_hi:[1,0,1]
	v_pk_fma_f32 v[102:103], v[102:103], 0.5, v[170:171] op_sel_hi:[1,0,1]
	v_pk_fma_f32 v[100:101], v[100:101], 0.5, v[196:197] op_sel_hi:[1,0,1]
	v_pk_fma_f32 v[98:99], v[98:99], 0.5, v[120:121] op_sel_hi:[1,0,1]
	v_pk_fma_f32 v[96:97], v[96:97], 0.5, v[198:199] op_sel_hi:[1,0,1]
	global_store_dwordx4 v[174:175], v[108:111], off
	global_store_dwordx4 v[174:175], v[112:115], off offset:16
	global_store_dwordx4 v[174:175], v[100:103], off offset:512
	global_store_dwordx4 v[174:175], v[96:99], off offset:528
	global_load_dwordx4 v[98:101], v[182:183], off
	s_nop 0
	global_load_dwordx4 v[108:111], v[182:183], off offset:256
	v_add_u32_e32 v96, 0x80, v146
	v_lshlrev_b64 v[112:113], 13, v[150:151]
	v_ashrrev_i32_e32 v97, 31, v96
	v_lshlrev_b64 v[114:115], 12, v[96:97]
	v_lshl_add_u64 v[112:113], s[18:19], 0, v[112:113]
	v_lshl_add_u64 v[114:115], s[64:65], 0, v[114:115]
	v_lshl_add_u64 v[112:113], v[112:113], 0, v[148:149]
	v_lshl_add_u64 v[114:115], v[114:115], 0, v[144:145]
	v_add_u32_e32 v102, 0x90, v146
	v_ashrrev_i32_e32 v103, 31, v102
	v_lshlrev_b64 v[120:121], 13, v[176:177]
	v_lshlrev_b64 v[122:123], 12, v[102:103]
	v_lshl_add_u64 v[120:121], s[18:19], 0, v[120:121]
	v_lshl_add_u64 v[122:123], s[64:65], 0, v[122:123]
	v_lshl_add_u64 v[120:121], v[120:121], 0, v[148:149]
	v_lshl_add_u64 v[122:123], v[122:123], 0, v[144:145]
	s_waitcnt vmcnt(7)
	v_cvt_f32_f16_e32 v124, v104
	v_cvt_f32_f16_sdwa v125, v104 dst_sel:DWORD dst_unused:UNUSED_PAD src0_sel:WORD_1
	v_cvt_f32_f16_e32 v104, v105
	v_cvt_f32_f16_sdwa v105, v105 dst_sel:DWORD dst_unused:UNUSED_PAD src0_sel:WORD_1
	v_cvt_f32_f16_e32 v126, v106
	v_cvt_f32_f16_sdwa v127, v106 dst_sel:DWORD dst_unused:UNUSED_PAD src0_sel:WORD_1
	v_cvt_f32_f16_e32 v106, v107
	v_cvt_f32_f16_sdwa v107, v107 dst_sel:DWORD dst_unused:UNUSED_PAD src0_sel:WORD_1
	s_waitcnt vmcnt(6)
	v_cvt_f32_f16_e32 v150, v116
	v_cvt_f32_f16_sdwa v151, v116 dst_sel:DWORD dst_unused:UNUSED_PAD src0_sel:WORD_1
	v_cvt_f32_f16_e32 v116, v117
	v_cvt_f32_f16_sdwa v117, v117 dst_sel:DWORD dst_unused:UNUSED_PAD src0_sel:WORD_1
	v_cvt_f32_f16_e32 v158, v118
	v_cvt_f32_f16_sdwa v159, v118 dst_sel:DWORD dst_unused:UNUSED_PAD src0_sel:WORD_1
	v_cvt_f32_f16_e32 v118, v119
	v_cvt_f32_f16_sdwa v119, v119 dst_sel:DWORD dst_unused:UNUSED_PAD src0_sel:WORD_1
	s_waitcnt vmcnt(1)
	v_cvt_f32_f16_e32 v160, v98
	v_cvt_f32_f16_sdwa v161, v98 dst_sel:DWORD dst_unused:UNUSED_PAD src0_sel:WORD_1
	v_cvt_f32_f16_e32 v98, v99
	v_cvt_f32_f16_sdwa v99, v99 dst_sel:DWORD dst_unused:UNUSED_PAD src0_sel:WORD_1
	v_pk_fma_f32 v[94:95], v[94:95], 0.5, v[104:105] op_sel_hi:[1,0,1]
	v_pk_fma_f32 v[92:93], v[92:93], 0.5, v[124:125] op_sel_hi:[1,0,1]
	v_pk_fma_f32 v[90:91], v[90:91], 0.5, v[106:107] op_sel_hi:[1,0,1]
	v_pk_fma_f32 v[88:89], v[88:89], 0.5, v[126:127] op_sel_hi:[1,0,1]
	v_pk_fma_f32 v[78:79], v[78:79], 0.5, v[116:117] op_sel_hi:[1,0,1]
	v_pk_fma_f32 v[76:77], v[76:77], 0.5, v[150:151] op_sel_hi:[1,0,1]
	v_pk_fma_f32 v[74:75], v[74:75], 0.5, v[118:119] op_sel_hi:[1,0,1]
	v_pk_fma_f32 v[72:73], v[72:73], 0.5, v[158:159] op_sel_hi:[1,0,1]
	global_store_dwordx4 v[112:113], v[92:95], off
	global_store_dwordx4 v[112:113], v[88:91], off offset:16
	global_store_dwordx4 v[112:113], v[76:79], off offset:512
	global_store_dwordx4 v[112:113], v[72:75], off offset:528
	v_cvt_f32_f16_e32 v162, v100
	v_cvt_f32_f16_sdwa v163, v100 dst_sel:DWORD dst_unused:UNUSED_PAD src0_sel:WORD_1
	v_cvt_f32_f16_e32 v100, v101
	v_cvt_f32_f16_sdwa v101, v101 dst_sel:DWORD dst_unused:UNUSED_PAD src0_sel:WORD_1
	s_waitcnt vmcnt(4)
	v_cvt_f32_f16_e32 v164, v108
	v_cvt_f32_f16_sdwa v165, v108 dst_sel:DWORD dst_unused:UNUSED_PAD src0_sel:WORD_1
	v_cvt_f32_f16_e32 v108, v109
	v_cvt_f32_f16_sdwa v109, v109 dst_sel:DWORD dst_unused:UNUSED_PAD src0_sel:WORD_1
	v_cvt_f32_f16_e32 v166, v110
	v_cvt_f32_f16_sdwa v167, v110 dst_sel:DWORD dst_unused:UNUSED_PAD src0_sel:WORD_1
	global_load_dwordx4 v[72:75], v[114:115], off
	v_cvt_f32_f16_e32 v88, v111
	v_cvt_f32_f16_sdwa v89, v111 dst_sel:DWORD dst_unused:UNUSED_PAD src0_sel:WORD_1
	v_pk_fma_f32 v[78:79], v[86:87], 0.5, v[98:99] op_sel_hi:[1,0,1]
	v_pk_fma_f32 v[76:77], v[84:85], 0.5, v[160:161] op_sel_hi:[1,0,1]
	global_load_dwordx4 v[84:87], v[114:115], off offset:256
	v_pk_fma_f32 v[82:83], v[82:83], 0.5, v[100:101] op_sel_hi:[1,0,1]
	v_pk_fma_f32 v[80:81], v[80:81], 0.5, v[162:163] op_sel_hi:[1,0,1]
	v_pk_fma_f32 v[70:71], v[70:71], 0.5, v[108:109] op_sel_hi:[1,0,1]
	v_pk_fma_f32 v[68:69], v[68:69], 0.5, v[164:165] op_sel_hi:[1,0,1]
	v_pk_fma_f32 v[66:67], v[66:67], 0.5, v[88:89] op_sel_hi:[1,0,1]
	v_pk_fma_f32 v[64:65], v[64:65], 0.5, v[166:167] op_sel_hi:[1,0,1]
	global_store_dwordx4 v[120:121], v[76:79], off
	global_store_dwordx4 v[120:121], v[80:83], off offset:16
	global_store_dwordx4 v[120:121], v[68:71], off offset:512
	global_store_dwordx4 v[120:121], v[64:67], off offset:528
	global_load_dwordx4 v[66:69], v[122:123], off
	s_nop 0
	global_load_dwordx4 v[76:79], v[122:123], off offset:256
	v_lshlrev_b64 v[80:81], 13, v[96:97]
	v_lshl_add_u64 v[80:81], s[18:19], 0, v[80:81]
	v_add_u32_e32 v64, 0xa0, v146
	v_lshl_add_u64 v[80:81], v[80:81], 0, v[148:149]
	v_add_u32_e32 v70, 0xb0, v146
	v_ashrrev_i32_e32 v65, 31, v64
	v_lshlrev_b64 v[88:89], 13, v[102:103]
	v_ashrrev_i32_e32 v71, 31, v70
	v_lshlrev_b64 v[82:83], 12, v[64:65]
	v_lshlrev_b64 v[90:91], 12, v[70:71]
	v_lshl_add_u64 v[82:83], s[64:65], 0, v[82:83]
	v_lshl_add_u64 v[88:89], s[18:19], 0, v[88:89]
	v_lshl_add_u64 v[90:91], s[64:65], 0, v[90:91]
	v_lshl_add_u64 v[82:83], v[82:83], 0, v[144:145]
	v_lshl_add_u64 v[88:89], v[88:89], 0, v[148:149]
	v_lshl_add_u64 v[90:91], v[90:91], 0, v[144:145]
	s_waitcnt vmcnt(7)
	v_cvt_f32_f16_e32 v92, v72
	v_cvt_f32_f16_sdwa v93, v72 dst_sel:DWORD dst_unused:UNUSED_PAD src0_sel:WORD_1
	v_cvt_f32_f16_e32 v72, v73
	v_cvt_f32_f16_sdwa v73, v73 dst_sel:DWORD dst_unused:UNUSED_PAD src0_sel:WORD_1
	v_cvt_f32_f16_e32 v94, v74
	v_cvt_f32_f16_sdwa v95, v74 dst_sel:DWORD dst_unused:UNUSED_PAD src0_sel:WORD_1
	v_cvt_f32_f16_e32 v74, v75
	v_cvt_f32_f16_sdwa v75, v75 dst_sel:DWORD dst_unused:UNUSED_PAD src0_sel:WORD_1
	s_waitcnt vmcnt(6)
	v_cvt_f32_f16_e32 v96, v84
	v_cvt_f32_f16_sdwa v97, v84 dst_sel:DWORD dst_unused:UNUSED_PAD src0_sel:WORD_1
	v_cvt_f32_f16_e32 v84, v85
	v_cvt_f32_f16_sdwa v85, v85 dst_sel:DWORD dst_unused:UNUSED_PAD src0_sel:WORD_1
	v_cvt_f32_f16_e32 v98, v86
	v_cvt_f32_f16_sdwa v99, v86 dst_sel:DWORD dst_unused:UNUSED_PAD src0_sel:WORD_1
	v_cvt_f32_f16_e32 v86, v87
	v_cvt_f32_f16_sdwa v87, v87 dst_sel:DWORD dst_unused:UNUSED_PAD src0_sel:WORD_1
	s_waitcnt vmcnt(1)
	v_cvt_f32_f16_e32 v100, v66
	v_cvt_f32_f16_sdwa v101, v66 dst_sel:DWORD dst_unused:UNUSED_PAD src0_sel:WORD_1
	v_cvt_f32_f16_e32 v66, v67
	v_cvt_f32_f16_sdwa v67, v67 dst_sel:DWORD dst_unused:UNUSED_PAD src0_sel:WORD_1
	v_pk_fma_f32 v[62:63], v[62:63], 0.5, v[72:73] op_sel_hi:[1,0,1]
	v_pk_fma_f32 v[60:61], v[60:61], 0.5, v[92:93] op_sel_hi:[1,0,1]
	v_pk_fma_f32 v[56:57], v[56:57], 0.5, v[94:95] op_sel_hi:[1,0,1]
	v_cvt_f32_f16_e32 v102, v68
	v_cvt_f32_f16_sdwa v103, v68 dst_sel:DWORD dst_unused:UNUSED_PAD src0_sel:WORD_1
	v_cvt_f32_f16_e32 v68, v69
	v_cvt_f32_f16_sdwa v69, v69 dst_sel:DWORD dst_unused:UNUSED_PAD src0_sel:WORD_1
	s_waitcnt vmcnt(0)
	v_cvt_f32_f16_e32 v104, v76
	v_cvt_f32_f16_sdwa v105, v76 dst_sel:DWORD dst_unused:UNUSED_PAD src0_sel:WORD_1
	v_cvt_f32_f16_e32 v76, v77
	v_cvt_f32_f16_sdwa v77, v77 dst_sel:DWORD dst_unused:UNUSED_PAD src0_sel:WORD_1
	v_cvt_f32_f16_e32 v106, v78
	v_cvt_f32_f16_sdwa v107, v78 dst_sel:DWORD dst_unused:UNUSED_PAD src0_sel:WORD_1
	v_pk_fma_f32 v[58:59], v[58:59], 0.5, v[74:75] op_sel_hi:[1,0,1]
	v_pk_fma_f32 v[46:47], v[46:47], 0.5, v[84:85] op_sel_hi:[1,0,1]
	v_pk_fma_f32 v[44:45], v[44:45], 0.5, v[96:97] op_sel_hi:[1,0,1]
	v_pk_fma_f32 v[42:43], v[42:43], 0.5, v[86:87] op_sel_hi:[1,0,1]
	v_pk_fma_f32 v[40:41], v[40:41], 0.5, v[98:99] op_sel_hi:[1,0,1]
	global_store_dwordx4 v[80:81], v[60:63], off
	global_store_dwordx4 v[80:81], v[56:59], off offset:16
	global_store_dwordx4 v[80:81], v[44:47], off offset:512
	global_store_dwordx4 v[80:81], v[40:43], off offset:528
	v_cvt_f32_f16_e32 v56, v79
	v_cvt_f32_f16_sdwa v57, v79 dst_sel:DWORD dst_unused:UNUSED_PAD src0_sel:WORD_1
	v_pk_fma_f32 v[46:47], v[54:55], 0.5, v[66:67] op_sel_hi:[1,0,1]
	v_pk_fma_f32 v[44:45], v[52:53], 0.5, v[100:101] op_sel_hi:[1,0,1]
	global_load_dwordx4 v[40:43], v[82:83], off
	global_load_dwordx4 v[52:55], v[82:83], off offset:256
	v_pk_fma_f32 v[50:51], v[50:51], 0.5, v[68:69] op_sel_hi:[1,0,1]
	v_pk_fma_f32 v[48:49], v[48:49], 0.5, v[102:103] op_sel_hi:[1,0,1]
	v_pk_fma_f32 v[38:39], v[38:39], 0.5, v[76:77] op_sel_hi:[1,0,1]
	v_pk_fma_f32 v[36:37], v[36:37], 0.5, v[104:105] op_sel_hi:[1,0,1]
	v_pk_fma_f32 v[34:35], v[34:35], 0.5, v[56:57] op_sel_hi:[1,0,1]
	v_pk_fma_f32 v[32:33], v[32:33], 0.5, v[106:107] op_sel_hi:[1,0,1]
	global_store_dwordx4 v[88:89], v[44:47], off
	global_store_dwordx4 v[88:89], v[48:51], off offset:16
	global_store_dwordx4 v[88:89], v[36:39], off offset:512
	global_store_dwordx4 v[88:89], v[32:35], off offset:528
	global_load_dwordx4 v[32:35], v[90:91], off offset:256
	s_nop 0
	global_load_dwordx4 v[36:39], v[90:91], off
	v_lshlrev_b64 v[44:45], 13, v[64:65]
	v_lshlrev_b64 v[46:47], 13, v[70:71]
	v_lshl_add_u64 v[44:45], s[18:19], 0, v[44:45]
	v_lshl_add_u64 v[46:47], s[18:19], 0, v[46:47]
	v_lshl_add_u64 v[44:45], v[44:45], 0, v[148:149]
	v_lshl_add_u64 v[46:47], v[46:47], 0, v[148:149]
	s_waitcnt vmcnt(7)
	v_cvt_f32_f16_e32 v48, v40
	v_cvt_f32_f16_sdwa v49, v40 dst_sel:DWORD dst_unused:UNUSED_PAD src0_sel:WORD_1
	v_cvt_f32_f16_e32 v40, v41
	v_cvt_f32_f16_sdwa v41, v41 dst_sel:DWORD dst_unused:UNUSED_PAD src0_sel:WORD_1
	s_waitcnt vmcnt(6)
	v_cvt_f32_f16_e32 v58, v54
	v_cvt_f32_f16_sdwa v59, v54 dst_sel:DWORD dst_unused:UNUSED_PAD src0_sel:WORD_1
	v_cvt_f32_f16_e32 v54, v55
	v_cvt_f32_f16_sdwa v55, v55 dst_sel:DWORD dst_unused:UNUSED_PAD src0_sel:WORD_1
	v_cvt_f32_f16_e32 v50, v42
	v_cvt_f32_f16_sdwa v51, v42 dst_sel:DWORD dst_unused:UNUSED_PAD src0_sel:WORD_1
	v_cvt_f32_f16_e32 v42, v43
	v_cvt_f32_f16_sdwa v43, v43 dst_sel:DWORD dst_unused:UNUSED_PAD src0_sel:WORD_1
	v_cvt_f32_f16_e32 v56, v52
	v_cvt_f32_f16_sdwa v57, v52 dst_sel:DWORD dst_unused:UNUSED_PAD src0_sel:WORD_1
	v_cvt_f32_f16_e32 v52, v53
	v_cvt_f32_f16_sdwa v53, v53 dst_sel:DWORD dst_unused:UNUSED_PAD src0_sel:WORD_1
	s_waitcnt vmcnt(0)
	v_cvt_f32_f16_e32 v66, v36
	v_cvt_f32_f16_sdwa v67, v36 dst_sel:DWORD dst_unused:UNUSED_PAD src0_sel:WORD_1
	v_cvt_f32_f16_e32 v36, v37
	v_cvt_f32_f16_sdwa v37, v37 dst_sel:DWORD dst_unused:UNUSED_PAD src0_sel:WORD_1
	v_cvt_f32_f16_e32 v60, v34
	v_cvt_f32_f16_sdwa v61, v34 dst_sel:DWORD dst_unused:UNUSED_PAD src0_sel:WORD_1
	v_cvt_f32_f16_e32 v34, v35
	v_cvt_f32_f16_sdwa v35, v35 dst_sel:DWORD dst_unused:UNUSED_PAD src0_sel:WORD_1
	v_cvt_f32_f16_e32 v62, v32
	v_cvt_f32_f16_sdwa v63, v32 dst_sel:DWORD dst_unused:UNUSED_PAD src0_sel:WORD_1
	v_cvt_f32_f16_e32 v32, v33
	v_cvt_f32_f16_sdwa v33, v33 dst_sel:DWORD dst_unused:UNUSED_PAD src0_sel:WORD_1
	v_cvt_f32_f16_e32 v64, v38
	v_cvt_f32_f16_sdwa v65, v38 dst_sel:DWORD dst_unused:UNUSED_PAD src0_sel:WORD_1
	v_cvt_f32_f16_e32 v38, v39
	v_cvt_f32_f16_sdwa v39, v39 dst_sel:DWORD dst_unused:UNUSED_PAD src0_sel:WORD_1
	v_pk_fma_f32 v[30:31], v[30:31], 0.5, v[40:41] op_sel_hi:[1,0,1]
	v_pk_fma_f32 v[28:29], v[28:29], 0.5, v[48:49] op_sel_hi:[1,0,1]
	v_pk_fma_f32 v[10:11], v[10:11], 0.5, v[54:55] op_sel_hi:[1,0,1]
	v_pk_fma_f32 v[8:9], v[8:9], 0.5, v[58:59] op_sel_hi:[1,0,1]
	v_pk_fma_f32 v[26:27], v[26:27], 0.5, v[42:43] op_sel_hi:[1,0,1]
	v_pk_fma_f32 v[24:25], v[24:25], 0.5, v[50:51] op_sel_hi:[1,0,1]
	v_pk_fma_f32 v[14:15], v[14:15], 0.5, v[52:53] op_sel_hi:[1,0,1]
	v_pk_fma_f32 v[12:13], v[12:13], 0.5, v[56:57] op_sel_hi:[1,0,1]
	global_store_dwordx4 v[44:45], v[28:31], off
	global_store_dwordx4 v[44:45], v[24:27], off offset:16
	global_store_dwordx4 v[44:45], v[12:15], off offset:512
	global_store_dwordx4 v[44:45], v[8:11], off offset:528
	v_pk_fma_f32 v[6:7], v[6:7], 0.5, v[32:33] op_sel_hi:[1,0,1]
	v_pk_fma_f32 v[14:15], v[18:19], 0.5, v[38:39] op_sel_hi:[1,0,1]
	v_pk_fma_f32 v[10:11], v[22:23], 0.5, v[36:37] op_sel_hi:[1,0,1]
	v_pk_fma_f32 v[8:9], v[20:21], 0.5, v[66:67] op_sel_hi:[1,0,1]
	v_pk_fma_f32 v[12:13], v[16:17], 0.5, v[64:65] op_sel_hi:[1,0,1]
	v_pk_fma_f32 v[4:5], v[4:5], 0.5, v[62:63] op_sel_hi:[1,0,1]
	v_pk_fma_f32 v[2:3], v[2:3], 0.5, v[34:35] op_sel_hi:[1,0,1]
	v_pk_fma_f32 v[0:1], v[0:1], 0.5, v[60:61] op_sel_hi:[1,0,1]
	global_store_dwordx4 v[46:47], v[8:11], off
	global_store_dwordx4 v[46:47], v[12:15], off offset:16
	global_store_dwordx4 v[46:47], v[4:7], off offset:512
	global_store_dwordx4 v[46:47], v[0:3], off offset:528
	s_cbranch_vccnz .LBB0_3918
	s_andn2_b64 vcc, exec, s[8:9]
	s_cbranch_vccnz .LBB0_3917
	s_barrier
	s_branch .LBB0_3917
